# GEMM loops: vmcnt/lgkmcnt waits before each MFMA-segment barrier merged into one s_waitcnt, redundant lgkmcnt(0) after the barrier removed
# speedup vs baseline: 1.0076x; 1.0066x over previous
.Lmid1_446:
	s_add_i32 s22, 0, 0x10000
	s_add_i32 s23, 0, 0x14000
	s_add_u32 s20, s56, 0xfff50080
	s_addc_u32 s21, s57, -1
	s_cmp_eq_u32 s84, 40
	s_cselect_b32 s61, s49, s21
	s_cselect_b32 s60, s48, s20
	s_cselect_b32 s21, s51, s63
	s_cselect_b32 s20, s50, s62
	s_add_i32 m0, s47, 0xc000
	v_lshl_add_u64 v[162:163], s[56:57], 0, v[156:157]
	global_load_lds_dwordx4 v[162:163], off
	v_lshl_add_u64 v[162:163], v[162:163], 0, s[2:3]
	s_add_i32 m0, s47, 0xe000
	s_nop 0
	global_load_lds_dwordx4 v[162:163], off
	s_waitcnt vmcnt(8) lgkmcnt(0)
	s_barrier
	v_mfma_f32_16x16x32_bf16 v[142:145], v[114:117], v[186:189], 0
	v_mfma_f32_16x16x32_bf16 v[142:145], v[126:129], v[194:197], v[142:145]
	v_mfma_f32_16x16x32_bf16 v[138:141], v[130:133], v[186:189], 0
	v_mfma_f32_16x16x32_bf16 v[138:141], v[134:137], v[194:197], v[138:141]
	v_mfma_f32_16x16x32_bf16 v[110:113], v[114:117], v[198:201], 0
	v_mfma_f32_16x16x32_bf16 v[110:113], v[126:129], v[214:217], v[110:113]
	v_mfma_f32_16x16x32_bf16 v[106:109], v[130:133], v[198:201], 0
	v_mfma_f32_16x16x32_bf16 v[106:109], v[134:137], v[214:217], v[106:109]
	v_mfma_f32_16x16x32_bf16 v[94:97], v[114:117], v[218:221], 0
	v_mfma_f32_16x16x32_bf16 v[94:97], v[126:129], v[222:225], v[94:97]
	v_mfma_f32_16x16x32_bf16 v[90:93], v[130:133], v[218:221], 0
	v_mfma_f32_16x16x32_bf16 v[90:93], v[134:137], v[222:225], v[90:93]
	v_mfma_f32_16x16x32_bf16 v[78:81], v[114:117], v[226:229], 0
	v_mfma_f32_16x16x32_bf16 v[78:81], v[126:129], v[230:233], v[78:81]
	v_mfma_f32_16x16x32_bf16 v[74:77], v[130:133], v[226:229], 0
	v_mfma_f32_16x16x32_bf16 v[74:77], v[134:137], v[230:233], v[74:77]
	v_mfma_f32_16x16x32_bf16 v[122:125], v[146:149], v[186:189], 0
	v_mfma_f32_16x16x32_bf16 v[122:125], v[150:153], v[194:197], v[122:125]
	v_mfma_f32_16x16x32_bf16 v[118:121], v[158:161], v[186:189], 0
	v_mfma_f32_16x16x32_bf16 v[118:121], v[182:185], v[194:197], v[118:121]
	v_mfma_f32_16x16x32_bf16 v[102:105], v[146:149], v[198:201], 0
	v_mfma_f32_16x16x32_bf16 v[102:105], v[150:153], v[214:217], v[102:105]
	v_mfma_f32_16x16x32_bf16 v[98:101], v[158:161], v[198:201], 0
	v_mfma_f32_16x16x32_bf16 v[98:101], v[182:185], v[214:217], v[98:101]
	v_mfma_f32_16x16x32_bf16 v[86:89], v[146:149], v[218:221], 0
	v_mfma_f32_16x16x32_bf16 v[86:89], v[150:153], v[222:225], v[86:89]
	v_mfma_f32_16x16x32_bf16 v[82:85], v[158:161], v[218:221], 0
	v_mfma_f32_16x16x32_bf16 v[82:85], v[182:185], v[222:225], v[82:85]
	v_mfma_f32_16x16x32_bf16 v[70:73], v[146:149], v[226:229], 0
	v_mfma_f32_16x16x32_bf16 v[70:73], v[150:153], v[230:233], v[70:73]
	v_mfma_f32_16x16x32_bf16 v[66:69], v[158:161], v[226:229], 0
	v_mfma_f32_16x16x32_bf16 v[66:69], v[182:185], v[230:233], v[66:69]
	s_barrier
	ds_read_b128 v[186:189], v193 offset:16384
	ds_read_b128 v[194:197], v193 offset:17408
	ds_read_b128 v[198:201], v193 offset:18432
	ds_read_b128 v[214:217], v193 offset:19456
	ds_read_b128 v[218:221], v193 offset:20480
	ds_read_b128 v[222:225], v193 offset:21504
	ds_read_b128 v[226:229], v193 offset:22528
	ds_read_b128 v[230:233], v193 offset:23552
	v_lshl_add_u64 v[162:163], s[20:21], 0, v[0:1]
	s_add_i32 s20, s22, s46
	s_mov_b32 m0, s20
	s_nop 0
	s_nop 0
	global_load_lds_dwordx4 v[162:163], off
	v_lshl_add_u64 v[202:203], v[162:163], 0, s[2:3]
	s_add_i32 m0, s20, 0x2000
	s_add_i32 s20, s23, s46
	global_load_lds_dwordx4 v[202:203], off
	v_lshl_add_u64 v[202:203], v[162:163], 0, s[12:13]
	s_mov_b32 m0, s20
	s_nop 0
	global_load_lds_dwordx4 v[202:203], off
	v_lshl_add_u64 v[202:203], v[162:163], 0, s[86:87]
	s_add_i32 m0, s20, 0x2000
	s_nop 0
	global_load_lds_dwordx4 v[202:203], off
	v_lshl_add_u64 v[202:203], s[60:61], 0, v[154:155]
	s_mov_b32 m0, s47
	v_lshl_add_u64 v[234:235], v[202:203], 0, s[2:3]
	global_load_lds_dwordx4 v[202:203], off
	s_mov_b32 m0, s68
	s_nop 0
	global_load_lds_dwordx4 v[234:235], off
	s_waitcnt vmcnt(8) lgkmcnt(0)
	s_barrier
	v_mfma_f32_16x16x32_bf16 v[62:65], v[114:117], v[186:189], 0
	v_mfma_f32_16x16x32_bf16 v[62:65], v[126:129], v[194:197], v[62:65]
	v_mfma_f32_16x16x32_bf16 v[58:61], v[130:133], v[186:189], 0
	v_mfma_f32_16x16x32_bf16 v[58:61], v[134:137], v[194:197], v[58:61]
	v_mfma_f32_16x16x32_bf16 v[46:49], v[114:117], v[198:201], 0
	v_mfma_f32_16x16x32_bf16 v[46:49], v[126:129], v[214:217], v[46:49]
	v_mfma_f32_16x16x32_bf16 v[42:45], v[130:133], v[198:201], 0
	v_mfma_f32_16x16x32_bf16 v[42:45], v[134:137], v[214:217], v[42:45]
	v_mfma_f32_16x16x32_bf16 v[30:33], v[114:117], v[218:221], 0
	v_mfma_f32_16x16x32_bf16 v[30:33], v[126:129], v[222:225], v[30:33]
	v_mfma_f32_16x16x32_bf16 v[26:29], v[130:133], v[218:221], 0
	v_mfma_f32_16x16x32_bf16 v[26:29], v[134:137], v[222:225], v[26:29]
	v_mfma_f32_16x16x32_bf16 v[14:17], v[114:117], v[226:229], 0
	v_mfma_f32_16x16x32_bf16 v[14:17], v[126:129], v[230:233], v[14:17]
	v_mfma_f32_16x16x32_bf16 v[10:13], v[130:133], v[226:229], 0
	v_mfma_f32_16x16x32_bf16 v[10:13], v[134:137], v[230:233], v[10:13]
	v_mfma_f32_16x16x32_bf16 v[54:57], v[146:149], v[186:189], 0
	v_mfma_f32_16x16x32_bf16 v[54:57], v[150:153], v[194:197], v[54:57]
	v_mfma_f32_16x16x32_bf16 v[50:53], v[158:161], v[186:189], 0
	v_mfma_f32_16x16x32_bf16 v[50:53], v[182:185], v[194:197], v[50:53]
	v_mfma_f32_16x16x32_bf16 v[38:41], v[146:149], v[198:201], 0
	v_mfma_f32_16x16x32_bf16 v[38:41], v[150:153], v[214:217], v[38:41]
	v_mfma_f32_16x16x32_bf16 v[34:37], v[158:161], v[198:201], 0
	v_mfma_f32_16x16x32_bf16 v[34:37], v[182:185], v[214:217], v[34:37]
	v_mfma_f32_16x16x32_bf16 v[22:25], v[146:149], v[218:221], 0
	v_mfma_f32_16x16x32_bf16 v[22:25], v[150:153], v[222:225], v[22:25]
	v_mfma_f32_16x16x32_bf16 v[18:21], v[158:161], v[218:221], 0
	v_mfma_f32_16x16x32_bf16 v[18:21], v[182:185], v[222:225], v[18:21]
	v_mfma_f32_16x16x32_bf16 v[6:9], v[146:149], v[226:229], 0
	v_mfma_f32_16x16x32_bf16 v[6:9], v[150:153], v[230:233], v[6:9]
	v_mfma_f32_16x16x32_bf16 v[2:5], v[158:161], v[226:229], 0
	v_mfma_f32_16x16x32_bf16 v[2:5], v[182:185], v[230:233], v[2:5]
	s_barrier
	s_add_i32 s20, 0, 0x18000
	s_add_i32 s21, 0, 0x1c000
	v_add_u32_e32 v134, s20, v191
	v_add_u32_e32 v182, s21, v191
	ds_read_b128 v[114:117], v134
	ds_read_b128 v[126:129], v134 offset:1024
	ds_read_b128 v[130:133], v134 offset:2048
	ds_read_b128 v[134:137], v134 offset:3072
	ds_read_b128 v[146:149], v182
	ds_read_b128 v[150:153], v182 offset:1024
	ds_read_b128 v[158:161], v182 offset:2048
	ds_read_b128 v[182:185], v182 offset:3072
	ds_read_b128 v[186:189], v193 offset:32768
	ds_read_b128 v[194:197], v193 offset:33792
	ds_read_b128 v[198:201], v193 offset:34816
	ds_read_b128 v[214:217], v193 offset:35840
	ds_read_b128 v[218:221], v193 offset:36864
	ds_read_b128 v[222:225], v193 offset:37888
	ds_read_b128 v[226:229], v193 offset:38912
	ds_read_b128 v[230:233], v193 offset:39936
	s_mov_b32 m0, s69
	v_lshl_add_u64 v[234:235], v[202:203], 0, s[12:13]
	global_load_lds_dwordx4 v[234:235], off
	v_lshl_add_u64 v[234:235], v[202:203], 0, s[86:87]
	s_mov_b32 m0, s76
	s_nop 0
	global_load_lds_dwordx4 v[234:235], off
	s_waitcnt vmcnt(8) lgkmcnt(0)
	s_barrier
	v_mfma_f32_16x16x32_bf16 v[142:145], v[114:117], v[186:189], v[142:145]
	v_mfma_f32_16x16x32_bf16 v[142:145], v[126:129], v[194:197], v[142:145]
	v_mfma_f32_16x16x32_bf16 v[138:141], v[130:133], v[186:189], v[138:141]
	v_mfma_f32_16x16x32_bf16 v[138:141], v[134:137], v[194:197], v[138:141]
	v_mfma_f32_16x16x32_bf16 v[110:113], v[114:117], v[198:201], v[110:113]
	v_mfma_f32_16x16x32_bf16 v[110:113], v[126:129], v[214:217], v[110:113]
	v_mfma_f32_16x16x32_bf16 v[106:109], v[130:133], v[198:201], v[106:109]
	v_mfma_f32_16x16x32_bf16 v[106:109], v[134:137], v[214:217], v[106:109]
	v_mfma_f32_16x16x32_bf16 v[94:97], v[114:117], v[218:221], v[94:97]
	v_mfma_f32_16x16x32_bf16 v[94:97], v[126:129], v[222:225], v[94:97]
	v_mfma_f32_16x16x32_bf16 v[90:93], v[130:133], v[218:221], v[90:93]
	v_mfma_f32_16x16x32_bf16 v[90:93], v[134:137], v[222:225], v[90:93]
	v_mfma_f32_16x16x32_bf16 v[78:81], v[114:117], v[226:229], v[78:81]
	v_mfma_f32_16x16x32_bf16 v[78:81], v[126:129], v[230:233], v[78:81]
	v_mfma_f32_16x16x32_bf16 v[74:77], v[130:133], v[226:229], v[74:77]
	v_mfma_f32_16x16x32_bf16 v[74:77], v[134:137], v[230:233], v[74:77]
	v_mfma_f32_16x16x32_bf16 v[122:125], v[146:149], v[186:189], v[122:125]
	v_mfma_f32_16x16x32_bf16 v[122:125], v[150:153], v[194:197], v[122:125]
	v_mfma_f32_16x16x32_bf16 v[118:121], v[158:161], v[186:189], v[118:121]
	v_mfma_f32_16x16x32_bf16 v[118:121], v[182:185], v[194:197], v[118:121]
	v_mfma_f32_16x16x32_bf16 v[102:105], v[146:149], v[198:201], v[102:105]
	v_mfma_f32_16x16x32_bf16 v[102:105], v[150:153], v[214:217], v[102:105]
	v_mfma_f32_16x16x32_bf16 v[98:101], v[158:161], v[198:201], v[98:101]
	v_mfma_f32_16x16x32_bf16 v[98:101], v[182:185], v[214:217], v[98:101]
	v_mfma_f32_16x16x32_bf16 v[86:89], v[146:149], v[218:221], v[86:89]
	v_mfma_f32_16x16x32_bf16 v[86:89], v[150:153], v[222:225], v[86:89]
	v_mfma_f32_16x16x32_bf16 v[82:85], v[158:161], v[218:221], v[82:85]
	v_mfma_f32_16x16x32_bf16 v[82:85], v[182:185], v[222:225], v[82:85]
	v_mfma_f32_16x16x32_bf16 v[70:73], v[146:149], v[226:229], v[70:73]
	v_mfma_f32_16x16x32_bf16 v[70:73], v[150:153], v[230:233], v[70:73]
	v_mfma_f32_16x16x32_bf16 v[66:69], v[158:161], v[226:229], v[66:69]
	v_mfma_f32_16x16x32_bf16 v[66:69], v[182:185], v[230:233], v[66:69]
	s_barrier
	ds_read_b128 v[186:189], v193 offset:49152
	ds_read_b128 v[194:197], v193 offset:50176
	ds_read_b128 v[198:201], v193 offset:51200
	ds_read_b128 v[214:217], v193 offset:52224
	ds_read_b128 v[218:221], v193 offset:53248
	ds_read_b128 v[222:225], v193 offset:54272
	ds_read_b128 v[226:229], v193 offset:55296
	ds_read_b128 v[230:233], v193 offset:56320
	s_add_i32 s20, s20, s46
	s_mov_b32 m0, s20
	v_lshl_add_u64 v[234:235], v[162:163], 0, s[34:35]
	global_load_lds_dwordx4 v[234:235], off
	v_lshl_add_u64 v[234:235], v[162:163], 0, s[96:97]
	s_add_i32 m0, s20, 0x2000
	s_add_i32 s20, s21, s46
	global_load_lds_dwordx4 v[234:235], off
	v_lshl_add_u64 v[234:235], v[162:163], 0, vcc
	s_mov_b32 m0, s20
	v_lshl_add_u64 v[162:163], v[162:163], 0, s[0:1]
	global_load_lds_dwordx4 v[234:235], off
	s_add_i32 m0, s20, 0x2000
	s_nop 0
	global_load_lds_dwordx4 v[162:163], off
	v_lshl_add_u64 v[162:163], v[202:203], 0, s[34:35]
	s_mov_b32 m0, s77
	s_nop 0
	global_load_lds_dwordx4 v[162:163], off
	v_lshl_add_u64 v[162:163], v[202:203], 0, s[96:97]
	s_mov_b32 m0, s78
	s_nop 0
	global_load_lds_dwordx4 v[162:163], off
	s_waitcnt vmcnt(8) lgkmcnt(0)
	s_barrier
	v_mfma_f32_16x16x32_bf16 v[62:65], v[114:117], v[186:189], v[62:65]
	v_mfma_f32_16x16x32_bf16 v[62:65], v[126:129], v[194:197], v[62:65]
	v_mfma_f32_16x16x32_bf16 v[58:61], v[130:133], v[186:189], v[58:61]
	v_mfma_f32_16x16x32_bf16 v[58:61], v[134:137], v[194:197], v[58:61]
	v_mfma_f32_16x16x32_bf16 v[46:49], v[114:117], v[198:201], v[46:49]
	v_mfma_f32_16x16x32_bf16 v[46:49], v[126:129], v[214:217], v[46:49]
	v_mfma_f32_16x16x32_bf16 v[42:45], v[130:133], v[198:201], v[42:45]
	v_mfma_f32_16x16x32_bf16 v[42:45], v[134:137], v[214:217], v[42:45]
	v_mfma_f32_16x16x32_bf16 v[30:33], v[114:117], v[218:221], v[30:33]
	v_mfma_f32_16x16x32_bf16 v[30:33], v[126:129], v[222:225], v[30:33]
	v_mfma_f32_16x16x32_bf16 v[26:29], v[130:133], v[218:221], v[26:29]
	v_mfma_f32_16x16x32_bf16 v[26:29], v[134:137], v[222:225], v[26:29]
	v_mfma_f32_16x16x32_bf16 v[14:17], v[114:117], v[226:229], v[14:17]
	v_mfma_f32_16x16x32_bf16 v[14:17], v[126:129], v[230:233], v[14:17]
	v_mfma_f32_16x16x32_bf16 v[10:13], v[130:133], v[226:229], v[10:13]
	v_mfma_f32_16x16x32_bf16 v[10:13], v[134:137], v[230:233], v[10:13]
	s_add_i32 s84, s84, 2
	s_add_u32 s56, s56, 0x100
	s_addc_u32 s57, s57, 0
	s_add_u32 s62, s62, 0x100
	s_addc_u32 s63, s63, 0
	v_mfma_f32_16x16x32_bf16 v[54:57], v[146:149], v[186:189], v[54:57]
	v_mfma_f32_16x16x32_bf16 v[54:57], v[150:153], v[194:197], v[54:57]
	v_mfma_f32_16x16x32_bf16 v[50:53], v[158:161], v[186:189], v[50:53]
	v_mfma_f32_16x16x32_bf16 v[50:53], v[182:185], v[194:197], v[50:53]
	v_mfma_f32_16x16x32_bf16 v[38:41], v[146:149], v[198:201], v[38:41]
	v_mfma_f32_16x16x32_bf16 v[38:41], v[150:153], v[214:217], v[38:41]
	v_mfma_f32_16x16x32_bf16 v[34:37], v[158:161], v[198:201], v[34:37]
	v_mfma_f32_16x16x32_bf16 v[34:37], v[182:185], v[214:217], v[34:37]
	v_mfma_f32_16x16x32_bf16 v[22:25], v[146:149], v[218:221], v[22:25]
	v_mfma_f32_16x16x32_bf16 v[22:25], v[150:153], v[222:225], v[22:25]
	v_mfma_f32_16x16x32_bf16 v[18:21], v[158:161], v[218:221], v[18:21]
	v_mfma_f32_16x16x32_bf16 v[18:21], v[182:185], v[222:225], v[18:21]
	v_mfma_f32_16x16x32_bf16 v[6:9], v[146:149], v[226:229], v[6:9]
	v_mfma_f32_16x16x32_bf16 v[6:9], v[150:153], v[230:233], v[6:9]
	v_mfma_f32_16x16x32_bf16 v[2:5], v[158:161], v[226:229], v[2:5]
	v_mfma_f32_16x16x32_bf16 v[2:5], v[182:185], v[230:233], v[2:5]
	s_barrier
	s_branch .LBB0_446
	.p2alignl 6, 3212836864
.LBB0_446:
	s_add_i32 s22, 0, 0x10000
	s_add_i32 s23, 0, 0x14000
	v_add_u32_e32 v134, s22, v191
	v_add_u32_e32 v162, s23, v191
	ds_read_b128 v[114:117], v134
	ds_read_b128 v[126:129], v134 offset:1024
	ds_read_b128 v[130:133], v134 offset:2048
	ds_read_b128 v[134:137], v134 offset:3072
	ds_read_b128 v[146:149], v162
	ds_read_b128 v[150:153], v162 offset:1024
	ds_read_b128 v[158:161], v162 offset:2048
	ds_read_b128 v[182:185], v162 offset:3072
	ds_read_b128 v[186:189], v193
	ds_read_b128 v[194:197], v193 offset:1024
	ds_read_b128 v[198:201], v193 offset:2048
	ds_read_b128 v[214:217], v193 offset:3072
	ds_read_b128 v[218:221], v193 offset:4096
	ds_read_b128 v[222:225], v193 offset:5120
	ds_read_b128 v[226:229], v193 offset:6144
	ds_read_b128 v[230:233], v193 offset:7168
	s_add_u32 s20, s56, 0xfff50080
	s_addc_u32 s21, s57, -1
	s_cmp_eq_u32 s84, 40
	s_cselect_b32 s61, s49, s21
	s_cselect_b32 s60, s48, s20
	s_cselect_b32 s21, s51, s63
	s_cselect_b32 s20, s50, s62
	s_add_i32 m0, s47, 0xc000
	v_lshl_add_u64 v[162:163], s[56:57], 0, v[156:157]
	global_load_lds_dwordx4 v[162:163], off
	v_lshl_add_u64 v[162:163], v[162:163], 0, s[2:3]
	s_add_i32 m0, s47, 0xe000
	s_nop 0
	global_load_lds_dwordx4 v[162:163], off
	s_waitcnt vmcnt(8) lgkmcnt(0)
	s_barrier
	v_mfma_f32_16x16x32_bf16 v[142:145], v[114:117], v[186:189], v[142:145]
	v_mfma_f32_16x16x32_bf16 v[142:145], v[126:129], v[194:197], v[142:145]
	v_mfma_f32_16x16x32_bf16 v[138:141], v[130:133], v[186:189], v[138:141]
	v_mfma_f32_16x16x32_bf16 v[138:141], v[134:137], v[194:197], v[138:141]
	v_mfma_f32_16x16x32_bf16 v[110:113], v[114:117], v[198:201], v[110:113]
	v_mfma_f32_16x16x32_bf16 v[110:113], v[126:129], v[214:217], v[110:113]
	v_mfma_f32_16x16x32_bf16 v[106:109], v[130:133], v[198:201], v[106:109]
	v_mfma_f32_16x16x32_bf16 v[106:109], v[134:137], v[214:217], v[106:109]
	v_mfma_f32_16x16x32_bf16 v[94:97], v[114:117], v[218:221], v[94:97]
	v_mfma_f32_16x16x32_bf16 v[94:97], v[126:129], v[222:225], v[94:97]
	v_mfma_f32_16x16x32_bf16 v[90:93], v[130:133], v[218:221], v[90:93]
	v_mfma_f32_16x16x32_bf16 v[90:93], v[134:137], v[222:225], v[90:93]
	v_mfma_f32_16x16x32_bf16 v[78:81], v[114:117], v[226:229], v[78:81]
	v_mfma_f32_16x16x32_bf16 v[78:81], v[126:129], v[230:233], v[78:81]
	v_mfma_f32_16x16x32_bf16 v[74:77], v[130:133], v[226:229], v[74:77]
	v_mfma_f32_16x16x32_bf16 v[74:77], v[134:137], v[230:233], v[74:77]
	v_mfma_f32_16x16x32_bf16 v[122:125], v[146:149], v[186:189], v[122:125]
	v_mfma_f32_16x16x32_bf16 v[122:125], v[150:153], v[194:197], v[122:125]
	v_mfma_f32_16x16x32_bf16 v[118:121], v[158:161], v[186:189], v[118:121]
	v_mfma_f32_16x16x32_bf16 v[118:121], v[182:185], v[194:197], v[118:121]
	v_mfma_f32_16x16x32_bf16 v[102:105], v[146:149], v[198:201], v[102:105]
	v_mfma_f32_16x16x32_bf16 v[102:105], v[150:153], v[214:217], v[102:105]
	v_mfma_f32_16x16x32_bf16 v[98:101], v[158:161], v[198:201], v[98:101]
	v_mfma_f32_16x16x32_bf16 v[98:101], v[182:185], v[214:217], v[98:101]
	v_mfma_f32_16x16x32_bf16 v[86:89], v[146:149], v[218:221], v[86:89]
	v_mfma_f32_16x16x32_bf16 v[86:89], v[150:153], v[222:225], v[86:89]
	v_mfma_f32_16x16x32_bf16 v[82:85], v[158:161], v[218:221], v[82:85]
	v_mfma_f32_16x16x32_bf16 v[82:85], v[182:185], v[222:225], v[82:85]
	v_mfma_f32_16x16x32_bf16 v[70:73], v[146:149], v[226:229], v[70:73]
	v_mfma_f32_16x16x32_bf16 v[70:73], v[150:153], v[230:233], v[70:73]
	v_mfma_f32_16x16x32_bf16 v[66:69], v[158:161], v[226:229], v[66:69]
	v_mfma_f32_16x16x32_bf16 v[66:69], v[182:185], v[230:233], v[66:69]
	s_barrier
	ds_read_b128 v[186:189], v193 offset:16384
	ds_read_b128 v[194:197], v193 offset:17408
	ds_read_b128 v[198:201], v193 offset:18432
	ds_read_b128 v[214:217], v193 offset:19456
	ds_read_b128 v[218:221], v193 offset:20480
	ds_read_b128 v[222:225], v193 offset:21504
	ds_read_b128 v[226:229], v193 offset:22528
	ds_read_b128 v[230:233], v193 offset:23552
	v_lshl_add_u64 v[162:163], s[20:21], 0, v[0:1]
	s_add_i32 s20, s22, s46
	s_mov_b32 m0, s20
	s_nop 0
	s_nop 0
	global_load_lds_dwordx4 v[162:163], off
	v_lshl_add_u64 v[202:203], v[162:163], 0, s[2:3]
	s_add_i32 m0, s20, 0x2000
	s_add_i32 s20, s23, s46
	global_load_lds_dwordx4 v[202:203], off
	v_lshl_add_u64 v[202:203], v[162:163], 0, s[12:13]
	s_mov_b32 m0, s20
	s_nop 0
	global_load_lds_dwordx4 v[202:203], off
	v_lshl_add_u64 v[202:203], v[162:163], 0, s[86:87]
	s_add_i32 m0, s20, 0x2000
	s_nop 0
	global_load_lds_dwordx4 v[202:203], off
	v_lshl_add_u64 v[202:203], s[60:61], 0, v[154:155]
	s_mov_b32 m0, s47
	v_lshl_add_u64 v[234:235], v[202:203], 0, s[2:3]
	global_load_lds_dwordx4 v[202:203], off
	s_mov_b32 m0, s68
	s_nop 0
	global_load_lds_dwordx4 v[234:235], off
	s_waitcnt vmcnt(8) lgkmcnt(0)
	s_barrier
	v_mfma_f32_16x16x32_bf16 v[62:65], v[114:117], v[186:189], v[62:65]
	v_mfma_f32_16x16x32_bf16 v[62:65], v[126:129], v[194:197], v[62:65]
	v_mfma_f32_16x16x32_bf16 v[58:61], v[130:133], v[186:189], v[58:61]
	v_mfma_f32_16x16x32_bf16 v[58:61], v[134:137], v[194:197], v[58:61]
	v_mfma_f32_16x16x32_bf16 v[46:49], v[114:117], v[198:201], v[46:49]
	v_mfma_f32_16x16x32_bf16 v[46:49], v[126:129], v[214:217], v[46:49]
	v_mfma_f32_16x16x32_bf16 v[42:45], v[130:133], v[198:201], v[42:45]
	v_mfma_f32_16x16x32_bf16 v[42:45], v[134:137], v[214:217], v[42:45]
	v_mfma_f32_16x16x32_bf16 v[30:33], v[114:117], v[218:221], v[30:33]
	v_mfma_f32_16x16x32_bf16 v[30:33], v[126:129], v[222:225], v[30:33]
	v_mfma_f32_16x16x32_bf16 v[26:29], v[130:133], v[218:221], v[26:29]
	v_mfma_f32_16x16x32_bf16 v[26:29], v[134:137], v[222:225], v[26:29]
	v_mfma_f32_16x16x32_bf16 v[14:17], v[114:117], v[226:229], v[14:17]
	v_mfma_f32_16x16x32_bf16 v[14:17], v[126:129], v[230:233], v[14:17]
	v_mfma_f32_16x16x32_bf16 v[10:13], v[130:133], v[226:229], v[10:13]
	v_mfma_f32_16x16x32_bf16 v[10:13], v[134:137], v[230:233], v[10:13]
	v_mfma_f32_16x16x32_bf16 v[54:57], v[146:149], v[186:189], v[54:57]
	v_mfma_f32_16x16x32_bf16 v[54:57], v[150:153], v[194:197], v[54:57]
	v_mfma_f32_16x16x32_bf16 v[50:53], v[158:161], v[186:189], v[50:53]
	v_mfma_f32_16x16x32_bf16 v[50:53], v[182:185], v[194:197], v[50:53]
	v_mfma_f32_16x16x32_bf16 v[38:41], v[146:149], v[198:201], v[38:41]
	v_mfma_f32_16x16x32_bf16 v[38:41], v[150:153], v[214:217], v[38:41]
	v_mfma_f32_16x16x32_bf16 v[34:37], v[158:161], v[198:201], v[34:37]
	v_mfma_f32_16x16x32_bf16 v[34:37], v[182:185], v[214:217], v[34:37]
	v_mfma_f32_16x16x32_bf16 v[22:25], v[146:149], v[218:221], v[22:25]
	v_mfma_f32_16x16x32_bf16 v[22:25], v[150:153], v[222:225], v[22:25]
	v_mfma_f32_16x16x32_bf16 v[18:21], v[158:161], v[218:221], v[18:21]
	v_mfma_f32_16x16x32_bf16 v[18:21], v[182:185], v[222:225], v[18:21]
	v_mfma_f32_16x16x32_bf16 v[6:9], v[146:149], v[226:229], v[6:9]
	v_mfma_f32_16x16x32_bf16 v[6:9], v[150:153], v[230:233], v[6:9]
	v_mfma_f32_16x16x32_bf16 v[2:5], v[158:161], v[226:229], v[2:5]
	v_mfma_f32_16x16x32_bf16 v[2:5], v[182:185], v[230:233], v[2:5]
	s_barrier
	s_add_i32 s20, 0, 0x18000
	s_add_i32 s21, 0, 0x1c000
	v_add_u32_e32 v134, s20, v191
	v_add_u32_e32 v182, s21, v191
	ds_read_b128 v[114:117], v134
	ds_read_b128 v[126:129], v134 offset:1024
	ds_read_b128 v[130:133], v134 offset:2048
	ds_read_b128 v[134:137], v134 offset:3072
	ds_read_b128 v[146:149], v182
	ds_read_b128 v[150:153], v182 offset:1024
	ds_read_b128 v[158:161], v182 offset:2048
	ds_read_b128 v[182:185], v182 offset:3072
	ds_read_b128 v[186:189], v193 offset:32768
	ds_read_b128 v[194:197], v193 offset:33792
	ds_read_b128 v[198:201], v193 offset:34816
	ds_read_b128 v[214:217], v193 offset:35840
	ds_read_b128 v[218:221], v193 offset:36864
	ds_read_b128 v[222:225], v193 offset:37888
	ds_read_b128 v[226:229], v193 offset:38912
	ds_read_b128 v[230:233], v193 offset:39936
	s_mov_b32 m0, s69
	v_lshl_add_u64 v[234:235], v[202:203], 0, s[12:13]
	global_load_lds_dwordx4 v[234:235], off
	v_lshl_add_u64 v[234:235], v[202:203], 0, s[86:87]
	s_mov_b32 m0, s76
	s_nop 0
	global_load_lds_dwordx4 v[234:235], off
	s_waitcnt vmcnt(8) lgkmcnt(0)
	s_barrier
	v_mfma_f32_16x16x32_bf16 v[142:145], v[114:117], v[186:189], v[142:145]
	v_mfma_f32_16x16x32_bf16 v[142:145], v[126:129], v[194:197], v[142:145]
	v_mfma_f32_16x16x32_bf16 v[138:141], v[130:133], v[186:189], v[138:141]
	v_mfma_f32_16x16x32_bf16 v[138:141], v[134:137], v[194:197], v[138:141]
	v_mfma_f32_16x16x32_bf16 v[110:113], v[114:117], v[198:201], v[110:113]
	v_mfma_f32_16x16x32_bf16 v[110:113], v[126:129], v[214:217], v[110:113]
	v_mfma_f32_16x16x32_bf16 v[106:109], v[130:133], v[198:201], v[106:109]
	v_mfma_f32_16x16x32_bf16 v[106:109], v[134:137], v[214:217], v[106:109]
	v_mfma_f32_16x16x32_bf16 v[94:97], v[114:117], v[218:221], v[94:97]
	v_mfma_f32_16x16x32_bf16 v[94:97], v[126:129], v[222:225], v[94:97]
	v_mfma_f32_16x16x32_bf16 v[90:93], v[130:133], v[218:221], v[90:93]
	v_mfma_f32_16x16x32_bf16 v[90:93], v[134:137], v[222:225], v[90:93]
	v_mfma_f32_16x16x32_bf16 v[78:81], v[114:117], v[226:229], v[78:81]
	v_mfma_f32_16x16x32_bf16 v[78:81], v[126:129], v[230:233], v[78:81]
	v_mfma_f32_16x16x32_bf16 v[74:77], v[130:133], v[226:229], v[74:77]
	v_mfma_f32_16x16x32_bf16 v[74:77], v[134:137], v[230:233], v[74:77]
	v_mfma_f32_16x16x32_bf16 v[122:125], v[146:149], v[186:189], v[122:125]
	v_mfma_f32_16x16x32_bf16 v[122:125], v[150:153], v[194:197], v[122:125]
	v_mfma_f32_16x16x32_bf16 v[118:121], v[158:161], v[186:189], v[118:121]
	v_mfma_f32_16x16x32_bf16 v[118:121], v[182:185], v[194:197], v[118:121]
	v_mfma_f32_16x16x32_bf16 v[102:105], v[146:149], v[198:201], v[102:105]
	v_mfma_f32_16x16x32_bf16 v[102:105], v[150:153], v[214:217], v[102:105]
	v_mfma_f32_16x16x32_bf16 v[98:101], v[158:161], v[198:201], v[98:101]
	v_mfma_f32_16x16x32_bf16 v[98:101], v[182:185], v[214:217], v[98:101]
	v_mfma_f32_16x16x32_bf16 v[86:89], v[146:149], v[218:221], v[86:89]
	v_mfma_f32_16x16x32_bf16 v[86:89], v[150:153], v[222:225], v[86:89]
	v_mfma_f32_16x16x32_bf16 v[82:85], v[158:161], v[218:221], v[82:85]
	v_mfma_f32_16x16x32_bf16 v[82:85], v[182:185], v[222:225], v[82:85]
	v_mfma_f32_16x16x32_bf16 v[70:73], v[146:149], v[226:229], v[70:73]
	v_mfma_f32_16x16x32_bf16 v[70:73], v[150:153], v[230:233], v[70:73]
	v_mfma_f32_16x16x32_bf16 v[66:69], v[158:161], v[226:229], v[66:69]
	v_mfma_f32_16x16x32_bf16 v[66:69], v[182:185], v[230:233], v[66:69]
	s_barrier
	ds_read_b128 v[186:189], v193 offset:49152
	ds_read_b128 v[194:197], v193 offset:50176
	ds_read_b128 v[198:201], v193 offset:51200
	ds_read_b128 v[214:217], v193 offset:52224
	ds_read_b128 v[218:221], v193 offset:53248
	ds_read_b128 v[222:225], v193 offset:54272
	ds_read_b128 v[226:229], v193 offset:55296
	ds_read_b128 v[230:233], v193 offset:56320
	s_add_i32 s20, s20, s46
	s_mov_b32 m0, s20
	v_lshl_add_u64 v[234:235], v[162:163], 0, s[34:35]
	global_load_lds_dwordx4 v[234:235], off
	v_lshl_add_u64 v[234:235], v[162:163], 0, s[96:97]
	s_add_i32 m0, s20, 0x2000
	s_add_i32 s20, s21, s46
	global_load_lds_dwordx4 v[234:235], off
	v_lshl_add_u64 v[234:235], v[162:163], 0, vcc
	s_mov_b32 m0, s20
	v_lshl_add_u64 v[162:163], v[162:163], 0, s[0:1]
	global_load_lds_dwordx4 v[234:235], off
	s_add_i32 m0, s20, 0x2000
	s_nop 0
	global_load_lds_dwordx4 v[162:163], off
	v_lshl_add_u64 v[162:163], v[202:203], 0, s[34:35]
	s_mov_b32 m0, s77
	s_nop 0
	global_load_lds_dwordx4 v[162:163], off
	v_lshl_add_u64 v[162:163], v[202:203], 0, s[96:97]
	s_mov_b32 m0, s78
	s_nop 0
	global_load_lds_dwordx4 v[162:163], off
	s_waitcnt vmcnt(8) lgkmcnt(0)
	s_barrier
	v_mfma_f32_16x16x32_bf16 v[62:65], v[114:117], v[186:189], v[62:65]
	v_mfma_f32_16x16x32_bf16 v[62:65], v[126:129], v[194:197], v[62:65]
	v_mfma_f32_16x16x32_bf16 v[58:61], v[130:133], v[186:189], v[58:61]
	v_mfma_f32_16x16x32_bf16 v[58:61], v[134:137], v[194:197], v[58:61]
	v_mfma_f32_16x16x32_bf16 v[46:49], v[114:117], v[198:201], v[46:49]
	v_mfma_f32_16x16x32_bf16 v[46:49], v[126:129], v[214:217], v[46:49]
	v_mfma_f32_16x16x32_bf16 v[42:45], v[130:133], v[198:201], v[42:45]
	v_mfma_f32_16x16x32_bf16 v[42:45], v[134:137], v[214:217], v[42:45]
	v_mfma_f32_16x16x32_bf16 v[30:33], v[114:117], v[218:221], v[30:33]
	v_mfma_f32_16x16x32_bf16 v[30:33], v[126:129], v[222:225], v[30:33]
	v_mfma_f32_16x16x32_bf16 v[26:29], v[130:133], v[218:221], v[26:29]
	v_mfma_f32_16x16x32_bf16 v[26:29], v[134:137], v[222:225], v[26:29]
	v_mfma_f32_16x16x32_bf16 v[14:17], v[114:117], v[226:229], v[14:17]
	v_mfma_f32_16x16x32_bf16 v[14:17], v[126:129], v[230:233], v[14:17]
	v_mfma_f32_16x16x32_bf16 v[10:13], v[130:133], v[226:229], v[10:13]
	v_mfma_f32_16x16x32_bf16 v[10:13], v[134:137], v[230:233], v[10:13]
	s_add_i32 s84, s84, 2
	s_add_u32 s56, s56, 0x100
	s_addc_u32 s57, s57, 0
	s_add_u32 s62, s62, 0x100
	s_addc_u32 s63, s63, 0
	v_mfma_f32_16x16x32_bf16 v[54:57], v[146:149], v[186:189], v[54:57]
	v_mfma_f32_16x16x32_bf16 v[54:57], v[150:153], v[194:197], v[54:57]
	v_mfma_f32_16x16x32_bf16 v[50:53], v[158:161], v[186:189], v[50:53]
	v_mfma_f32_16x16x32_bf16 v[50:53], v[182:185], v[194:197], v[50:53]
	v_mfma_f32_16x16x32_bf16 v[38:41], v[146:149], v[198:201], v[38:41]
	v_mfma_f32_16x16x32_bf16 v[38:41], v[150:153], v[214:217], v[38:41]
	v_mfma_f32_16x16x32_bf16 v[34:37], v[158:161], v[198:201], v[34:37]
	v_mfma_f32_16x16x32_bf16 v[34:37], v[182:185], v[214:217], v[34:37]
	v_mfma_f32_16x16x32_bf16 v[22:25], v[146:149], v[218:221], v[22:25]
	v_mfma_f32_16x16x32_bf16 v[22:25], v[150:153], v[222:225], v[22:25]
	v_mfma_f32_16x16x32_bf16 v[18:21], v[158:161], v[218:221], v[18:21]
	v_mfma_f32_16x16x32_bf16 v[18:21], v[182:185], v[222:225], v[18:21]
	v_mfma_f32_16x16x32_bf16 v[6:9], v[146:149], v[226:229], v[6:9]
	v_mfma_f32_16x16x32_bf16 v[6:9], v[150:153], v[230:233], v[6:9]
	v_mfma_f32_16x16x32_bf16 v[2:5], v[158:161], v[226:229], v[2:5]
	v_mfma_f32_16x16x32_bf16 v[2:5], v[182:185], v[230:233], v[2:5]
	s_barrier
	s_cmp_gt_u32 s84, 41
	s_cbranch_scc0 .LBB0_446
	s_setprio 0
	s_and_b64 vcc, exec, s[40:41]
	s_cbranch_vccz .LBB0_449
	s_barrier

.Lmid1_488:
	s_add_i32 s22, 0, 0x10000
	s_add_i32 s23, 0, 0x14000
	s_add_u32 s20, s68, 0xfffc0080
	s_addc_u32 s21, s69, -1
	s_cmp_eq_u32 s97, 12
	s_cselect_b32 s77, s57, s21
	s_cselect_b32 s76, s86, s20
	s_cselect_b32 s21, s51, s96
	s_cselect_b32 s20, s87, s91
	s_add_i32 m0, s43, 0xc000
	v_lshl_add_u64 v[202:203], s[68:69], 0, v[132:133]
	global_load_lds_dwordx4 v[202:203], off
	v_lshl_add_u64 v[202:203], v[202:203], 0, s[72:73]
	s_add_i32 m0, s43, 0xe000
	s_nop 0
	global_load_lds_dwordx4 v[202:203], off
	s_waitcnt vmcnt(8) lgkmcnt(0)
	s_barrier
	v_mfma_f32_16x16x32_bf16 v[126:129], v[134:137], v[190:193], 0
	v_mfma_f32_16x16x32_bf16 v[126:129], v[144:147], v[194:197], v[126:129]
	v_mfma_f32_16x16x32_bf16 v[114:117], v[148:151], v[190:193], 0
	v_mfma_f32_16x16x32_bf16 v[114:117], v[152:155], v[194:197], v[114:117]
	v_mfma_f32_16x16x32_bf16 v[110:113], v[134:137], v[198:201], 0
	v_mfma_f32_16x16x32_bf16 v[110:113], v[144:147], v[214:217], v[110:113]
	v_mfma_f32_16x16x32_bf16 v[98:101], v[148:151], v[198:201], 0
	v_mfma_f32_16x16x32_bf16 v[98:101], v[152:155], v[214:217], v[98:101]
	v_mfma_f32_16x16x32_bf16 v[94:97], v[134:137], v[218:221], 0
	v_mfma_f32_16x16x32_bf16 v[94:97], v[144:147], v[222:225], v[94:97]
	v_mfma_f32_16x16x32_bf16 v[82:85], v[148:151], v[218:221], 0
	v_mfma_f32_16x16x32_bf16 v[82:85], v[152:155], v[222:225], v[82:85]
	v_mfma_f32_16x16x32_bf16 v[78:81], v[134:137], v[226:229], 0
	v_mfma_f32_16x16x32_bf16 v[78:81], v[144:147], v[230:233], v[78:81]
	v_mfma_f32_16x16x32_bf16 v[66:69], v[148:151], v[226:229], 0
	v_mfma_f32_16x16x32_bf16 v[66:69], v[152:155], v[230:233], v[66:69]
	v_mfma_f32_16x16x32_bf16 v[122:125], v[156:159], v[190:193], 0
	v_mfma_f32_16x16x32_bf16 v[122:125], v[160:163], v[194:197], v[122:125]
	v_mfma_f32_16x16x32_bf16 v[118:121], v[182:185], v[190:193], 0
	v_mfma_f32_16x16x32_bf16 v[118:121], v[186:189], v[194:197], v[118:121]
	v_mfma_f32_16x16x32_bf16 v[106:109], v[156:159], v[198:201], 0
	v_mfma_f32_16x16x32_bf16 v[106:109], v[160:163], v[214:217], v[106:109]
	v_mfma_f32_16x16x32_bf16 v[102:105], v[182:185], v[198:201], 0
	v_mfma_f32_16x16x32_bf16 v[102:105], v[186:189], v[214:217], v[102:105]
	v_mfma_f32_16x16x32_bf16 v[90:93], v[156:159], v[218:221], 0
	v_mfma_f32_16x16x32_bf16 v[90:93], v[160:163], v[222:225], v[90:93]
	v_mfma_f32_16x16x32_bf16 v[86:89], v[182:185], v[218:221], 0
	v_mfma_f32_16x16x32_bf16 v[86:89], v[186:189], v[222:225], v[86:89]
	v_mfma_f32_16x16x32_bf16 v[74:77], v[156:159], v[226:229], 0
	v_mfma_f32_16x16x32_bf16 v[74:77], v[160:163], v[230:233], v[74:77]
	v_mfma_f32_16x16x32_bf16 v[70:73], v[182:185], v[226:229], 0
	v_mfma_f32_16x16x32_bf16 v[70:73], v[186:189], v[230:233], v[70:73]
	s_barrier
	ds_read_b128 v[190:193], v142 offset:16384
	ds_read_b128 v[194:197], v142 offset:17408
	ds_read_b128 v[198:201], v142 offset:18432
	ds_read_b128 v[214:217], v142 offset:19456
	ds_read_b128 v[218:221], v142 offset:20480
	ds_read_b128 v[222:225], v142 offset:21504
	ds_read_b128 v[226:229], v142 offset:22528
	ds_read_b128 v[230:233], v142 offset:23552
	v_lshl_add_u64 v[202:203], s[20:21], 0, v[0:1]
	s_add_i32 s20, s22, s14
	s_mov_b32 m0, s20
	s_nop 0
	s_nop 0
	global_load_lds_dwordx4 v[202:203], off
	v_lshl_add_u64 v[234:235], v[202:203], 0, s[72:73]
	s_add_i32 m0, s20, 0x2000
	s_add_i32 s20, s23, s14
	global_load_lds_dwordx4 v[234:235], off
	v_lshl_add_u64 v[234:235], v[202:203], 0, s[28:29]
	s_mov_b32 m0, s20
	s_nop 0
	global_load_lds_dwordx4 v[234:235], off
	v_lshl_add_u64 v[234:235], v[202:203], 0, s[82:83]
	s_add_i32 m0, s20, 0x2000
	s_nop 0
	global_load_lds_dwordx4 v[234:235], off
	v_lshl_add_u64 v[234:235], s[76:77], 0, v[130:131]
	s_mov_b32 m0, s43
	v_lshl_add_u64 v[236:237], v[234:235], 0, s[72:73]
	global_load_lds_dwordx4 v[234:235], off
	s_mov_b32 m0, s46
	s_nop 0
	global_load_lds_dwordx4 v[236:237], off
	s_waitcnt vmcnt(8) lgkmcnt(0)
	s_barrier
	v_mfma_f32_16x16x32_bf16 v[62:65], v[134:137], v[190:193], 0
	v_mfma_f32_16x16x32_bf16 v[62:65], v[144:147], v[194:197], v[62:65]
	v_mfma_f32_16x16x32_bf16 v[50:53], v[148:151], v[190:193], 0
	v_mfma_f32_16x16x32_bf16 v[50:53], v[152:155], v[194:197], v[50:53]
	v_mfma_f32_16x16x32_bf16 v[46:49], v[134:137], v[198:201], 0
	v_mfma_f32_16x16x32_bf16 v[46:49], v[144:147], v[214:217], v[46:49]
	v_mfma_f32_16x16x32_bf16 v[34:37], v[148:151], v[198:201], 0
	v_mfma_f32_16x16x32_bf16 v[34:37], v[152:155], v[214:217], v[34:37]
	v_mfma_f32_16x16x32_bf16 v[30:33], v[134:137], v[218:221], 0
	v_mfma_f32_16x16x32_bf16 v[30:33], v[144:147], v[222:225], v[30:33]
	v_mfma_f32_16x16x32_bf16 v[18:21], v[148:151], v[218:221], 0
	v_mfma_f32_16x16x32_bf16 v[18:21], v[152:155], v[222:225], v[18:21]
	v_mfma_f32_16x16x32_bf16 v[14:17], v[134:137], v[226:229], 0
	v_mfma_f32_16x16x32_bf16 v[14:17], v[144:147], v[230:233], v[14:17]
	v_mfma_f32_16x16x32_bf16 v[6:9], v[148:151], v[226:229], 0
	v_mfma_f32_16x16x32_bf16 v[6:9], v[152:155], v[230:233], v[6:9]
	v_mfma_f32_16x16x32_bf16 v[58:61], v[156:159], v[190:193], 0
	v_mfma_f32_16x16x32_bf16 v[58:61], v[160:163], v[194:197], v[58:61]
	v_mfma_f32_16x16x32_bf16 v[54:57], v[182:185], v[190:193], 0
	v_mfma_f32_16x16x32_bf16 v[54:57], v[186:189], v[194:197], v[54:57]
	v_mfma_f32_16x16x32_bf16 v[42:45], v[156:159], v[198:201], 0
	v_mfma_f32_16x16x32_bf16 v[42:45], v[160:163], v[214:217], v[42:45]
	v_mfma_f32_16x16x32_bf16 v[38:41], v[182:185], v[198:201], 0
	v_mfma_f32_16x16x32_bf16 v[38:41], v[186:189], v[214:217], v[38:41]
	v_mfma_f32_16x16x32_bf16 v[26:29], v[156:159], v[218:221], 0
	v_mfma_f32_16x16x32_bf16 v[26:29], v[160:163], v[222:225], v[26:29]
	v_mfma_f32_16x16x32_bf16 v[22:25], v[182:185], v[218:221], 0
	v_mfma_f32_16x16x32_bf16 v[22:25], v[186:189], v[222:225], v[22:25]
	v_mfma_f32_16x16x32_bf16 v[10:13], v[156:159], v[226:229], 0
	v_mfma_f32_16x16x32_bf16 v[10:13], v[160:163], v[230:233], v[10:13]
	v_mfma_f32_16x16x32_bf16 v[2:5], v[182:185], v[226:229], 0
	v_mfma_f32_16x16x32_bf16 v[2:5], v[186:189], v[230:233], v[2:5]
	s_barrier
	s_add_i32 s20, 0, 0x18000
	v_add_u32_e32 v143, s20, v139
	s_add_i32 s21, 0, 0x1c000
	ds_read_b128 v[134:137], v143
	ds_read_b128 v[144:147], v143 offset:1024
	ds_read_b128 v[148:151], v143 offset:2048
	ds_read_b128 v[152:155], v143 offset:3072
	v_add_u32_e32 v143, s21, v139
	ds_read_b128 v[156:159], v143
	ds_read_b128 v[160:163], v143 offset:1024
	ds_read_b128 v[182:185], v143 offset:2048
	ds_read_b128 v[186:189], v143 offset:3072
	ds_read_b128 v[190:193], v142 offset:32768
	ds_read_b128 v[194:197], v142 offset:33792
	ds_read_b128 v[198:201], v142 offset:34816
	ds_read_b128 v[214:217], v142 offset:35840
	ds_read_b128 v[218:221], v142 offset:36864
	ds_read_b128 v[222:225], v142 offset:37888
	ds_read_b128 v[226:229], v142 offset:38912
	ds_read_b128 v[230:233], v142 offset:39936
	s_mov_b32 m0, s47
	v_lshl_add_u64 v[236:237], v[234:235], 0, s[28:29]
	global_load_lds_dwordx4 v[236:237], off
	v_lshl_add_u64 v[236:237], v[234:235], 0, s[82:83]
	s_mov_b32 m0, s78
	s_nop 0
	global_load_lds_dwordx4 v[236:237], off
	s_waitcnt vmcnt(8) lgkmcnt(0)
	s_barrier
	v_mfma_f32_16x16x32_bf16 v[126:129], v[134:137], v[190:193], v[126:129]
	v_mfma_f32_16x16x32_bf16 v[126:129], v[144:147], v[194:197], v[126:129]
	v_mfma_f32_16x16x32_bf16 v[114:117], v[148:151], v[190:193], v[114:117]
	v_mfma_f32_16x16x32_bf16 v[114:117], v[152:155], v[194:197], v[114:117]
	v_mfma_f32_16x16x32_bf16 v[110:113], v[134:137], v[198:201], v[110:113]
	v_mfma_f32_16x16x32_bf16 v[110:113], v[144:147], v[214:217], v[110:113]
	v_mfma_f32_16x16x32_bf16 v[98:101], v[148:151], v[198:201], v[98:101]
	v_mfma_f32_16x16x32_bf16 v[98:101], v[152:155], v[214:217], v[98:101]
	v_mfma_f32_16x16x32_bf16 v[94:97], v[134:137], v[218:221], v[94:97]
	v_mfma_f32_16x16x32_bf16 v[94:97], v[144:147], v[222:225], v[94:97]
	v_mfma_f32_16x16x32_bf16 v[82:85], v[148:151], v[218:221], v[82:85]
	v_mfma_f32_16x16x32_bf16 v[82:85], v[152:155], v[222:225], v[82:85]
	v_mfma_f32_16x16x32_bf16 v[78:81], v[134:137], v[226:229], v[78:81]
	v_mfma_f32_16x16x32_bf16 v[78:81], v[144:147], v[230:233], v[78:81]
	v_mfma_f32_16x16x32_bf16 v[66:69], v[148:151], v[226:229], v[66:69]
	v_mfma_f32_16x16x32_bf16 v[66:69], v[152:155], v[230:233], v[66:69]
	v_mfma_f32_16x16x32_bf16 v[122:125], v[156:159], v[190:193], v[122:125]
	v_mfma_f32_16x16x32_bf16 v[122:125], v[160:163], v[194:197], v[122:125]
	v_mfma_f32_16x16x32_bf16 v[118:121], v[182:185], v[190:193], v[118:121]
	v_mfma_f32_16x16x32_bf16 v[118:121], v[186:189], v[194:197], v[118:121]
	v_mfma_f32_16x16x32_bf16 v[106:109], v[156:159], v[198:201], v[106:109]
	v_mfma_f32_16x16x32_bf16 v[106:109], v[160:163], v[214:217], v[106:109]
	v_mfma_f32_16x16x32_bf16 v[102:105], v[182:185], v[198:201], v[102:105]
	v_mfma_f32_16x16x32_bf16 v[102:105], v[186:189], v[214:217], v[102:105]
	v_mfma_f32_16x16x32_bf16 v[90:93], v[156:159], v[218:221], v[90:93]
	v_mfma_f32_16x16x32_bf16 v[90:93], v[160:163], v[222:225], v[90:93]
	v_mfma_f32_16x16x32_bf16 v[86:89], v[182:185], v[218:221], v[86:89]
	v_mfma_f32_16x16x32_bf16 v[86:89], v[186:189], v[222:225], v[86:89]
	v_mfma_f32_16x16x32_bf16 v[74:77], v[156:159], v[226:229], v[74:77]
	v_mfma_f32_16x16x32_bf16 v[74:77], v[160:163], v[230:233], v[74:77]
	v_mfma_f32_16x16x32_bf16 v[70:73], v[182:185], v[226:229], v[70:73]
	v_mfma_f32_16x16x32_bf16 v[70:73], v[186:189], v[230:233], v[70:73]
	s_barrier
	ds_read_b128 v[190:193], v142 offset:49152
	ds_read_b128 v[194:197], v142 offset:50176
	ds_read_b128 v[198:201], v142 offset:51200
	ds_read_b128 v[214:217], v142 offset:52224
	ds_read_b128 v[218:221], v142 offset:53248
	ds_read_b128 v[222:225], v142 offset:54272
	ds_read_b128 v[226:229], v142 offset:55296
	ds_read_b128 v[230:233], v142 offset:56320
	s_add_i32 s20, s20, s14
	s_mov_b32 m0, s20
	v_lshl_add_u64 v[236:237], v[202:203], 0, s[34:35]
	global_load_lds_dwordx4 v[236:237], off
	v_lshl_add_u64 v[236:237], v[202:203], 0, s[38:39]
	s_add_i32 m0, s20, 0x2000
	s_add_i32 s20, s21, s14
	global_load_lds_dwordx4 v[236:237], off
	v_lshl_add_u64 v[236:237], v[202:203], 0, s[44:45]
	s_mov_b32 m0, s20
	v_lshl_add_u64 v[202:203], v[202:203], 0, s[10:11]
	global_load_lds_dwordx4 v[236:237], off
	s_add_i32 m0, s20, 0x2000
	s_nop 0
	global_load_lds_dwordx4 v[202:203], off
	v_lshl_add_u64 v[202:203], v[234:235], 0, s[34:35]
	s_mov_b32 m0, s79
	s_nop 0
	global_load_lds_dwordx4 v[202:203], off
	v_lshl_add_u64 v[202:203], v[234:235], 0, s[38:39]
	s_mov_b32 m0, s88
	s_nop 0
	global_load_lds_dwordx4 v[202:203], off
	s_waitcnt vmcnt(8) lgkmcnt(0)
	s_barrier
	v_mfma_f32_16x16x32_bf16 v[62:65], v[134:137], v[190:193], v[62:65]
	v_mfma_f32_16x16x32_bf16 v[62:65], v[144:147], v[194:197], v[62:65]
	v_mfma_f32_16x16x32_bf16 v[50:53], v[148:151], v[190:193], v[50:53]
	v_mfma_f32_16x16x32_bf16 v[50:53], v[152:155], v[194:197], v[50:53]
	v_mfma_f32_16x16x32_bf16 v[46:49], v[134:137], v[198:201], v[46:49]
	v_mfma_f32_16x16x32_bf16 v[46:49], v[144:147], v[214:217], v[46:49]
	v_mfma_f32_16x16x32_bf16 v[34:37], v[148:151], v[198:201], v[34:37]
	v_mfma_f32_16x16x32_bf16 v[34:37], v[152:155], v[214:217], v[34:37]
	v_mfma_f32_16x16x32_bf16 v[30:33], v[134:137], v[218:221], v[30:33]
	v_mfma_f32_16x16x32_bf16 v[30:33], v[144:147], v[222:225], v[30:33]
	v_mfma_f32_16x16x32_bf16 v[18:21], v[148:151], v[218:221], v[18:21]
	v_mfma_f32_16x16x32_bf16 v[18:21], v[152:155], v[222:225], v[18:21]
	v_mfma_f32_16x16x32_bf16 v[14:17], v[134:137], v[226:229], v[14:17]
	v_mfma_f32_16x16x32_bf16 v[14:17], v[144:147], v[230:233], v[14:17]
	v_mfma_f32_16x16x32_bf16 v[6:9], v[148:151], v[226:229], v[6:9]
	v_mfma_f32_16x16x32_bf16 v[6:9], v[152:155], v[230:233], v[6:9]
	s_add_i32 s97, s97, 2
	s_add_u32 s68, s68, 0x100
	s_addc_u32 s69, s69, 0
	s_add_u32 s91, s91, 0x100
	s_addc_u32 s96, s96, 0
	v_mfma_f32_16x16x32_bf16 v[58:61], v[156:159], v[190:193], v[58:61]
	v_mfma_f32_16x16x32_bf16 v[58:61], v[160:163], v[194:197], v[58:61]
	v_mfma_f32_16x16x32_bf16 v[54:57], v[182:185], v[190:193], v[54:57]
	v_mfma_f32_16x16x32_bf16 v[54:57], v[186:189], v[194:197], v[54:57]
	v_mfma_f32_16x16x32_bf16 v[42:45], v[156:159], v[198:201], v[42:45]
	v_mfma_f32_16x16x32_bf16 v[42:45], v[160:163], v[214:217], v[42:45]
	v_mfma_f32_16x16x32_bf16 v[38:41], v[182:185], v[198:201], v[38:41]
	v_mfma_f32_16x16x32_bf16 v[38:41], v[186:189], v[214:217], v[38:41]
	v_mfma_f32_16x16x32_bf16 v[26:29], v[156:159], v[218:221], v[26:29]
	v_mfma_f32_16x16x32_bf16 v[26:29], v[160:163], v[222:225], v[26:29]
	v_mfma_f32_16x16x32_bf16 v[22:25], v[182:185], v[218:221], v[22:25]
	v_mfma_f32_16x16x32_bf16 v[22:25], v[186:189], v[222:225], v[22:25]
	v_mfma_f32_16x16x32_bf16 v[10:13], v[156:159], v[226:229], v[10:13]
	v_mfma_f32_16x16x32_bf16 v[10:13], v[160:163], v[230:233], v[10:13]
	v_mfma_f32_16x16x32_bf16 v[2:5], v[182:185], v[226:229], v[2:5]
	v_mfma_f32_16x16x32_bf16 v[2:5], v[186:189], v[230:233], v[2:5]
	s_barrier
	s_branch .LBB0_488
	.p2alignl 6, 3212836864
.LBB0_488:
	s_add_i32 s22, 0, 0x10000
	v_add_u32_e32 v143, s22, v139
	s_add_i32 s23, 0, 0x14000
	ds_read_b128 v[134:137], v143
	ds_read_b128 v[144:147], v143 offset:1024
	ds_read_b128 v[148:151], v143 offset:2048
	ds_read_b128 v[152:155], v143 offset:3072
	v_add_u32_e32 v143, s23, v139
	ds_read_b128 v[156:159], v143
	ds_read_b128 v[160:163], v143 offset:1024
	ds_read_b128 v[182:185], v143 offset:2048
	ds_read_b128 v[186:189], v143 offset:3072
	ds_read_b128 v[190:193], v142
	ds_read_b128 v[194:197], v142 offset:1024
	ds_read_b128 v[198:201], v142 offset:2048
	ds_read_b128 v[214:217], v142 offset:3072
	ds_read_b128 v[218:221], v142 offset:4096
	ds_read_b128 v[222:225], v142 offset:5120
	ds_read_b128 v[226:229], v142 offset:6144
	ds_read_b128 v[230:233], v142 offset:7168
	s_add_u32 s20, s68, 0xfffc0080
	s_addc_u32 s21, s69, -1
	s_cmp_eq_u32 s97, 12
	s_cselect_b32 s77, s57, s21
	s_cselect_b32 s76, s86, s20
	s_cselect_b32 s21, s51, s96
	s_cselect_b32 s20, s87, s91
	s_add_i32 m0, s43, 0xc000
	v_lshl_add_u64 v[202:203], s[68:69], 0, v[132:133]
	global_load_lds_dwordx4 v[202:203], off
	v_lshl_add_u64 v[202:203], v[202:203], 0, s[72:73]
	s_add_i32 m0, s43, 0xe000
	s_nop 0
	global_load_lds_dwordx4 v[202:203], off
	s_waitcnt vmcnt(8) lgkmcnt(0)
	s_barrier
	v_mfma_f32_16x16x32_bf16 v[126:129], v[134:137], v[190:193], v[126:129]
	v_mfma_f32_16x16x32_bf16 v[126:129], v[144:147], v[194:197], v[126:129]
	v_mfma_f32_16x16x32_bf16 v[114:117], v[148:151], v[190:193], v[114:117]
	v_mfma_f32_16x16x32_bf16 v[114:117], v[152:155], v[194:197], v[114:117]
	v_mfma_f32_16x16x32_bf16 v[110:113], v[134:137], v[198:201], v[110:113]
	v_mfma_f32_16x16x32_bf16 v[110:113], v[144:147], v[214:217], v[110:113]
	v_mfma_f32_16x16x32_bf16 v[98:101], v[148:151], v[198:201], v[98:101]
	v_mfma_f32_16x16x32_bf16 v[98:101], v[152:155], v[214:217], v[98:101]
	v_mfma_f32_16x16x32_bf16 v[94:97], v[134:137], v[218:221], v[94:97]
	v_mfma_f32_16x16x32_bf16 v[94:97], v[144:147], v[222:225], v[94:97]
	v_mfma_f32_16x16x32_bf16 v[82:85], v[148:151], v[218:221], v[82:85]
	v_mfma_f32_16x16x32_bf16 v[82:85], v[152:155], v[222:225], v[82:85]
	v_mfma_f32_16x16x32_bf16 v[78:81], v[134:137], v[226:229], v[78:81]
	v_mfma_f32_16x16x32_bf16 v[78:81], v[144:147], v[230:233], v[78:81]
	v_mfma_f32_16x16x32_bf16 v[66:69], v[148:151], v[226:229], v[66:69]
	v_mfma_f32_16x16x32_bf16 v[66:69], v[152:155], v[230:233], v[66:69]
	v_mfma_f32_16x16x32_bf16 v[122:125], v[156:159], v[190:193], v[122:125]
	v_mfma_f32_16x16x32_bf16 v[122:125], v[160:163], v[194:197], v[122:125]
	v_mfma_f32_16x16x32_bf16 v[118:121], v[182:185], v[190:193], v[118:121]
	v_mfma_f32_16x16x32_bf16 v[118:121], v[186:189], v[194:197], v[118:121]
	v_mfma_f32_16x16x32_bf16 v[106:109], v[156:159], v[198:201], v[106:109]
	v_mfma_f32_16x16x32_bf16 v[106:109], v[160:163], v[214:217], v[106:109]
	v_mfma_f32_16x16x32_bf16 v[102:105], v[182:185], v[198:201], v[102:105]
	v_mfma_f32_16x16x32_bf16 v[102:105], v[186:189], v[214:217], v[102:105]
	v_mfma_f32_16x16x32_bf16 v[90:93], v[156:159], v[218:221], v[90:93]
	v_mfma_f32_16x16x32_bf16 v[90:93], v[160:163], v[222:225], v[90:93]
	v_mfma_f32_16x16x32_bf16 v[86:89], v[182:185], v[218:221], v[86:89]
	v_mfma_f32_16x16x32_bf16 v[86:89], v[186:189], v[222:225], v[86:89]
	v_mfma_f32_16x16x32_bf16 v[74:77], v[156:159], v[226:229], v[74:77]
	v_mfma_f32_16x16x32_bf16 v[74:77], v[160:163], v[230:233], v[74:77]
	v_mfma_f32_16x16x32_bf16 v[70:73], v[182:185], v[226:229], v[70:73]
	v_mfma_f32_16x16x32_bf16 v[70:73], v[186:189], v[230:233], v[70:73]
	s_barrier
	ds_read_b128 v[190:193], v142 offset:16384
	ds_read_b128 v[194:197], v142 offset:17408
	ds_read_b128 v[198:201], v142 offset:18432
	ds_read_b128 v[214:217], v142 offset:19456
	ds_read_b128 v[218:221], v142 offset:20480
	ds_read_b128 v[222:225], v142 offset:21504
	ds_read_b128 v[226:229], v142 offset:22528
	ds_read_b128 v[230:233], v142 offset:23552
	v_lshl_add_u64 v[202:203], s[20:21], 0, v[0:1]
	s_add_i32 s20, s22, s14
	s_mov_b32 m0, s20
	s_nop 0
	s_nop 0
	global_load_lds_dwordx4 v[202:203], off
	v_lshl_add_u64 v[234:235], v[202:203], 0, s[72:73]
	s_add_i32 m0, s20, 0x2000
	s_add_i32 s20, s23, s14
	global_load_lds_dwordx4 v[234:235], off
	v_lshl_add_u64 v[234:235], v[202:203], 0, s[28:29]
	s_mov_b32 m0, s20
	s_nop 0
	global_load_lds_dwordx4 v[234:235], off
	v_lshl_add_u64 v[234:235], v[202:203], 0, s[82:83]
	s_add_i32 m0, s20, 0x2000
	s_nop 0
	global_load_lds_dwordx4 v[234:235], off
	v_lshl_add_u64 v[234:235], s[76:77], 0, v[130:131]
	s_mov_b32 m0, s43
	v_lshl_add_u64 v[236:237], v[234:235], 0, s[72:73]
	global_load_lds_dwordx4 v[234:235], off
	s_mov_b32 m0, s46
	s_nop 0
	global_load_lds_dwordx4 v[236:237], off
	s_waitcnt vmcnt(8) lgkmcnt(0)
	s_barrier
	v_mfma_f32_16x16x32_bf16 v[62:65], v[134:137], v[190:193], v[62:65]
	v_mfma_f32_16x16x32_bf16 v[62:65], v[144:147], v[194:197], v[62:65]
	v_mfma_f32_16x16x32_bf16 v[50:53], v[148:151], v[190:193], v[50:53]
	v_mfma_f32_16x16x32_bf16 v[50:53], v[152:155], v[194:197], v[50:53]
	v_mfma_f32_16x16x32_bf16 v[46:49], v[134:137], v[198:201], v[46:49]
	v_mfma_f32_16x16x32_bf16 v[46:49], v[144:147], v[214:217], v[46:49]
	v_mfma_f32_16x16x32_bf16 v[34:37], v[148:151], v[198:201], v[34:37]
	v_mfma_f32_16x16x32_bf16 v[34:37], v[152:155], v[214:217], v[34:37]
	v_mfma_f32_16x16x32_bf16 v[30:33], v[134:137], v[218:221], v[30:33]
	v_mfma_f32_16x16x32_bf16 v[30:33], v[144:147], v[222:225], v[30:33]
	v_mfma_f32_16x16x32_bf16 v[18:21], v[148:151], v[218:221], v[18:21]
	v_mfma_f32_16x16x32_bf16 v[18:21], v[152:155], v[222:225], v[18:21]
	v_mfma_f32_16x16x32_bf16 v[14:17], v[134:137], v[226:229], v[14:17]
	v_mfma_f32_16x16x32_bf16 v[14:17], v[144:147], v[230:233], v[14:17]
	v_mfma_f32_16x16x32_bf16 v[6:9], v[148:151], v[226:229], v[6:9]
	v_mfma_f32_16x16x32_bf16 v[6:9], v[152:155], v[230:233], v[6:9]
	v_mfma_f32_16x16x32_bf16 v[58:61], v[156:159], v[190:193], v[58:61]
	v_mfma_f32_16x16x32_bf16 v[58:61], v[160:163], v[194:197], v[58:61]
	v_mfma_f32_16x16x32_bf16 v[54:57], v[182:185], v[190:193], v[54:57]
	v_mfma_f32_16x16x32_bf16 v[54:57], v[186:189], v[194:197], v[54:57]
	v_mfma_f32_16x16x32_bf16 v[42:45], v[156:159], v[198:201], v[42:45]
	v_mfma_f32_16x16x32_bf16 v[42:45], v[160:163], v[214:217], v[42:45]
	v_mfma_f32_16x16x32_bf16 v[38:41], v[182:185], v[198:201], v[38:41]
	v_mfma_f32_16x16x32_bf16 v[38:41], v[186:189], v[214:217], v[38:41]
	v_mfma_f32_16x16x32_bf16 v[26:29], v[156:159], v[218:221], v[26:29]
	v_mfma_f32_16x16x32_bf16 v[26:29], v[160:163], v[222:225], v[26:29]
	v_mfma_f32_16x16x32_bf16 v[22:25], v[182:185], v[218:221], v[22:25]
	v_mfma_f32_16x16x32_bf16 v[22:25], v[186:189], v[222:225], v[22:25]
	v_mfma_f32_16x16x32_bf16 v[10:13], v[156:159], v[226:229], v[10:13]
	v_mfma_f32_16x16x32_bf16 v[10:13], v[160:163], v[230:233], v[10:13]
	v_mfma_f32_16x16x32_bf16 v[2:5], v[182:185], v[226:229], v[2:5]
	v_mfma_f32_16x16x32_bf16 v[2:5], v[186:189], v[230:233], v[2:5]
	s_barrier
	s_add_i32 s20, 0, 0x18000
	v_add_u32_e32 v143, s20, v139
	s_add_i32 s21, 0, 0x1c000
	ds_read_b128 v[134:137], v143
	ds_read_b128 v[144:147], v143 offset:1024
	ds_read_b128 v[148:151], v143 offset:2048
	ds_read_b128 v[152:155], v143 offset:3072
	v_add_u32_e32 v143, s21, v139
	ds_read_b128 v[156:159], v143
	ds_read_b128 v[160:163], v143 offset:1024
	ds_read_b128 v[182:185], v143 offset:2048
	ds_read_b128 v[186:189], v143 offset:3072
	ds_read_b128 v[190:193], v142 offset:32768
	ds_read_b128 v[194:197], v142 offset:33792
	ds_read_b128 v[198:201], v142 offset:34816
	ds_read_b128 v[214:217], v142 offset:35840
	ds_read_b128 v[218:221], v142 offset:36864
	ds_read_b128 v[222:225], v142 offset:37888
	ds_read_b128 v[226:229], v142 offset:38912
	ds_read_b128 v[230:233], v142 offset:39936
	s_mov_b32 m0, s47
	v_lshl_add_u64 v[236:237], v[234:235], 0, s[28:29]
	global_load_lds_dwordx4 v[236:237], off
	v_lshl_add_u64 v[236:237], v[234:235], 0, s[82:83]
	s_mov_b32 m0, s78
	s_nop 0
	global_load_lds_dwordx4 v[236:237], off
	s_waitcnt vmcnt(8) lgkmcnt(0)
	s_barrier
	v_mfma_f32_16x16x32_bf16 v[126:129], v[134:137], v[190:193], v[126:129]
	v_mfma_f32_16x16x32_bf16 v[126:129], v[144:147], v[194:197], v[126:129]
	v_mfma_f32_16x16x32_bf16 v[114:117], v[148:151], v[190:193], v[114:117]
	v_mfma_f32_16x16x32_bf16 v[114:117], v[152:155], v[194:197], v[114:117]
	v_mfma_f32_16x16x32_bf16 v[110:113], v[134:137], v[198:201], v[110:113]
	v_mfma_f32_16x16x32_bf16 v[110:113], v[144:147], v[214:217], v[110:113]
	v_mfma_f32_16x16x32_bf16 v[98:101], v[148:151], v[198:201], v[98:101]
	v_mfma_f32_16x16x32_bf16 v[98:101], v[152:155], v[214:217], v[98:101]
	v_mfma_f32_16x16x32_bf16 v[94:97], v[134:137], v[218:221], v[94:97]
	v_mfma_f32_16x16x32_bf16 v[94:97], v[144:147], v[222:225], v[94:97]
	v_mfma_f32_16x16x32_bf16 v[82:85], v[148:151], v[218:221], v[82:85]
	v_mfma_f32_16x16x32_bf16 v[82:85], v[152:155], v[222:225], v[82:85]
	v_mfma_f32_16x16x32_bf16 v[78:81], v[134:137], v[226:229], v[78:81]
	v_mfma_f32_16x16x32_bf16 v[78:81], v[144:147], v[230:233], v[78:81]
	v_mfma_f32_16x16x32_bf16 v[66:69], v[148:151], v[226:229], v[66:69]
	v_mfma_f32_16x16x32_bf16 v[66:69], v[152:155], v[230:233], v[66:69]
	v_mfma_f32_16x16x32_bf16 v[122:125], v[156:159], v[190:193], v[122:125]
	v_mfma_f32_16x16x32_bf16 v[122:125], v[160:163], v[194:197], v[122:125]
	v_mfma_f32_16x16x32_bf16 v[118:121], v[182:185], v[190:193], v[118:121]
	v_mfma_f32_16x16x32_bf16 v[118:121], v[186:189], v[194:197], v[118:121]
	v_mfma_f32_16x16x32_bf16 v[106:109], v[156:159], v[198:201], v[106:109]
	v_mfma_f32_16x16x32_bf16 v[106:109], v[160:163], v[214:217], v[106:109]
	v_mfma_f32_16x16x32_bf16 v[102:105], v[182:185], v[198:201], v[102:105]
	v_mfma_f32_16x16x32_bf16 v[102:105], v[186:189], v[214:217], v[102:105]
	v_mfma_f32_16x16x32_bf16 v[90:93], v[156:159], v[218:221], v[90:93]
	v_mfma_f32_16x16x32_bf16 v[90:93], v[160:163], v[222:225], v[90:93]
	v_mfma_f32_16x16x32_bf16 v[86:89], v[182:185], v[218:221], v[86:89]
	v_mfma_f32_16x16x32_bf16 v[86:89], v[186:189], v[222:225], v[86:89]
	v_mfma_f32_16x16x32_bf16 v[74:77], v[156:159], v[226:229], v[74:77]
	v_mfma_f32_16x16x32_bf16 v[74:77], v[160:163], v[230:233], v[74:77]
	v_mfma_f32_16x16x32_bf16 v[70:73], v[182:185], v[226:229], v[70:73]
	v_mfma_f32_16x16x32_bf16 v[70:73], v[186:189], v[230:233], v[70:73]
	s_barrier
	ds_read_b128 v[190:193], v142 offset:49152
	ds_read_b128 v[194:197], v142 offset:50176
	ds_read_b128 v[198:201], v142 offset:51200
	ds_read_b128 v[214:217], v142 offset:52224
	ds_read_b128 v[218:221], v142 offset:53248
	ds_read_b128 v[222:225], v142 offset:54272
	ds_read_b128 v[226:229], v142 offset:55296
	ds_read_b128 v[230:233], v142 offset:56320
	s_add_i32 s20, s20, s14
	s_mov_b32 m0, s20
	v_lshl_add_u64 v[236:237], v[202:203], 0, s[34:35]
	global_load_lds_dwordx4 v[236:237], off
	v_lshl_add_u64 v[236:237], v[202:203], 0, s[38:39]
	s_add_i32 m0, s20, 0x2000
	s_add_i32 s20, s21, s14
	global_load_lds_dwordx4 v[236:237], off
	v_lshl_add_u64 v[236:237], v[202:203], 0, s[44:45]
	s_mov_b32 m0, s20
	v_lshl_add_u64 v[202:203], v[202:203], 0, s[10:11]
	global_load_lds_dwordx4 v[236:237], off
	s_add_i32 m0, s20, 0x2000
	s_nop 0
	global_load_lds_dwordx4 v[202:203], off
	v_lshl_add_u64 v[202:203], v[234:235], 0, s[34:35]
	s_mov_b32 m0, s79
	s_nop 0
	global_load_lds_dwordx4 v[202:203], off
	v_lshl_add_u64 v[202:203], v[234:235], 0, s[38:39]
	s_mov_b32 m0, s88
	s_nop 0
	global_load_lds_dwordx4 v[202:203], off
	s_waitcnt vmcnt(8) lgkmcnt(0)
	s_barrier
	v_mfma_f32_16x16x32_bf16 v[62:65], v[134:137], v[190:193], v[62:65]
	v_mfma_f32_16x16x32_bf16 v[62:65], v[144:147], v[194:197], v[62:65]
	v_mfma_f32_16x16x32_bf16 v[50:53], v[148:151], v[190:193], v[50:53]
	v_mfma_f32_16x16x32_bf16 v[50:53], v[152:155], v[194:197], v[50:53]
	v_mfma_f32_16x16x32_bf16 v[46:49], v[134:137], v[198:201], v[46:49]
	v_mfma_f32_16x16x32_bf16 v[46:49], v[144:147], v[214:217], v[46:49]
	v_mfma_f32_16x16x32_bf16 v[34:37], v[148:151], v[198:201], v[34:37]
	v_mfma_f32_16x16x32_bf16 v[34:37], v[152:155], v[214:217], v[34:37]
	v_mfma_f32_16x16x32_bf16 v[30:33], v[134:137], v[218:221], v[30:33]
	v_mfma_f32_16x16x32_bf16 v[30:33], v[144:147], v[222:225], v[30:33]
	v_mfma_f32_16x16x32_bf16 v[18:21], v[148:151], v[218:221], v[18:21]
	v_mfma_f32_16x16x32_bf16 v[18:21], v[152:155], v[222:225], v[18:21]
	v_mfma_f32_16x16x32_bf16 v[14:17], v[134:137], v[226:229], v[14:17]
	v_mfma_f32_16x16x32_bf16 v[14:17], v[144:147], v[230:233], v[14:17]
	v_mfma_f32_16x16x32_bf16 v[6:9], v[148:151], v[226:229], v[6:9]
	v_mfma_f32_16x16x32_bf16 v[6:9], v[152:155], v[230:233], v[6:9]
	s_add_i32 s97, s97, 2
	s_add_u32 s68, s68, 0x100
	s_addc_u32 s69, s69, 0
	s_add_u32 s91, s91, 0x100
	s_addc_u32 s96, s96, 0
	v_mfma_f32_16x16x32_bf16 v[58:61], v[156:159], v[190:193], v[58:61]
	v_mfma_f32_16x16x32_bf16 v[58:61], v[160:163], v[194:197], v[58:61]
	v_mfma_f32_16x16x32_bf16 v[54:57], v[182:185], v[190:193], v[54:57]
	v_mfma_f32_16x16x32_bf16 v[54:57], v[186:189], v[194:197], v[54:57]
	v_mfma_f32_16x16x32_bf16 v[42:45], v[156:159], v[198:201], v[42:45]
	v_mfma_f32_16x16x32_bf16 v[42:45], v[160:163], v[214:217], v[42:45]
	v_mfma_f32_16x16x32_bf16 v[38:41], v[182:185], v[198:201], v[38:41]
	v_mfma_f32_16x16x32_bf16 v[38:41], v[186:189], v[214:217], v[38:41]
	v_mfma_f32_16x16x32_bf16 v[26:29], v[156:159], v[218:221], v[26:29]
	v_mfma_f32_16x16x32_bf16 v[26:29], v[160:163], v[222:225], v[26:29]
	v_mfma_f32_16x16x32_bf16 v[22:25], v[182:185], v[218:221], v[22:25]
	v_mfma_f32_16x16x32_bf16 v[22:25], v[186:189], v[222:225], v[22:25]
	v_mfma_f32_16x16x32_bf16 v[10:13], v[156:159], v[226:229], v[10:13]
	v_mfma_f32_16x16x32_bf16 v[10:13], v[160:163], v[230:233], v[10:13]
	v_mfma_f32_16x16x32_bf16 v[2:5], v[182:185], v[226:229], v[2:5]
	v_mfma_f32_16x16x32_bf16 v[2:5], v[186:189], v[230:233], v[2:5]
	s_barrier
	s_cmp_gt_u32 s97, 13
	s_cbranch_scc0 .LBB0_488
	s_setprio 0
	s_and_b64 vcc, exec, s[48:49]
	s_cbranch_vccz .LBB0_491
	s_barrier

.Lmid1_604:
	s_add_i32 s22, 0, 0x10000
	s_add_i32 s23, 0, 0x14000
	s_add_u32 s20, s6, 0xfffe0080
	s_addc_u32 s21, s7, -1
	s_cmp_eq_u32 s84, 4
	s_cselect_b32 s69, s42, s21
	s_cselect_b32 s68, s43, s20
	s_cselect_b32 s21, s46, s51
	s_cselect_b32 s20, s47, s49
	s_add_i32 m0, s89, 0xc000
	v_lshl_add_u64 v[162:163], s[6:7], 0, v[132:133]
	global_load_lds_dwordx4 v[162:163], off
	v_lshl_add_u64 v[162:163], v[162:163], 0, s[64:65]
	s_add_i32 m0, s89, 0xe000
	s_nop 0
	global_load_lds_dwordx4 v[162:163], off
	s_waitcnt vmcnt(8) lgkmcnt(0)
	s_barrier
	v_mfma_f32_16x16x32_bf16 v[126:129], v[134:137], v[190:193], 0
	v_mfma_f32_16x16x32_bf16 v[126:129], v[142:145], v[194:197], v[126:129]
	v_mfma_f32_16x16x32_bf16 v[122:125], v[146:149], v[190:193], 0
	v_mfma_f32_16x16x32_bf16 v[122:125], v[150:153], v[194:197], v[122:125]
	v_mfma_f32_16x16x32_bf16 v[110:113], v[134:137], v[198:201], 0
	v_mfma_f32_16x16x32_bf16 v[110:113], v[142:145], v[214:217], v[110:113]
	v_mfma_f32_16x16x32_bf16 v[106:109], v[146:149], v[198:201], 0
	v_mfma_f32_16x16x32_bf16 v[106:109], v[150:153], v[214:217], v[106:109]
	v_mfma_f32_16x16x32_bf16 v[94:97], v[134:137], v[218:221], 0
	v_mfma_f32_16x16x32_bf16 v[94:97], v[142:145], v[222:225], v[94:97]
	v_mfma_f32_16x16x32_bf16 v[90:93], v[146:149], v[218:221], 0
	v_mfma_f32_16x16x32_bf16 v[90:93], v[150:153], v[222:225], v[90:93]
	v_mfma_f32_16x16x32_bf16 v[78:81], v[134:137], v[226:229], 0
	v_mfma_f32_16x16x32_bf16 v[78:81], v[142:145], v[230:233], v[78:81]
	v_mfma_f32_16x16x32_bf16 v[74:77], v[146:149], v[226:229], 0
	v_mfma_f32_16x16x32_bf16 v[74:77], v[150:153], v[230:233], v[74:77]
	v_mfma_f32_16x16x32_bf16 v[118:121], v[154:157], v[190:193], 0
	v_mfma_f32_16x16x32_bf16 v[118:121], v[158:161], v[194:197], v[118:121]
	v_mfma_f32_16x16x32_bf16 v[114:117], v[182:185], v[190:193], 0
	v_mfma_f32_16x16x32_bf16 v[114:117], v[186:189], v[194:197], v[114:117]
	v_mfma_f32_16x16x32_bf16 v[102:105], v[154:157], v[198:201], 0
	v_mfma_f32_16x16x32_bf16 v[102:105], v[158:161], v[214:217], v[102:105]
	v_mfma_f32_16x16x32_bf16 v[98:101], v[182:185], v[198:201], 0
	v_mfma_f32_16x16x32_bf16 v[98:101], v[186:189], v[214:217], v[98:101]
	v_mfma_f32_16x16x32_bf16 v[86:89], v[154:157], v[218:221], 0
	v_mfma_f32_16x16x32_bf16 v[86:89], v[158:161], v[222:225], v[86:89]
	v_mfma_f32_16x16x32_bf16 v[82:85], v[182:185], v[218:221], 0
	v_mfma_f32_16x16x32_bf16 v[82:85], v[186:189], v[222:225], v[82:85]
	v_mfma_f32_16x16x32_bf16 v[70:73], v[154:157], v[226:229], 0
	v_mfma_f32_16x16x32_bf16 v[70:73], v[158:161], v[230:233], v[70:73]
	v_mfma_f32_16x16x32_bf16 v[66:69], v[182:185], v[226:229], 0
	v_mfma_f32_16x16x32_bf16 v[66:69], v[186:189], v[230:233], v[66:69]
	s_barrier
	ds_read_b128 v[190:193], v141 offset:16384
	ds_read_b128 v[194:197], v141 offset:17408
	ds_read_b128 v[198:201], v141 offset:18432
	ds_read_b128 v[214:217], v141 offset:19456
	ds_read_b128 v[218:221], v141 offset:20480
	ds_read_b128 v[222:225], v141 offset:21504
	ds_read_b128 v[226:229], v141 offset:22528
	ds_read_b128 v[230:233], v141 offset:23552
	v_lshl_add_u64 v[162:163], s[20:21], 0, v[0:1]
	s_add_i32 s20, s22, s88
	s_mov_b32 m0, s20
	s_nop 0
	s_nop 0
	global_load_lds_dwordx4 v[162:163], off
	v_lshl_add_u64 v[202:203], v[162:163], 0, s[64:65]
	s_add_i32 m0, s20, 0x2000
	s_add_i32 s20, s23, s88
	global_load_lds_dwordx4 v[202:203], off
	v_lshl_add_u64 v[202:203], v[162:163], 0, s[72:73]
	s_mov_b32 m0, s20
	s_nop 0
	global_load_lds_dwordx4 v[202:203], off
	v_lshl_add_u64 v[202:203], v[162:163], 0, s[74:75]
	s_add_i32 m0, s20, 0x2000
	s_nop 0
	global_load_lds_dwordx4 v[202:203], off
	v_lshl_add_u64 v[202:203], s[68:69], 0, v[130:131]
	s_mov_b32 m0, s89
	v_lshl_add_u64 v[234:235], v[202:203], 0, s[64:65]
	global_load_lds_dwordx4 v[202:203], off
	s_mov_b32 m0, s90
	s_nop 0
	global_load_lds_dwordx4 v[234:235], off
	s_waitcnt vmcnt(8) lgkmcnt(0)
	s_barrier
	v_mfma_f32_16x16x32_bf16 v[62:65], v[134:137], v[190:193], 0
	v_mfma_f32_16x16x32_bf16 v[62:65], v[142:145], v[194:197], v[62:65]
	v_mfma_f32_16x16x32_bf16 v[58:61], v[146:149], v[190:193], 0
	v_mfma_f32_16x16x32_bf16 v[58:61], v[150:153], v[194:197], v[58:61]
	v_mfma_f32_16x16x32_bf16 v[46:49], v[134:137], v[198:201], 0
	v_mfma_f32_16x16x32_bf16 v[46:49], v[142:145], v[214:217], v[46:49]
	v_mfma_f32_16x16x32_bf16 v[42:45], v[146:149], v[198:201], 0
	v_mfma_f32_16x16x32_bf16 v[42:45], v[150:153], v[214:217], v[42:45]
	v_mfma_f32_16x16x32_bf16 v[30:33], v[134:137], v[218:221], 0
	v_mfma_f32_16x16x32_bf16 v[30:33], v[142:145], v[222:225], v[30:33]
	v_mfma_f32_16x16x32_bf16 v[26:29], v[146:149], v[218:221], 0
	v_mfma_f32_16x16x32_bf16 v[26:29], v[150:153], v[222:225], v[26:29]
	v_mfma_f32_16x16x32_bf16 v[14:17], v[134:137], v[226:229], 0
	v_mfma_f32_16x16x32_bf16 v[14:17], v[142:145], v[230:233], v[14:17]
	v_mfma_f32_16x16x32_bf16 v[10:13], v[146:149], v[226:229], 0
	v_mfma_f32_16x16x32_bf16 v[10:13], v[150:153], v[230:233], v[10:13]
	v_mfma_f32_16x16x32_bf16 v[54:57], v[154:157], v[190:193], 0
	v_mfma_f32_16x16x32_bf16 v[54:57], v[158:161], v[194:197], v[54:57]
	v_mfma_f32_16x16x32_bf16 v[50:53], v[182:185], v[190:193], 0
	v_mfma_f32_16x16x32_bf16 v[50:53], v[186:189], v[194:197], v[50:53]
	v_mfma_f32_16x16x32_bf16 v[38:41], v[154:157], v[198:201], 0
	v_mfma_f32_16x16x32_bf16 v[38:41], v[158:161], v[214:217], v[38:41]
	v_mfma_f32_16x16x32_bf16 v[34:37], v[182:185], v[198:201], 0
	v_mfma_f32_16x16x32_bf16 v[34:37], v[186:189], v[214:217], v[34:37]
	v_mfma_f32_16x16x32_bf16 v[22:25], v[154:157], v[218:221], 0
	v_mfma_f32_16x16x32_bf16 v[22:25], v[158:161], v[222:225], v[22:25]
	v_mfma_f32_16x16x32_bf16 v[18:21], v[182:185], v[218:221], 0
	v_mfma_f32_16x16x32_bf16 v[18:21], v[186:189], v[222:225], v[18:21]
	v_mfma_f32_16x16x32_bf16 v[6:9], v[154:157], v[226:229], 0
	v_mfma_f32_16x16x32_bf16 v[6:9], v[158:161], v[230:233], v[6:9]
	v_mfma_f32_16x16x32_bf16 v[2:5], v[182:185], v[226:229], 0
	v_mfma_f32_16x16x32_bf16 v[2:5], v[186:189], v[230:233], v[2:5]
	s_barrier
	s_add_i32 s20, 0, 0x18000
	s_add_i32 s21, 0, 0x1c000
	v_add_u32_e32 v150, s20, v139
	v_add_u32_e32 v186, s21, v139
	ds_read_b128 v[134:137], v150
	ds_read_b128 v[142:145], v150 offset:1024
	ds_read_b128 v[146:149], v150 offset:2048
	ds_read_b128 v[150:153], v150 offset:3072
	ds_read_b128 v[154:157], v186
	ds_read_b128 v[158:161], v186 offset:1024
	ds_read_b128 v[182:185], v186 offset:2048
	ds_read_b128 v[186:189], v186 offset:3072
	ds_read_b128 v[190:193], v141 offset:32768
	ds_read_b128 v[194:197], v141 offset:33792
	ds_read_b128 v[198:201], v141 offset:34816
	ds_read_b128 v[214:217], v141 offset:35840
	ds_read_b128 v[218:221], v141 offset:36864
	ds_read_b128 v[222:225], v141 offset:37888
	ds_read_b128 v[226:229], v141 offset:38912
	ds_read_b128 v[230:233], v141 offset:39936
	s_mov_b32 m0, s91
	v_lshl_add_u64 v[234:235], v[202:203], 0, s[72:73]
	global_load_lds_dwordx4 v[234:235], off
	v_lshl_add_u64 v[234:235], v[202:203], 0, s[74:75]
	s_mov_b32 m0, s96
	s_nop 0
	global_load_lds_dwordx4 v[234:235], off
	s_waitcnt vmcnt(8) lgkmcnt(0)
	s_barrier
	v_mfma_f32_16x16x32_bf16 v[126:129], v[134:137], v[190:193], v[126:129]
	v_mfma_f32_16x16x32_bf16 v[126:129], v[142:145], v[194:197], v[126:129]
	v_mfma_f32_16x16x32_bf16 v[122:125], v[146:149], v[190:193], v[122:125]
	v_mfma_f32_16x16x32_bf16 v[122:125], v[150:153], v[194:197], v[122:125]
	v_mfma_f32_16x16x32_bf16 v[110:113], v[134:137], v[198:201], v[110:113]
	v_mfma_f32_16x16x32_bf16 v[110:113], v[142:145], v[214:217], v[110:113]
	v_mfma_f32_16x16x32_bf16 v[106:109], v[146:149], v[198:201], v[106:109]
	v_mfma_f32_16x16x32_bf16 v[106:109], v[150:153], v[214:217], v[106:109]
	v_mfma_f32_16x16x32_bf16 v[94:97], v[134:137], v[218:221], v[94:97]
	v_mfma_f32_16x16x32_bf16 v[94:97], v[142:145], v[222:225], v[94:97]
	v_mfma_f32_16x16x32_bf16 v[90:93], v[146:149], v[218:221], v[90:93]
	v_mfma_f32_16x16x32_bf16 v[90:93], v[150:153], v[222:225], v[90:93]
	v_mfma_f32_16x16x32_bf16 v[78:81], v[134:137], v[226:229], v[78:81]
	v_mfma_f32_16x16x32_bf16 v[78:81], v[142:145], v[230:233], v[78:81]
	v_mfma_f32_16x16x32_bf16 v[74:77], v[146:149], v[226:229], v[74:77]
	v_mfma_f32_16x16x32_bf16 v[74:77], v[150:153], v[230:233], v[74:77]
	v_mfma_f32_16x16x32_bf16 v[118:121], v[154:157], v[190:193], v[118:121]
	v_mfma_f32_16x16x32_bf16 v[118:121], v[158:161], v[194:197], v[118:121]
	v_mfma_f32_16x16x32_bf16 v[114:117], v[182:185], v[190:193], v[114:117]
	v_mfma_f32_16x16x32_bf16 v[114:117], v[186:189], v[194:197], v[114:117]
	v_mfma_f32_16x16x32_bf16 v[102:105], v[154:157], v[198:201], v[102:105]
	v_mfma_f32_16x16x32_bf16 v[102:105], v[158:161], v[214:217], v[102:105]
	v_mfma_f32_16x16x32_bf16 v[98:101], v[182:185], v[198:201], v[98:101]
	v_mfma_f32_16x16x32_bf16 v[98:101], v[186:189], v[214:217], v[98:101]
	v_mfma_f32_16x16x32_bf16 v[86:89], v[154:157], v[218:221], v[86:89]
	v_mfma_f32_16x16x32_bf16 v[86:89], v[158:161], v[222:225], v[86:89]
	v_mfma_f32_16x16x32_bf16 v[82:85], v[182:185], v[218:221], v[82:85]
	v_mfma_f32_16x16x32_bf16 v[82:85], v[186:189], v[222:225], v[82:85]
	v_mfma_f32_16x16x32_bf16 v[70:73], v[154:157], v[226:229], v[70:73]
	v_mfma_f32_16x16x32_bf16 v[70:73], v[158:161], v[230:233], v[70:73]
	v_mfma_f32_16x16x32_bf16 v[66:69], v[182:185], v[226:229], v[66:69]
	v_mfma_f32_16x16x32_bf16 v[66:69], v[186:189], v[230:233], v[66:69]
	s_barrier
	ds_read_b128 v[190:193], v141 offset:49152
	ds_read_b128 v[194:197], v141 offset:50176
	ds_read_b128 v[198:201], v141 offset:51200
	ds_read_b128 v[214:217], v141 offset:52224
	ds_read_b128 v[218:221], v141 offset:53248
	ds_read_b128 v[222:225], v141 offset:54272
	ds_read_b128 v[226:229], v141 offset:55296
	ds_read_b128 v[230:233], v141 offset:56320
	s_add_i32 s20, s20, s88
	s_mov_b32 m0, s20
	v_lshl_add_u64 v[234:235], v[162:163], 0, s[34:35]
	global_load_lds_dwordx4 v[234:235], off
	v_lshl_add_u64 v[234:235], v[162:163], 0, s[80:81]
	s_add_i32 m0, s20, 0x2000
	s_add_i32 s20, s21, s88
	global_load_lds_dwordx4 v[234:235], off
	v_lshl_add_u64 v[234:235], v[162:163], 0, s[38:39]
	s_mov_b32 m0, s20
	v_lshl_add_u64 v[162:163], v[162:163], 0, s[86:87]
	global_load_lds_dwordx4 v[234:235], off
	s_add_i32 m0, s20, 0x2000
	s_nop 0
	global_load_lds_dwordx4 v[162:163], off
	v_lshl_add_u64 v[162:163], v[202:203], 0, s[34:35]
	s_mov_b32 m0, s97
	s_nop 0
	global_load_lds_dwordx4 v[162:163], off
	v_lshl_add_u64 v[162:163], v[202:203], 0, s[80:81]
	s_mov_b32 m0, s58
	s_nop 0
	global_load_lds_dwordx4 v[162:163], off
	s_waitcnt vmcnt(8) lgkmcnt(0)
	s_barrier
	v_mfma_f32_16x16x32_bf16 v[62:65], v[134:137], v[190:193], v[62:65]
	v_mfma_f32_16x16x32_bf16 v[62:65], v[142:145], v[194:197], v[62:65]
	v_mfma_f32_16x16x32_bf16 v[58:61], v[146:149], v[190:193], v[58:61]
	v_mfma_f32_16x16x32_bf16 v[58:61], v[150:153], v[194:197], v[58:61]
	v_mfma_f32_16x16x32_bf16 v[46:49], v[134:137], v[198:201], v[46:49]
	v_mfma_f32_16x16x32_bf16 v[46:49], v[142:145], v[214:217], v[46:49]
	v_mfma_f32_16x16x32_bf16 v[42:45], v[146:149], v[198:201], v[42:45]
	v_mfma_f32_16x16x32_bf16 v[42:45], v[150:153], v[214:217], v[42:45]
	v_mfma_f32_16x16x32_bf16 v[30:33], v[134:137], v[218:221], v[30:33]
	v_mfma_f32_16x16x32_bf16 v[30:33], v[142:145], v[222:225], v[30:33]
	v_mfma_f32_16x16x32_bf16 v[26:29], v[146:149], v[218:221], v[26:29]
	v_mfma_f32_16x16x32_bf16 v[26:29], v[150:153], v[222:225], v[26:29]
	v_mfma_f32_16x16x32_bf16 v[14:17], v[134:137], v[226:229], v[14:17]
	v_mfma_f32_16x16x32_bf16 v[14:17], v[142:145], v[230:233], v[14:17]
	v_mfma_f32_16x16x32_bf16 v[10:13], v[146:149], v[226:229], v[10:13]
	v_mfma_f32_16x16x32_bf16 v[10:13], v[150:153], v[230:233], v[10:13]
	s_add_i32 s84, s84, 2
	s_add_u32 s6, s6, 0x100
	s_addc_u32 s7, s7, 0
	s_add_u32 s49, s49, 0x100
	s_addc_u32 s51, s51, 0
	v_mfma_f32_16x16x32_bf16 v[54:57], v[154:157], v[190:193], v[54:57]
	v_mfma_f32_16x16x32_bf16 v[54:57], v[158:161], v[194:197], v[54:57]
	v_mfma_f32_16x16x32_bf16 v[50:53], v[182:185], v[190:193], v[50:53]
	v_mfma_f32_16x16x32_bf16 v[50:53], v[186:189], v[194:197], v[50:53]
	v_mfma_f32_16x16x32_bf16 v[38:41], v[154:157], v[198:201], v[38:41]
	v_mfma_f32_16x16x32_bf16 v[38:41], v[158:161], v[214:217], v[38:41]
	v_mfma_f32_16x16x32_bf16 v[34:37], v[182:185], v[198:201], v[34:37]
	v_mfma_f32_16x16x32_bf16 v[34:37], v[186:189], v[214:217], v[34:37]
	v_mfma_f32_16x16x32_bf16 v[22:25], v[154:157], v[218:221], v[22:25]
	v_mfma_f32_16x16x32_bf16 v[22:25], v[158:161], v[222:225], v[22:25]
	v_mfma_f32_16x16x32_bf16 v[18:21], v[182:185], v[218:221], v[18:21]
	v_mfma_f32_16x16x32_bf16 v[18:21], v[186:189], v[222:225], v[18:21]
	v_mfma_f32_16x16x32_bf16 v[6:9], v[154:157], v[226:229], v[6:9]
	v_mfma_f32_16x16x32_bf16 v[6:9], v[158:161], v[230:233], v[6:9]
	v_mfma_f32_16x16x32_bf16 v[2:5], v[182:185], v[226:229], v[2:5]
	v_mfma_f32_16x16x32_bf16 v[2:5], v[186:189], v[230:233], v[2:5]
	s_barrier
	s_branch .LBB0_604
	.p2alignl 6, 3212836864
.LBB0_604:
	s_add_i32 s22, 0, 0x10000
	s_add_i32 s23, 0, 0x14000
	v_add_u32_e32 v150, s22, v139
	v_add_u32_e32 v162, s23, v139
	ds_read_b128 v[134:137], v150
	ds_read_b128 v[142:145], v150 offset:1024
	ds_read_b128 v[146:149], v150 offset:2048
	ds_read_b128 v[150:153], v150 offset:3072
	ds_read_b128 v[154:157], v162
	ds_read_b128 v[158:161], v162 offset:1024
	ds_read_b128 v[182:185], v162 offset:2048
	ds_read_b128 v[186:189], v162 offset:3072
	ds_read_b128 v[190:193], v141
	ds_read_b128 v[194:197], v141 offset:1024
	ds_read_b128 v[198:201], v141 offset:2048
	ds_read_b128 v[214:217], v141 offset:3072
	ds_read_b128 v[218:221], v141 offset:4096
	ds_read_b128 v[222:225], v141 offset:5120
	ds_read_b128 v[226:229], v141 offset:6144
	ds_read_b128 v[230:233], v141 offset:7168
	s_add_u32 s20, s6, 0xfffe0080
	s_addc_u32 s21, s7, -1
	s_cmp_eq_u32 s84, 4
	s_cselect_b32 s69, s42, s21
	s_cselect_b32 s68, s43, s20
	s_cselect_b32 s21, s46, s51
	s_cselect_b32 s20, s47, s49
	s_add_i32 m0, s89, 0xc000
	v_lshl_add_u64 v[162:163], s[6:7], 0, v[132:133]
	global_load_lds_dwordx4 v[162:163], off
	v_lshl_add_u64 v[162:163], v[162:163], 0, s[64:65]
	s_add_i32 m0, s89, 0xe000
	s_nop 0
	global_load_lds_dwordx4 v[162:163], off
	s_waitcnt vmcnt(8) lgkmcnt(0)
	s_barrier
	v_mfma_f32_16x16x32_bf16 v[126:129], v[134:137], v[190:193], v[126:129]
	v_mfma_f32_16x16x32_bf16 v[126:129], v[142:145], v[194:197], v[126:129]
	v_mfma_f32_16x16x32_bf16 v[122:125], v[146:149], v[190:193], v[122:125]
	v_mfma_f32_16x16x32_bf16 v[122:125], v[150:153], v[194:197], v[122:125]
	v_mfma_f32_16x16x32_bf16 v[110:113], v[134:137], v[198:201], v[110:113]
	v_mfma_f32_16x16x32_bf16 v[110:113], v[142:145], v[214:217], v[110:113]
	v_mfma_f32_16x16x32_bf16 v[106:109], v[146:149], v[198:201], v[106:109]
	v_mfma_f32_16x16x32_bf16 v[106:109], v[150:153], v[214:217], v[106:109]
	v_mfma_f32_16x16x32_bf16 v[94:97], v[134:137], v[218:221], v[94:97]
	v_mfma_f32_16x16x32_bf16 v[94:97], v[142:145], v[222:225], v[94:97]
	v_mfma_f32_16x16x32_bf16 v[90:93], v[146:149], v[218:221], v[90:93]
	v_mfma_f32_16x16x32_bf16 v[90:93], v[150:153], v[222:225], v[90:93]
	v_mfma_f32_16x16x32_bf16 v[78:81], v[134:137], v[226:229], v[78:81]
	v_mfma_f32_16x16x32_bf16 v[78:81], v[142:145], v[230:233], v[78:81]
	v_mfma_f32_16x16x32_bf16 v[74:77], v[146:149], v[226:229], v[74:77]
	v_mfma_f32_16x16x32_bf16 v[74:77], v[150:153], v[230:233], v[74:77]
	v_mfma_f32_16x16x32_bf16 v[118:121], v[154:157], v[190:193], v[118:121]
	v_mfma_f32_16x16x32_bf16 v[118:121], v[158:161], v[194:197], v[118:121]
	v_mfma_f32_16x16x32_bf16 v[114:117], v[182:185], v[190:193], v[114:117]
	v_mfma_f32_16x16x32_bf16 v[114:117], v[186:189], v[194:197], v[114:117]
	v_mfma_f32_16x16x32_bf16 v[102:105], v[154:157], v[198:201], v[102:105]
	v_mfma_f32_16x16x32_bf16 v[102:105], v[158:161], v[214:217], v[102:105]
	v_mfma_f32_16x16x32_bf16 v[98:101], v[182:185], v[198:201], v[98:101]
	v_mfma_f32_16x16x32_bf16 v[98:101], v[186:189], v[214:217], v[98:101]
	v_mfma_f32_16x16x32_bf16 v[86:89], v[154:157], v[218:221], v[86:89]
	v_mfma_f32_16x16x32_bf16 v[86:89], v[158:161], v[222:225], v[86:89]
	v_mfma_f32_16x16x32_bf16 v[82:85], v[182:185], v[218:221], v[82:85]
	v_mfma_f32_16x16x32_bf16 v[82:85], v[186:189], v[222:225], v[82:85]
	v_mfma_f32_16x16x32_bf16 v[70:73], v[154:157], v[226:229], v[70:73]
	v_mfma_f32_16x16x32_bf16 v[70:73], v[158:161], v[230:233], v[70:73]
	v_mfma_f32_16x16x32_bf16 v[66:69], v[182:185], v[226:229], v[66:69]
	v_mfma_f32_16x16x32_bf16 v[66:69], v[186:189], v[230:233], v[66:69]
	s_barrier
	ds_read_b128 v[190:193], v141 offset:16384
	ds_read_b128 v[194:197], v141 offset:17408
	ds_read_b128 v[198:201], v141 offset:18432
	ds_read_b128 v[214:217], v141 offset:19456
	ds_read_b128 v[218:221], v141 offset:20480
	ds_read_b128 v[222:225], v141 offset:21504
	ds_read_b128 v[226:229], v141 offset:22528
	ds_read_b128 v[230:233], v141 offset:23552
	v_lshl_add_u64 v[162:163], s[20:21], 0, v[0:1]
	s_add_i32 s20, s22, s88
	s_mov_b32 m0, s20
	s_nop 0
	s_nop 0
	global_load_lds_dwordx4 v[162:163], off
	v_lshl_add_u64 v[202:203], v[162:163], 0, s[64:65]
	s_add_i32 m0, s20, 0x2000
	s_add_i32 s20, s23, s88
	global_load_lds_dwordx4 v[202:203], off
	v_lshl_add_u64 v[202:203], v[162:163], 0, s[72:73]
	s_mov_b32 m0, s20
	s_nop 0
	global_load_lds_dwordx4 v[202:203], off
	v_lshl_add_u64 v[202:203], v[162:163], 0, s[74:75]
	s_add_i32 m0, s20, 0x2000
	s_nop 0
	global_load_lds_dwordx4 v[202:203], off
	v_lshl_add_u64 v[202:203], s[68:69], 0, v[130:131]
	s_mov_b32 m0, s89
	v_lshl_add_u64 v[234:235], v[202:203], 0, s[64:65]
	global_load_lds_dwordx4 v[202:203], off
	s_mov_b32 m0, s90
	s_nop 0
	global_load_lds_dwordx4 v[234:235], off
	s_waitcnt vmcnt(8) lgkmcnt(0)
	s_barrier
	v_mfma_f32_16x16x32_bf16 v[62:65], v[134:137], v[190:193], v[62:65]
	v_mfma_f32_16x16x32_bf16 v[62:65], v[142:145], v[194:197], v[62:65]
	v_mfma_f32_16x16x32_bf16 v[58:61], v[146:149], v[190:193], v[58:61]
	v_mfma_f32_16x16x32_bf16 v[58:61], v[150:153], v[194:197], v[58:61]
	v_mfma_f32_16x16x32_bf16 v[46:49], v[134:137], v[198:201], v[46:49]
	v_mfma_f32_16x16x32_bf16 v[46:49], v[142:145], v[214:217], v[46:49]
	v_mfma_f32_16x16x32_bf16 v[42:45], v[146:149], v[198:201], v[42:45]
	v_mfma_f32_16x16x32_bf16 v[42:45], v[150:153], v[214:217], v[42:45]
	v_mfma_f32_16x16x32_bf16 v[30:33], v[134:137], v[218:221], v[30:33]
	v_mfma_f32_16x16x32_bf16 v[30:33], v[142:145], v[222:225], v[30:33]
	v_mfma_f32_16x16x32_bf16 v[26:29], v[146:149], v[218:221], v[26:29]
	v_mfma_f32_16x16x32_bf16 v[26:29], v[150:153], v[222:225], v[26:29]
	v_mfma_f32_16x16x32_bf16 v[14:17], v[134:137], v[226:229], v[14:17]
	v_mfma_f32_16x16x32_bf16 v[14:17], v[142:145], v[230:233], v[14:17]
	v_mfma_f32_16x16x32_bf16 v[10:13], v[146:149], v[226:229], v[10:13]
	v_mfma_f32_16x16x32_bf16 v[10:13], v[150:153], v[230:233], v[10:13]
	v_mfma_f32_16x16x32_bf16 v[54:57], v[154:157], v[190:193], v[54:57]
	v_mfma_f32_16x16x32_bf16 v[54:57], v[158:161], v[194:197], v[54:57]
	v_mfma_f32_16x16x32_bf16 v[50:53], v[182:185], v[190:193], v[50:53]
	v_mfma_f32_16x16x32_bf16 v[50:53], v[186:189], v[194:197], v[50:53]
	v_mfma_f32_16x16x32_bf16 v[38:41], v[154:157], v[198:201], v[38:41]
	v_mfma_f32_16x16x32_bf16 v[38:41], v[158:161], v[214:217], v[38:41]
	v_mfma_f32_16x16x32_bf16 v[34:37], v[182:185], v[198:201], v[34:37]
	v_mfma_f32_16x16x32_bf16 v[34:37], v[186:189], v[214:217], v[34:37]
	v_mfma_f32_16x16x32_bf16 v[22:25], v[154:157], v[218:221], v[22:25]
	v_mfma_f32_16x16x32_bf16 v[22:25], v[158:161], v[222:225], v[22:25]
	v_mfma_f32_16x16x32_bf16 v[18:21], v[182:185], v[218:221], v[18:21]
	v_mfma_f32_16x16x32_bf16 v[18:21], v[186:189], v[222:225], v[18:21]
	v_mfma_f32_16x16x32_bf16 v[6:9], v[154:157], v[226:229], v[6:9]
	v_mfma_f32_16x16x32_bf16 v[6:9], v[158:161], v[230:233], v[6:9]
	v_mfma_f32_16x16x32_bf16 v[2:5], v[182:185], v[226:229], v[2:5]
	v_mfma_f32_16x16x32_bf16 v[2:5], v[186:189], v[230:233], v[2:5]
	s_barrier
	s_add_i32 s20, 0, 0x18000
	s_add_i32 s21, 0, 0x1c000
	v_add_u32_e32 v150, s20, v139
	v_add_u32_e32 v186, s21, v139
	ds_read_b128 v[134:137], v150
	ds_read_b128 v[142:145], v150 offset:1024
	ds_read_b128 v[146:149], v150 offset:2048
	ds_read_b128 v[150:153], v150 offset:3072
	ds_read_b128 v[154:157], v186
	ds_read_b128 v[158:161], v186 offset:1024
	ds_read_b128 v[182:185], v186 offset:2048
	ds_read_b128 v[186:189], v186 offset:3072
	ds_read_b128 v[190:193], v141 offset:32768
	ds_read_b128 v[194:197], v141 offset:33792
	ds_read_b128 v[198:201], v141 offset:34816
	ds_read_b128 v[214:217], v141 offset:35840
	ds_read_b128 v[218:221], v141 offset:36864
	ds_read_b128 v[222:225], v141 offset:37888
	ds_read_b128 v[226:229], v141 offset:38912
	ds_read_b128 v[230:233], v141 offset:39936
	s_mov_b32 m0, s91
	v_lshl_add_u64 v[234:235], v[202:203], 0, s[72:73]
	global_load_lds_dwordx4 v[234:235], off
	v_lshl_add_u64 v[234:235], v[202:203], 0, s[74:75]
	s_mov_b32 m0, s96
	s_nop 0
	global_load_lds_dwordx4 v[234:235], off
	s_waitcnt vmcnt(8) lgkmcnt(0)
	s_barrier
	v_mfma_f32_16x16x32_bf16 v[126:129], v[134:137], v[190:193], v[126:129]
	v_mfma_f32_16x16x32_bf16 v[126:129], v[142:145], v[194:197], v[126:129]
	v_mfma_f32_16x16x32_bf16 v[122:125], v[146:149], v[190:193], v[122:125]
	v_mfma_f32_16x16x32_bf16 v[122:125], v[150:153], v[194:197], v[122:125]
	v_mfma_f32_16x16x32_bf16 v[110:113], v[134:137], v[198:201], v[110:113]
	v_mfma_f32_16x16x32_bf16 v[110:113], v[142:145], v[214:217], v[110:113]
	v_mfma_f32_16x16x32_bf16 v[106:109], v[146:149], v[198:201], v[106:109]
	v_mfma_f32_16x16x32_bf16 v[106:109], v[150:153], v[214:217], v[106:109]
	v_mfma_f32_16x16x32_bf16 v[94:97], v[134:137], v[218:221], v[94:97]
	v_mfma_f32_16x16x32_bf16 v[94:97], v[142:145], v[222:225], v[94:97]
	v_mfma_f32_16x16x32_bf16 v[90:93], v[146:149], v[218:221], v[90:93]
	v_mfma_f32_16x16x32_bf16 v[90:93], v[150:153], v[222:225], v[90:93]
	v_mfma_f32_16x16x32_bf16 v[78:81], v[134:137], v[226:229], v[78:81]
	v_mfma_f32_16x16x32_bf16 v[78:81], v[142:145], v[230:233], v[78:81]
	v_mfma_f32_16x16x32_bf16 v[74:77], v[146:149], v[226:229], v[74:77]
	v_mfma_f32_16x16x32_bf16 v[74:77], v[150:153], v[230:233], v[74:77]
	v_mfma_f32_16x16x32_bf16 v[118:121], v[154:157], v[190:193], v[118:121]
	v_mfma_f32_16x16x32_bf16 v[118:121], v[158:161], v[194:197], v[118:121]
	v_mfma_f32_16x16x32_bf16 v[114:117], v[182:185], v[190:193], v[114:117]
	v_mfma_f32_16x16x32_bf16 v[114:117], v[186:189], v[194:197], v[114:117]
	v_mfma_f32_16x16x32_bf16 v[102:105], v[154:157], v[198:201], v[102:105]
	v_mfma_f32_16x16x32_bf16 v[102:105], v[158:161], v[214:217], v[102:105]
	v_mfma_f32_16x16x32_bf16 v[98:101], v[182:185], v[198:201], v[98:101]
	v_mfma_f32_16x16x32_bf16 v[98:101], v[186:189], v[214:217], v[98:101]
	v_mfma_f32_16x16x32_bf16 v[86:89], v[154:157], v[218:221], v[86:89]
	v_mfma_f32_16x16x32_bf16 v[86:89], v[158:161], v[222:225], v[86:89]
	v_mfma_f32_16x16x32_bf16 v[82:85], v[182:185], v[218:221], v[82:85]
	v_mfma_f32_16x16x32_bf16 v[82:85], v[186:189], v[222:225], v[82:85]
	v_mfma_f32_16x16x32_bf16 v[70:73], v[154:157], v[226:229], v[70:73]
	v_mfma_f32_16x16x32_bf16 v[70:73], v[158:161], v[230:233], v[70:73]
	v_mfma_f32_16x16x32_bf16 v[66:69], v[182:185], v[226:229], v[66:69]
	v_mfma_f32_16x16x32_bf16 v[66:69], v[186:189], v[230:233], v[66:69]
	s_barrier
	ds_read_b128 v[190:193], v141 offset:49152
	ds_read_b128 v[194:197], v141 offset:50176
	ds_read_b128 v[198:201], v141 offset:51200
	ds_read_b128 v[214:217], v141 offset:52224
	ds_read_b128 v[218:221], v141 offset:53248
	ds_read_b128 v[222:225], v141 offset:54272
	ds_read_b128 v[226:229], v141 offset:55296
	ds_read_b128 v[230:233], v141 offset:56320
	s_add_i32 s20, s20, s88
	s_mov_b32 m0, s20
	v_lshl_add_u64 v[234:235], v[162:163], 0, s[34:35]
	global_load_lds_dwordx4 v[234:235], off
	v_lshl_add_u64 v[234:235], v[162:163], 0, s[80:81]
	s_add_i32 m0, s20, 0x2000
	s_add_i32 s20, s21, s88
	global_load_lds_dwordx4 v[234:235], off
	v_lshl_add_u64 v[234:235], v[162:163], 0, s[38:39]
	s_mov_b32 m0, s20
	v_lshl_add_u64 v[162:163], v[162:163], 0, s[86:87]
	global_load_lds_dwordx4 v[234:235], off
	s_add_i32 m0, s20, 0x2000
	s_nop 0
	global_load_lds_dwordx4 v[162:163], off
	v_lshl_add_u64 v[162:163], v[202:203], 0, s[34:35]
	s_mov_b32 m0, s97
	s_nop 0
	global_load_lds_dwordx4 v[162:163], off
	v_lshl_add_u64 v[162:163], v[202:203], 0, s[80:81]
	s_mov_b32 m0, s58
	s_nop 0
	global_load_lds_dwordx4 v[162:163], off
	s_waitcnt vmcnt(8) lgkmcnt(0)
	s_barrier
	v_mfma_f32_16x16x32_bf16 v[62:65], v[134:137], v[190:193], v[62:65]
	v_mfma_f32_16x16x32_bf16 v[62:65], v[142:145], v[194:197], v[62:65]
	v_mfma_f32_16x16x32_bf16 v[58:61], v[146:149], v[190:193], v[58:61]
	v_mfma_f32_16x16x32_bf16 v[58:61], v[150:153], v[194:197], v[58:61]
	v_mfma_f32_16x16x32_bf16 v[46:49], v[134:137], v[198:201], v[46:49]
	v_mfma_f32_16x16x32_bf16 v[46:49], v[142:145], v[214:217], v[46:49]
	v_mfma_f32_16x16x32_bf16 v[42:45], v[146:149], v[198:201], v[42:45]
	v_mfma_f32_16x16x32_bf16 v[42:45], v[150:153], v[214:217], v[42:45]
	v_mfma_f32_16x16x32_bf16 v[30:33], v[134:137], v[218:221], v[30:33]
	v_mfma_f32_16x16x32_bf16 v[30:33], v[142:145], v[222:225], v[30:33]
	v_mfma_f32_16x16x32_bf16 v[26:29], v[146:149], v[218:221], v[26:29]
	v_mfma_f32_16x16x32_bf16 v[26:29], v[150:153], v[222:225], v[26:29]
	v_mfma_f32_16x16x32_bf16 v[14:17], v[134:137], v[226:229], v[14:17]
	v_mfma_f32_16x16x32_bf16 v[14:17], v[142:145], v[230:233], v[14:17]
	v_mfma_f32_16x16x32_bf16 v[10:13], v[146:149], v[226:229], v[10:13]
	v_mfma_f32_16x16x32_bf16 v[10:13], v[150:153], v[230:233], v[10:13]
	s_add_i32 s84, s84, 2
	s_add_u32 s6, s6, 0x100
	s_addc_u32 s7, s7, 0
	s_add_u32 s49, s49, 0x100
	s_addc_u32 s51, s51, 0
	v_mfma_f32_16x16x32_bf16 v[54:57], v[154:157], v[190:193], v[54:57]
	v_mfma_f32_16x16x32_bf16 v[54:57], v[158:161], v[194:197], v[54:57]
	v_mfma_f32_16x16x32_bf16 v[50:53], v[182:185], v[190:193], v[50:53]
	v_mfma_f32_16x16x32_bf16 v[50:53], v[186:189], v[194:197], v[50:53]
	v_mfma_f32_16x16x32_bf16 v[38:41], v[154:157], v[198:201], v[38:41]
	v_mfma_f32_16x16x32_bf16 v[38:41], v[158:161], v[214:217], v[38:41]
	v_mfma_f32_16x16x32_bf16 v[34:37], v[182:185], v[198:201], v[34:37]
	v_mfma_f32_16x16x32_bf16 v[34:37], v[186:189], v[214:217], v[34:37]
	v_mfma_f32_16x16x32_bf16 v[22:25], v[154:157], v[218:221], v[22:25]
	v_mfma_f32_16x16x32_bf16 v[22:25], v[158:161], v[222:225], v[22:25]
	v_mfma_f32_16x16x32_bf16 v[18:21], v[182:185], v[218:221], v[18:21]
	v_mfma_f32_16x16x32_bf16 v[18:21], v[186:189], v[222:225], v[18:21]
	v_mfma_f32_16x16x32_bf16 v[6:9], v[154:157], v[226:229], v[6:9]
	v_mfma_f32_16x16x32_bf16 v[6:9], v[158:161], v[230:233], v[6:9]
	v_mfma_f32_16x16x32_bf16 v[2:5], v[182:185], v[226:229], v[2:5]
	v_mfma_f32_16x16x32_bf16 v[2:5], v[186:189], v[230:233], v[2:5]
	s_barrier
	s_cmp_gt_u32 s84, 5
	s_cbranch_scc0 .LBB0_604
	s_setprio 0
	s_and_b64 vcc, exec, s[52:53]
	s_cbranch_vccz .LBB0_607
	s_barrier

.Lmid1_778:
	s_add_i32 s22, 0, 0x10000
	s_add_i32 s23, 0, 0x14000
	s_add_u32 s20, s76, 0xfffc0080
	s_addc_u32 s21, s77, -1
	s_cmp_eq_u32 vcc_hi, 12
	s_cselect_b32 s79, s61, s21
	s_cselect_b32 s78, s85, s20
	s_cselect_b32 s21, s59, vcc_lo
	s_cselect_b32 s20, s86, s87
	s_add_i32 m0, s43, 0xc000
	v_lshl_add_u64 v[202:203], s[76:77], 0, v[182:183]
	global_load_lds_dwordx4 v[202:203], off
	v_lshl_add_u64 v[202:203], v[202:203], 0, s[72:73]
	s_add_i32 m0, s43, 0xe000
	s_nop 0
	global_load_lds_dwordx4 v[202:203], off
	s_waitcnt vmcnt(8) lgkmcnt(0)
	s_barrier
	v_mfma_f32_16x16x32_bf16 v[126:129], v[130:133], v[184:187], 0
	v_mfma_f32_16x16x32_bf16 v[126:129], v[134:137], v[188:191], v[126:129]
	v_mfma_f32_16x16x32_bf16 v[122:125], v[138:141], v[184:187], 0
	v_mfma_f32_16x16x32_bf16 v[122:125], v[142:145], v[188:191], v[122:125]
	v_mfma_f32_16x16x32_bf16 v[110:113], v[130:133], v[198:201], 0
	v_mfma_f32_16x16x32_bf16 v[110:113], v[134:137], v[214:217], v[110:113]
	v_mfma_f32_16x16x32_bf16 v[106:109], v[138:141], v[198:201], 0
	v_mfma_f32_16x16x32_bf16 v[106:109], v[142:145], v[214:217], v[106:109]
	v_mfma_f32_16x16x32_bf16 v[94:97], v[130:133], v[218:221], 0
	v_mfma_f32_16x16x32_bf16 v[94:97], v[134:137], v[222:225], v[94:97]
	v_mfma_f32_16x16x32_bf16 v[90:93], v[138:141], v[218:221], 0
	v_mfma_f32_16x16x32_bf16 v[90:93], v[142:145], v[222:225], v[90:93]
	v_mfma_f32_16x16x32_bf16 v[78:81], v[130:133], v[226:229], 0
	v_mfma_f32_16x16x32_bf16 v[78:81], v[134:137], v[230:233], v[78:81]
	v_mfma_f32_16x16x32_bf16 v[74:77], v[138:141], v[226:229], 0
	v_mfma_f32_16x16x32_bf16 v[74:77], v[142:145], v[230:233], v[74:77]
	v_mfma_f32_16x16x32_bf16 v[118:121], v[146:149], v[184:187], 0
	v_mfma_f32_16x16x32_bf16 v[118:121], v[150:153], v[188:191], v[118:121]
	v_mfma_f32_16x16x32_bf16 v[114:117], v[154:157], v[184:187], 0
	v_mfma_f32_16x16x32_bf16 v[114:117], v[158:161], v[188:191], v[114:117]
	v_mfma_f32_16x16x32_bf16 v[102:105], v[146:149], v[198:201], 0
	v_mfma_f32_16x16x32_bf16 v[102:105], v[150:153], v[214:217], v[102:105]
	v_mfma_f32_16x16x32_bf16 v[98:101], v[154:157], v[198:201], 0
	v_mfma_f32_16x16x32_bf16 v[98:101], v[158:161], v[214:217], v[98:101]
	v_mfma_f32_16x16x32_bf16 v[86:89], v[146:149], v[218:221], 0
	v_mfma_f32_16x16x32_bf16 v[86:89], v[150:153], v[222:225], v[86:89]
	v_mfma_f32_16x16x32_bf16 v[82:85], v[154:157], v[218:221], 0
	v_mfma_f32_16x16x32_bf16 v[82:85], v[158:161], v[222:225], v[82:85]
	v_mfma_f32_16x16x32_bf16 v[70:73], v[146:149], v[226:229], 0
	v_mfma_f32_16x16x32_bf16 v[70:73], v[150:153], v[230:233], v[70:73]
	v_mfma_f32_16x16x32_bf16 v[66:69], v[154:157], v[226:229], 0
	v_mfma_f32_16x16x32_bf16 v[66:69], v[158:161], v[230:233], v[66:69]
	s_barrier
	ds_read_b128 v[184:187], v196 offset:16384
	ds_read_b128 v[188:191], v196 offset:17408
	ds_read_b128 v[198:201], v196 offset:18432
	ds_read_b128 v[214:217], v196 offset:19456
	ds_read_b128 v[218:221], v196 offset:20480
	ds_read_b128 v[222:225], v196 offset:21504
	ds_read_b128 v[226:229], v196 offset:22528
	ds_read_b128 v[230:233], v196 offset:23552
	v_lshl_add_u64 v[202:203], s[20:21], 0, v[0:1]
	s_add_i32 s20, s22, s14
	s_mov_b32 m0, s20
	s_nop 0
	s_nop 0
	global_load_lds_dwordx4 v[202:203], off
	v_lshl_add_u64 v[234:235], v[202:203], 0, s[72:73]
	s_add_i32 m0, s20, 0x2000
	s_add_i32 s20, s23, s14
	global_load_lds_dwordx4 v[234:235], off
	v_lshl_add_u64 v[234:235], v[202:203], 0, s[28:29]
	s_mov_b32 m0, s20
	s_nop 0
	global_load_lds_dwordx4 v[234:235], off
	v_lshl_add_u64 v[234:235], v[202:203], 0, s[82:83]
	s_add_i32 m0, s20, 0x2000
	s_nop 0
	global_load_lds_dwordx4 v[234:235], off
	v_lshl_add_u64 v[234:235], s[78:79], 0, v[162:163]
	s_mov_b32 m0, s43
	v_lshl_add_u64 v[236:237], v[234:235], 0, s[72:73]
	global_load_lds_dwordx4 v[234:235], off
	s_mov_b32 m0, s46
	s_nop 0
	global_load_lds_dwordx4 v[236:237], off
	s_waitcnt vmcnt(8) lgkmcnt(0)
	s_barrier
	v_mfma_f32_16x16x32_bf16 v[62:65], v[130:133], v[184:187], 0
	v_mfma_f32_16x16x32_bf16 v[62:65], v[134:137], v[188:191], v[62:65]
	v_mfma_f32_16x16x32_bf16 v[58:61], v[138:141], v[184:187], 0
	v_mfma_f32_16x16x32_bf16 v[58:61], v[142:145], v[188:191], v[58:61]
	v_mfma_f32_16x16x32_bf16 v[46:49], v[130:133], v[198:201], 0
	v_mfma_f32_16x16x32_bf16 v[46:49], v[134:137], v[214:217], v[46:49]
	v_mfma_f32_16x16x32_bf16 v[42:45], v[138:141], v[198:201], 0
	v_mfma_f32_16x16x32_bf16 v[42:45], v[142:145], v[214:217], v[42:45]
	v_mfma_f32_16x16x32_bf16 v[30:33], v[130:133], v[218:221], 0
	v_mfma_f32_16x16x32_bf16 v[30:33], v[134:137], v[222:225], v[30:33]
	v_mfma_f32_16x16x32_bf16 v[26:29], v[138:141], v[218:221], 0
	v_mfma_f32_16x16x32_bf16 v[26:29], v[142:145], v[222:225], v[26:29]
	v_mfma_f32_16x16x32_bf16 v[14:17], v[130:133], v[226:229], 0
	v_mfma_f32_16x16x32_bf16 v[14:17], v[134:137], v[230:233], v[14:17]
	v_mfma_f32_16x16x32_bf16 v[10:13], v[138:141], v[226:229], 0
	v_mfma_f32_16x16x32_bf16 v[10:13], v[142:145], v[230:233], v[10:13]
	v_mfma_f32_16x16x32_bf16 v[54:57], v[146:149], v[184:187], 0
	v_mfma_f32_16x16x32_bf16 v[54:57], v[150:153], v[188:191], v[54:57]
	v_mfma_f32_16x16x32_bf16 v[50:53], v[154:157], v[184:187], 0
	v_mfma_f32_16x16x32_bf16 v[50:53], v[158:161], v[188:191], v[50:53]
	v_mfma_f32_16x16x32_bf16 v[38:41], v[146:149], v[198:201], 0
	v_mfma_f32_16x16x32_bf16 v[38:41], v[150:153], v[214:217], v[38:41]
	v_mfma_f32_16x16x32_bf16 v[34:37], v[154:157], v[198:201], 0
	v_mfma_f32_16x16x32_bf16 v[34:37], v[158:161], v[214:217], v[34:37]
	v_mfma_f32_16x16x32_bf16 v[22:25], v[146:149], v[218:221], 0
	v_mfma_f32_16x16x32_bf16 v[22:25], v[150:153], v[222:225], v[22:25]
	v_mfma_f32_16x16x32_bf16 v[18:21], v[154:157], v[218:221], 0
	v_mfma_f32_16x16x32_bf16 v[18:21], v[158:161], v[222:225], v[18:21]
	v_mfma_f32_16x16x32_bf16 v[6:9], v[146:149], v[226:229], 0
	v_mfma_f32_16x16x32_bf16 v[6:9], v[150:153], v[230:233], v[6:9]
	v_mfma_f32_16x16x32_bf16 v[2:5], v[154:157], v[226:229], 0
	v_mfma_f32_16x16x32_bf16 v[2:5], v[158:161], v[230:233], v[2:5]
	s_barrier
	s_add_i32 s20, 0, 0x18000
	s_add_i32 s21, 0, 0x1c000
	v_add_u32_e32 v142, s20, v193
	v_add_u32_e32 v158, s21, v193
	ds_read_b128 v[130:133], v142
	ds_read_b128 v[134:137], v142 offset:1024
	ds_read_b128 v[138:141], v142 offset:2048
	ds_read_b128 v[142:145], v142 offset:3072
	ds_read_b128 v[146:149], v158
	ds_read_b128 v[150:153], v158 offset:1024
	ds_read_b128 v[154:157], v158 offset:2048
	ds_read_b128 v[158:161], v158 offset:3072
	ds_read_b128 v[184:187], v196 offset:32768
	ds_read_b128 v[188:191], v196 offset:33792
	ds_read_b128 v[198:201], v196 offset:34816
	ds_read_b128 v[214:217], v196 offset:35840
	ds_read_b128 v[218:221], v196 offset:36864
	ds_read_b128 v[222:225], v196 offset:37888
	ds_read_b128 v[226:229], v196 offset:38912
	ds_read_b128 v[230:233], v196 offset:39936
	s_mov_b32 m0, s47
	v_lshl_add_u64 v[236:237], v[234:235], 0, s[28:29]
	global_load_lds_dwordx4 v[236:237], off
	v_lshl_add_u64 v[236:237], v[234:235], 0, s[82:83]
	s_mov_b32 m0, s88
	s_nop 0
	global_load_lds_dwordx4 v[236:237], off
	s_waitcnt vmcnt(8) lgkmcnt(0)
	s_barrier
	v_mfma_f32_16x16x32_bf16 v[126:129], v[130:133], v[184:187], v[126:129]
	v_mfma_f32_16x16x32_bf16 v[126:129], v[134:137], v[188:191], v[126:129]
	v_mfma_f32_16x16x32_bf16 v[122:125], v[138:141], v[184:187], v[122:125]
	v_mfma_f32_16x16x32_bf16 v[122:125], v[142:145], v[188:191], v[122:125]
	v_mfma_f32_16x16x32_bf16 v[110:113], v[130:133], v[198:201], v[110:113]
	v_mfma_f32_16x16x32_bf16 v[110:113], v[134:137], v[214:217], v[110:113]
	v_mfma_f32_16x16x32_bf16 v[106:109], v[138:141], v[198:201], v[106:109]
	v_mfma_f32_16x16x32_bf16 v[106:109], v[142:145], v[214:217], v[106:109]
	v_mfma_f32_16x16x32_bf16 v[94:97], v[130:133], v[218:221], v[94:97]
	v_mfma_f32_16x16x32_bf16 v[94:97], v[134:137], v[222:225], v[94:97]
	v_mfma_f32_16x16x32_bf16 v[90:93], v[138:141], v[218:221], v[90:93]
	v_mfma_f32_16x16x32_bf16 v[90:93], v[142:145], v[222:225], v[90:93]
	v_mfma_f32_16x16x32_bf16 v[78:81], v[130:133], v[226:229], v[78:81]
	v_mfma_f32_16x16x32_bf16 v[78:81], v[134:137], v[230:233], v[78:81]
	v_mfma_f32_16x16x32_bf16 v[74:77], v[138:141], v[226:229], v[74:77]
	v_mfma_f32_16x16x32_bf16 v[74:77], v[142:145], v[230:233], v[74:77]
	v_mfma_f32_16x16x32_bf16 v[118:121], v[146:149], v[184:187], v[118:121]
	v_mfma_f32_16x16x32_bf16 v[118:121], v[150:153], v[188:191], v[118:121]
	v_mfma_f32_16x16x32_bf16 v[114:117], v[154:157], v[184:187], v[114:117]
	v_mfma_f32_16x16x32_bf16 v[114:117], v[158:161], v[188:191], v[114:117]
	v_mfma_f32_16x16x32_bf16 v[102:105], v[146:149], v[198:201], v[102:105]
	v_mfma_f32_16x16x32_bf16 v[102:105], v[150:153], v[214:217], v[102:105]
	v_mfma_f32_16x16x32_bf16 v[98:101], v[154:157], v[198:201], v[98:101]
	v_mfma_f32_16x16x32_bf16 v[98:101], v[158:161], v[214:217], v[98:101]
	v_mfma_f32_16x16x32_bf16 v[86:89], v[146:149], v[218:221], v[86:89]
	v_mfma_f32_16x16x32_bf16 v[86:89], v[150:153], v[222:225], v[86:89]
	v_mfma_f32_16x16x32_bf16 v[82:85], v[154:157], v[218:221], v[82:85]
	v_mfma_f32_16x16x32_bf16 v[82:85], v[158:161], v[222:225], v[82:85]
	v_mfma_f32_16x16x32_bf16 v[70:73], v[146:149], v[226:229], v[70:73]
	v_mfma_f32_16x16x32_bf16 v[70:73], v[150:153], v[230:233], v[70:73]
	v_mfma_f32_16x16x32_bf16 v[66:69], v[154:157], v[226:229], v[66:69]
	v_mfma_f32_16x16x32_bf16 v[66:69], v[158:161], v[230:233], v[66:69]
	s_barrier
	ds_read_b128 v[184:187], v196 offset:49152
	ds_read_b128 v[188:191], v196 offset:50176
	ds_read_b128 v[198:201], v196 offset:51200
	ds_read_b128 v[214:217], v196 offset:52224
	ds_read_b128 v[218:221], v196 offset:53248
	ds_read_b128 v[222:225], v196 offset:54272
	ds_read_b128 v[226:229], v196 offset:55296
	ds_read_b128 v[230:233], v196 offset:56320
	s_add_i32 s20, s20, s14
	s_mov_b32 m0, s20
	v_lshl_add_u64 v[236:237], v[202:203], 0, s[34:35]
	global_load_lds_dwordx4 v[236:237], off
	v_lshl_add_u64 v[236:237], v[202:203], 0, s[38:39]
	s_add_i32 m0, s20, 0x2000
	s_add_i32 s20, s21, s14
	global_load_lds_dwordx4 v[236:237], off
	v_lshl_add_u64 v[236:237], v[202:203], 0, s[44:45]
	s_mov_b32 m0, s20
	v_lshl_add_u64 v[202:203], v[202:203], 0, s[10:11]
	global_load_lds_dwordx4 v[236:237], off
	s_add_i32 m0, s20, 0x2000
	s_nop 0
	global_load_lds_dwordx4 v[202:203], off
	v_lshl_add_u64 v[202:203], v[234:235], 0, s[34:35]
	s_mov_b32 m0, s89
	s_nop 0
	global_load_lds_dwordx4 v[202:203], off
	v_lshl_add_u64 v[202:203], v[234:235], 0, s[38:39]
	s_mov_b32 m0, s90
	s_nop 0
	global_load_lds_dwordx4 v[202:203], off
	s_waitcnt vmcnt(8) lgkmcnt(0)
	s_barrier
	v_mfma_f32_16x16x32_bf16 v[62:65], v[130:133], v[184:187], v[62:65]
	v_mfma_f32_16x16x32_bf16 v[62:65], v[134:137], v[188:191], v[62:65]
	v_mfma_f32_16x16x32_bf16 v[58:61], v[138:141], v[184:187], v[58:61]
	v_mfma_f32_16x16x32_bf16 v[58:61], v[142:145], v[188:191], v[58:61]
	v_mfma_f32_16x16x32_bf16 v[46:49], v[130:133], v[198:201], v[46:49]
	v_mfma_f32_16x16x32_bf16 v[46:49], v[134:137], v[214:217], v[46:49]
	v_mfma_f32_16x16x32_bf16 v[42:45], v[138:141], v[198:201], v[42:45]
	v_mfma_f32_16x16x32_bf16 v[42:45], v[142:145], v[214:217], v[42:45]
	v_mfma_f32_16x16x32_bf16 v[30:33], v[130:133], v[218:221], v[30:33]
	v_mfma_f32_16x16x32_bf16 v[30:33], v[134:137], v[222:225], v[30:33]
	v_mfma_f32_16x16x32_bf16 v[26:29], v[138:141], v[218:221], v[26:29]
	v_mfma_f32_16x16x32_bf16 v[26:29], v[142:145], v[222:225], v[26:29]
	v_mfma_f32_16x16x32_bf16 v[14:17], v[130:133], v[226:229], v[14:17]
	v_mfma_f32_16x16x32_bf16 v[14:17], v[134:137], v[230:233], v[14:17]
	v_mfma_f32_16x16x32_bf16 v[10:13], v[138:141], v[226:229], v[10:13]
	v_mfma_f32_16x16x32_bf16 v[10:13], v[142:145], v[230:233], v[10:13]
	s_add_i32 vcc_hi, vcc_hi, 2
	s_add_u32 s76, s76, 0x100
	s_addc_u32 s77, s77, 0
	s_add_u32 s87, s87, 0x100
	s_addc_u32 vcc_lo, vcc_lo, 0
	v_mfma_f32_16x16x32_bf16 v[54:57], v[146:149], v[184:187], v[54:57]
	v_mfma_f32_16x16x32_bf16 v[54:57], v[150:153], v[188:191], v[54:57]
	v_mfma_f32_16x16x32_bf16 v[50:53], v[154:157], v[184:187], v[50:53]
	v_mfma_f32_16x16x32_bf16 v[50:53], v[158:161], v[188:191], v[50:53]
	v_mfma_f32_16x16x32_bf16 v[38:41], v[146:149], v[198:201], v[38:41]
	v_mfma_f32_16x16x32_bf16 v[38:41], v[150:153], v[214:217], v[38:41]
	v_mfma_f32_16x16x32_bf16 v[34:37], v[154:157], v[198:201], v[34:37]
	v_mfma_f32_16x16x32_bf16 v[34:37], v[158:161], v[214:217], v[34:37]
	v_mfma_f32_16x16x32_bf16 v[22:25], v[146:149], v[218:221], v[22:25]
	v_mfma_f32_16x16x32_bf16 v[22:25], v[150:153], v[222:225], v[22:25]
	v_mfma_f32_16x16x32_bf16 v[18:21], v[154:157], v[218:221], v[18:21]
	v_mfma_f32_16x16x32_bf16 v[18:21], v[158:161], v[222:225], v[18:21]
	v_mfma_f32_16x16x32_bf16 v[6:9], v[146:149], v[226:229], v[6:9]
	v_mfma_f32_16x16x32_bf16 v[6:9], v[150:153], v[230:233], v[6:9]
	v_mfma_f32_16x16x32_bf16 v[2:5], v[154:157], v[226:229], v[2:5]
	v_mfma_f32_16x16x32_bf16 v[2:5], v[158:161], v[230:233], v[2:5]
	s_barrier
	s_branch .LBB0_778
	.p2alignl 6, 3212836864
.LBB0_778:
	s_add_i32 s22, 0, 0x10000
	s_add_i32 s23, 0, 0x14000
	v_add_u32_e32 v142, s22, v193
	v_add_u32_e32 v158, s23, v193
	ds_read_b128 v[130:133], v142
	ds_read_b128 v[134:137], v142 offset:1024
	ds_read_b128 v[138:141], v142 offset:2048
	ds_read_b128 v[142:145], v142 offset:3072
	ds_read_b128 v[146:149], v158
	ds_read_b128 v[150:153], v158 offset:1024
	ds_read_b128 v[154:157], v158 offset:2048
	ds_read_b128 v[158:161], v158 offset:3072
	ds_read_b128 v[184:187], v196
	ds_read_b128 v[188:191], v196 offset:1024
	ds_read_b128 v[198:201], v196 offset:2048
	ds_read_b128 v[214:217], v196 offset:3072
	ds_read_b128 v[218:221], v196 offset:4096
	ds_read_b128 v[222:225], v196 offset:5120
	ds_read_b128 v[226:229], v196 offset:6144
	ds_read_b128 v[230:233], v196 offset:7168
	s_add_u32 s20, s76, 0xfffc0080
	s_addc_u32 s21, s77, -1
	s_cmp_eq_u32 vcc_hi, 12
	s_cselect_b32 s79, s61, s21
	s_cselect_b32 s78, s85, s20
	s_cselect_b32 s21, s59, vcc_lo
	s_cselect_b32 s20, s86, s87
	s_add_i32 m0, s43, 0xc000
	v_lshl_add_u64 v[202:203], s[76:77], 0, v[182:183]
	global_load_lds_dwordx4 v[202:203], off
	v_lshl_add_u64 v[202:203], v[202:203], 0, s[72:73]
	s_add_i32 m0, s43, 0xe000
	s_nop 0
	global_load_lds_dwordx4 v[202:203], off
	s_waitcnt vmcnt(8) lgkmcnt(0)
	s_barrier
	v_mfma_f32_16x16x32_bf16 v[126:129], v[130:133], v[184:187], v[126:129]
	v_mfma_f32_16x16x32_bf16 v[126:129], v[134:137], v[188:191], v[126:129]
	v_mfma_f32_16x16x32_bf16 v[122:125], v[138:141], v[184:187], v[122:125]
	v_mfma_f32_16x16x32_bf16 v[122:125], v[142:145], v[188:191], v[122:125]
	v_mfma_f32_16x16x32_bf16 v[110:113], v[130:133], v[198:201], v[110:113]
	v_mfma_f32_16x16x32_bf16 v[110:113], v[134:137], v[214:217], v[110:113]
	v_mfma_f32_16x16x32_bf16 v[106:109], v[138:141], v[198:201], v[106:109]
	v_mfma_f32_16x16x32_bf16 v[106:109], v[142:145], v[214:217], v[106:109]
	v_mfma_f32_16x16x32_bf16 v[94:97], v[130:133], v[218:221], v[94:97]
	v_mfma_f32_16x16x32_bf16 v[94:97], v[134:137], v[222:225], v[94:97]
	v_mfma_f32_16x16x32_bf16 v[90:93], v[138:141], v[218:221], v[90:93]
	v_mfma_f32_16x16x32_bf16 v[90:93], v[142:145], v[222:225], v[90:93]
	v_mfma_f32_16x16x32_bf16 v[78:81], v[130:133], v[226:229], v[78:81]
	v_mfma_f32_16x16x32_bf16 v[78:81], v[134:137], v[230:233], v[78:81]
	v_mfma_f32_16x16x32_bf16 v[74:77], v[138:141], v[226:229], v[74:77]
	v_mfma_f32_16x16x32_bf16 v[74:77], v[142:145], v[230:233], v[74:77]
	v_mfma_f32_16x16x32_bf16 v[118:121], v[146:149], v[184:187], v[118:121]
	v_mfma_f32_16x16x32_bf16 v[118:121], v[150:153], v[188:191], v[118:121]
	v_mfma_f32_16x16x32_bf16 v[114:117], v[154:157], v[184:187], v[114:117]
	v_mfma_f32_16x16x32_bf16 v[114:117], v[158:161], v[188:191], v[114:117]
	v_mfma_f32_16x16x32_bf16 v[102:105], v[146:149], v[198:201], v[102:105]
	v_mfma_f32_16x16x32_bf16 v[102:105], v[150:153], v[214:217], v[102:105]
	v_mfma_f32_16x16x32_bf16 v[98:101], v[154:157], v[198:201], v[98:101]
	v_mfma_f32_16x16x32_bf16 v[98:101], v[158:161], v[214:217], v[98:101]
	v_mfma_f32_16x16x32_bf16 v[86:89], v[146:149], v[218:221], v[86:89]
	v_mfma_f32_16x16x32_bf16 v[86:89], v[150:153], v[222:225], v[86:89]
	v_mfma_f32_16x16x32_bf16 v[82:85], v[154:157], v[218:221], v[82:85]
	v_mfma_f32_16x16x32_bf16 v[82:85], v[158:161], v[222:225], v[82:85]
	v_mfma_f32_16x16x32_bf16 v[70:73], v[146:149], v[226:229], v[70:73]
	v_mfma_f32_16x16x32_bf16 v[70:73], v[150:153], v[230:233], v[70:73]
	v_mfma_f32_16x16x32_bf16 v[66:69], v[154:157], v[226:229], v[66:69]
	v_mfma_f32_16x16x32_bf16 v[66:69], v[158:161], v[230:233], v[66:69]
	s_barrier
	ds_read_b128 v[184:187], v196 offset:16384
	ds_read_b128 v[188:191], v196 offset:17408
	ds_read_b128 v[198:201], v196 offset:18432
	ds_read_b128 v[214:217], v196 offset:19456
	ds_read_b128 v[218:221], v196 offset:20480
	ds_read_b128 v[222:225], v196 offset:21504
	ds_read_b128 v[226:229], v196 offset:22528
	ds_read_b128 v[230:233], v196 offset:23552
	v_lshl_add_u64 v[202:203], s[20:21], 0, v[0:1]
	s_add_i32 s20, s22, s14
	s_mov_b32 m0, s20
	s_nop 0
	s_nop 0
	global_load_lds_dwordx4 v[202:203], off
	v_lshl_add_u64 v[234:235], v[202:203], 0, s[72:73]
	s_add_i32 m0, s20, 0x2000
	s_add_i32 s20, s23, s14
	global_load_lds_dwordx4 v[234:235], off
	v_lshl_add_u64 v[234:235], v[202:203], 0, s[28:29]
	s_mov_b32 m0, s20
	s_nop 0
	global_load_lds_dwordx4 v[234:235], off
	v_lshl_add_u64 v[234:235], v[202:203], 0, s[82:83]
	s_add_i32 m0, s20, 0x2000
	s_nop 0
	global_load_lds_dwordx4 v[234:235], off
	v_lshl_add_u64 v[234:235], s[78:79], 0, v[162:163]
	s_mov_b32 m0, s43
	v_lshl_add_u64 v[236:237], v[234:235], 0, s[72:73]
	global_load_lds_dwordx4 v[234:235], off
	s_mov_b32 m0, s46
	s_nop 0
	global_load_lds_dwordx4 v[236:237], off
	s_waitcnt vmcnt(8) lgkmcnt(0)
	s_barrier
	v_mfma_f32_16x16x32_bf16 v[62:65], v[130:133], v[184:187], v[62:65]
	v_mfma_f32_16x16x32_bf16 v[62:65], v[134:137], v[188:191], v[62:65]
	v_mfma_f32_16x16x32_bf16 v[58:61], v[138:141], v[184:187], v[58:61]
	v_mfma_f32_16x16x32_bf16 v[58:61], v[142:145], v[188:191], v[58:61]
	v_mfma_f32_16x16x32_bf16 v[46:49], v[130:133], v[198:201], v[46:49]
	v_mfma_f32_16x16x32_bf16 v[46:49], v[134:137], v[214:217], v[46:49]
	v_mfma_f32_16x16x32_bf16 v[42:45], v[138:141], v[198:201], v[42:45]
	v_mfma_f32_16x16x32_bf16 v[42:45], v[142:145], v[214:217], v[42:45]
	v_mfma_f32_16x16x32_bf16 v[30:33], v[130:133], v[218:221], v[30:33]
	v_mfma_f32_16x16x32_bf16 v[30:33], v[134:137], v[222:225], v[30:33]
	v_mfma_f32_16x16x32_bf16 v[26:29], v[138:141], v[218:221], v[26:29]
	v_mfma_f32_16x16x32_bf16 v[26:29], v[142:145], v[222:225], v[26:29]
	v_mfma_f32_16x16x32_bf16 v[14:17], v[130:133], v[226:229], v[14:17]
	v_mfma_f32_16x16x32_bf16 v[14:17], v[134:137], v[230:233], v[14:17]
	v_mfma_f32_16x16x32_bf16 v[10:13], v[138:141], v[226:229], v[10:13]
	v_mfma_f32_16x16x32_bf16 v[10:13], v[142:145], v[230:233], v[10:13]
	v_mfma_f32_16x16x32_bf16 v[54:57], v[146:149], v[184:187], v[54:57]
	v_mfma_f32_16x16x32_bf16 v[54:57], v[150:153], v[188:191], v[54:57]
	v_mfma_f32_16x16x32_bf16 v[50:53], v[154:157], v[184:187], v[50:53]
	v_mfma_f32_16x16x32_bf16 v[50:53], v[158:161], v[188:191], v[50:53]
	v_mfma_f32_16x16x32_bf16 v[38:41], v[146:149], v[198:201], v[38:41]
	v_mfma_f32_16x16x32_bf16 v[38:41], v[150:153], v[214:217], v[38:41]
	v_mfma_f32_16x16x32_bf16 v[34:37], v[154:157], v[198:201], v[34:37]
	v_mfma_f32_16x16x32_bf16 v[34:37], v[158:161], v[214:217], v[34:37]
	v_mfma_f32_16x16x32_bf16 v[22:25], v[146:149], v[218:221], v[22:25]
	v_mfma_f32_16x16x32_bf16 v[22:25], v[150:153], v[222:225], v[22:25]
	v_mfma_f32_16x16x32_bf16 v[18:21], v[154:157], v[218:221], v[18:21]
	v_mfma_f32_16x16x32_bf16 v[18:21], v[158:161], v[222:225], v[18:21]
	v_mfma_f32_16x16x32_bf16 v[6:9], v[146:149], v[226:229], v[6:9]
	v_mfma_f32_16x16x32_bf16 v[6:9], v[150:153], v[230:233], v[6:9]
	v_mfma_f32_16x16x32_bf16 v[2:5], v[154:157], v[226:229], v[2:5]
	v_mfma_f32_16x16x32_bf16 v[2:5], v[158:161], v[230:233], v[2:5]
	s_barrier
	s_add_i32 s20, 0, 0x18000
	s_add_i32 s21, 0, 0x1c000
	v_add_u32_e32 v142, s20, v193
	v_add_u32_e32 v158, s21, v193
	ds_read_b128 v[130:133], v142
	ds_read_b128 v[134:137], v142 offset:1024
	ds_read_b128 v[138:141], v142 offset:2048
	ds_read_b128 v[142:145], v142 offset:3072
	ds_read_b128 v[146:149], v158
	ds_read_b128 v[150:153], v158 offset:1024
	ds_read_b128 v[154:157], v158 offset:2048
	ds_read_b128 v[158:161], v158 offset:3072
	ds_read_b128 v[184:187], v196 offset:32768
	ds_read_b128 v[188:191], v196 offset:33792
	ds_read_b128 v[198:201], v196 offset:34816
	ds_read_b128 v[214:217], v196 offset:35840
	ds_read_b128 v[218:221], v196 offset:36864
	ds_read_b128 v[222:225], v196 offset:37888
	ds_read_b128 v[226:229], v196 offset:38912
	ds_read_b128 v[230:233], v196 offset:39936
	s_mov_b32 m0, s47
	v_lshl_add_u64 v[236:237], v[234:235], 0, s[28:29]
	global_load_lds_dwordx4 v[236:237], off
	v_lshl_add_u64 v[236:237], v[234:235], 0, s[82:83]
	s_mov_b32 m0, s88
	s_nop 0
	global_load_lds_dwordx4 v[236:237], off
	s_waitcnt vmcnt(8) lgkmcnt(0)
	s_barrier
	v_mfma_f32_16x16x32_bf16 v[126:129], v[130:133], v[184:187], v[126:129]
	v_mfma_f32_16x16x32_bf16 v[126:129], v[134:137], v[188:191], v[126:129]
	v_mfma_f32_16x16x32_bf16 v[122:125], v[138:141], v[184:187], v[122:125]
	v_mfma_f32_16x16x32_bf16 v[122:125], v[142:145], v[188:191], v[122:125]
	v_mfma_f32_16x16x32_bf16 v[110:113], v[130:133], v[198:201], v[110:113]
	v_mfma_f32_16x16x32_bf16 v[110:113], v[134:137], v[214:217], v[110:113]
	v_mfma_f32_16x16x32_bf16 v[106:109], v[138:141], v[198:201], v[106:109]
	v_mfma_f32_16x16x32_bf16 v[106:109], v[142:145], v[214:217], v[106:109]
	v_mfma_f32_16x16x32_bf16 v[94:97], v[130:133], v[218:221], v[94:97]
	v_mfma_f32_16x16x32_bf16 v[94:97], v[134:137], v[222:225], v[94:97]
	v_mfma_f32_16x16x32_bf16 v[90:93], v[138:141], v[218:221], v[90:93]
	v_mfma_f32_16x16x32_bf16 v[90:93], v[142:145], v[222:225], v[90:93]
	v_mfma_f32_16x16x32_bf16 v[78:81], v[130:133], v[226:229], v[78:81]
	v_mfma_f32_16x16x32_bf16 v[78:81], v[134:137], v[230:233], v[78:81]
	v_mfma_f32_16x16x32_bf16 v[74:77], v[138:141], v[226:229], v[74:77]
	v_mfma_f32_16x16x32_bf16 v[74:77], v[142:145], v[230:233], v[74:77]
	v_mfma_f32_16x16x32_bf16 v[118:121], v[146:149], v[184:187], v[118:121]
	v_mfma_f32_16x16x32_bf16 v[118:121], v[150:153], v[188:191], v[118:121]
	v_mfma_f32_16x16x32_bf16 v[114:117], v[154:157], v[184:187], v[114:117]
	v_mfma_f32_16x16x32_bf16 v[114:117], v[158:161], v[188:191], v[114:117]
	v_mfma_f32_16x16x32_bf16 v[102:105], v[146:149], v[198:201], v[102:105]
	v_mfma_f32_16x16x32_bf16 v[102:105], v[150:153], v[214:217], v[102:105]
	v_mfma_f32_16x16x32_bf16 v[98:101], v[154:157], v[198:201], v[98:101]
	v_mfma_f32_16x16x32_bf16 v[98:101], v[158:161], v[214:217], v[98:101]
	v_mfma_f32_16x16x32_bf16 v[86:89], v[146:149], v[218:221], v[86:89]
	v_mfma_f32_16x16x32_bf16 v[86:89], v[150:153], v[222:225], v[86:89]
	v_mfma_f32_16x16x32_bf16 v[82:85], v[154:157], v[218:221], v[82:85]
	v_mfma_f32_16x16x32_bf16 v[82:85], v[158:161], v[222:225], v[82:85]
	v_mfma_f32_16x16x32_bf16 v[70:73], v[146:149], v[226:229], v[70:73]
	v_mfma_f32_16x16x32_bf16 v[70:73], v[150:153], v[230:233], v[70:73]
	v_mfma_f32_16x16x32_bf16 v[66:69], v[154:157], v[226:229], v[66:69]
	v_mfma_f32_16x16x32_bf16 v[66:69], v[158:161], v[230:233], v[66:69]
	s_barrier
	ds_read_b128 v[184:187], v196 offset:49152
	ds_read_b128 v[188:191], v196 offset:50176
	ds_read_b128 v[198:201], v196 offset:51200
	ds_read_b128 v[214:217], v196 offset:52224
	ds_read_b128 v[218:221], v196 offset:53248
	ds_read_b128 v[222:225], v196 offset:54272
	ds_read_b128 v[226:229], v196 offset:55296
	ds_read_b128 v[230:233], v196 offset:56320
	s_add_i32 s20, s20, s14
	s_mov_b32 m0, s20
	v_lshl_add_u64 v[236:237], v[202:203], 0, s[34:35]
	global_load_lds_dwordx4 v[236:237], off
	v_lshl_add_u64 v[236:237], v[202:203], 0, s[38:39]
	s_add_i32 m0, s20, 0x2000
	s_add_i32 s20, s21, s14
	global_load_lds_dwordx4 v[236:237], off
	v_lshl_add_u64 v[236:237], v[202:203], 0, s[44:45]
	s_mov_b32 m0, s20
	v_lshl_add_u64 v[202:203], v[202:203], 0, s[10:11]
	global_load_lds_dwordx4 v[236:237], off
	s_add_i32 m0, s20, 0x2000
	s_nop 0
	global_load_lds_dwordx4 v[202:203], off
	v_lshl_add_u64 v[202:203], v[234:235], 0, s[34:35]
	s_mov_b32 m0, s89
	s_nop 0
	global_load_lds_dwordx4 v[202:203], off
	v_lshl_add_u64 v[202:203], v[234:235], 0, s[38:39]
	s_mov_b32 m0, s90
	s_nop 0
	global_load_lds_dwordx4 v[202:203], off
	s_waitcnt vmcnt(8) lgkmcnt(0)
	s_barrier
	v_mfma_f32_16x16x32_bf16 v[62:65], v[130:133], v[184:187], v[62:65]
	v_mfma_f32_16x16x32_bf16 v[62:65], v[134:137], v[188:191], v[62:65]
	v_mfma_f32_16x16x32_bf16 v[58:61], v[138:141], v[184:187], v[58:61]
	v_mfma_f32_16x16x32_bf16 v[58:61], v[142:145], v[188:191], v[58:61]
	v_mfma_f32_16x16x32_bf16 v[46:49], v[130:133], v[198:201], v[46:49]
	v_mfma_f32_16x16x32_bf16 v[46:49], v[134:137], v[214:217], v[46:49]
	v_mfma_f32_16x16x32_bf16 v[42:45], v[138:141], v[198:201], v[42:45]
	v_mfma_f32_16x16x32_bf16 v[42:45], v[142:145], v[214:217], v[42:45]
	v_mfma_f32_16x16x32_bf16 v[30:33], v[130:133], v[218:221], v[30:33]
	v_mfma_f32_16x16x32_bf16 v[30:33], v[134:137], v[222:225], v[30:33]
	v_mfma_f32_16x16x32_bf16 v[26:29], v[138:141], v[218:221], v[26:29]
	v_mfma_f32_16x16x32_bf16 v[26:29], v[142:145], v[222:225], v[26:29]
	v_mfma_f32_16x16x32_bf16 v[14:17], v[130:133], v[226:229], v[14:17]
	v_mfma_f32_16x16x32_bf16 v[14:17], v[134:137], v[230:233], v[14:17]
	v_mfma_f32_16x16x32_bf16 v[10:13], v[138:141], v[226:229], v[10:13]
	v_mfma_f32_16x16x32_bf16 v[10:13], v[142:145], v[230:233], v[10:13]
	s_add_i32 vcc_hi, vcc_hi, 2
	s_add_u32 s76, s76, 0x100
	s_addc_u32 s77, s77, 0
	s_add_u32 s87, s87, 0x100
	s_addc_u32 vcc_lo, vcc_lo, 0
	v_mfma_f32_16x16x32_bf16 v[54:57], v[146:149], v[184:187], v[54:57]
	v_mfma_f32_16x16x32_bf16 v[54:57], v[150:153], v[188:191], v[54:57]
	v_mfma_f32_16x16x32_bf16 v[50:53], v[154:157], v[184:187], v[50:53]
	v_mfma_f32_16x16x32_bf16 v[50:53], v[158:161], v[188:191], v[50:53]
	v_mfma_f32_16x16x32_bf16 v[38:41], v[146:149], v[198:201], v[38:41]
	v_mfma_f32_16x16x32_bf16 v[38:41], v[150:153], v[214:217], v[38:41]
	v_mfma_f32_16x16x32_bf16 v[34:37], v[154:157], v[198:201], v[34:37]
	v_mfma_f32_16x16x32_bf16 v[34:37], v[158:161], v[214:217], v[34:37]
	v_mfma_f32_16x16x32_bf16 v[22:25], v[146:149], v[218:221], v[22:25]
	v_mfma_f32_16x16x32_bf16 v[22:25], v[150:153], v[222:225], v[22:25]
	v_mfma_f32_16x16x32_bf16 v[18:21], v[154:157], v[218:221], v[18:21]
	v_mfma_f32_16x16x32_bf16 v[18:21], v[158:161], v[222:225], v[18:21]
	v_mfma_f32_16x16x32_bf16 v[6:9], v[146:149], v[226:229], v[6:9]
	v_mfma_f32_16x16x32_bf16 v[6:9], v[150:153], v[230:233], v[6:9]
	v_mfma_f32_16x16x32_bf16 v[2:5], v[154:157], v[226:229], v[2:5]
	v_mfma_f32_16x16x32_bf16 v[2:5], v[158:161], v[230:233], v[2:5]
	s_barrier
	s_cmp_gt_u32 vcc_hi, 13
	s_cbranch_scc0 .LBB0_778
	s_setprio 0
	s_and_b64 vcc, exec, s[50:51]
	s_cbranch_vccz .LBB0_781
	s_barrier

.Lmid1_850:
	s_add_i32 vcc_lo, 0, 0x10000
	s_add_i32 vcc_hi, 0, 0x14000
	s_add_u32 s20, s56, 0xfffc0080
	s_addc_u32 s21, s57, -1
	s_cmp_eq_u32 s91, 12
	s_cselect_b32 s59, s76, s21
	s_cselect_b32 s58, s77, s20
	s_cselect_b32 s21, s69, s87
	s_cselect_b32 s20, s79, s86
	s_add_i32 m0, s15, 0xc000
	v_lshl_add_u64 v[142:143], s[56:57], 0, v[136:137]
	global_load_lds_dwordx4 v[142:143], off
	v_lshl_add_u64 v[142:143], v[142:143], 0, s[72:73]
	s_add_i32 m0, s15, 0xe000
	s_nop 0
	global_load_lds_dwordx4 v[142:143], off
	s_waitcnt vmcnt(8) lgkmcnt(0)
	s_barrier
	v_mfma_f32_16x16x32_bf16 v[126:129], v[138:141], v[198:201], 0
	v_mfma_f32_16x16x32_bf16 v[126:129], v[146:149], v[214:217], v[126:129]
	v_mfma_f32_16x16x32_bf16 v[122:125], v[150:153], v[198:201], 0
	v_mfma_f32_16x16x32_bf16 v[122:125], v[158:161], v[214:217], v[122:125]
	v_mfma_f32_16x16x32_bf16 v[110:113], v[138:141], v[218:221], 0
	v_mfma_f32_16x16x32_bf16 v[110:113], v[146:149], v[222:225], v[110:113]
	v_mfma_f32_16x16x32_bf16 v[106:109], v[150:153], v[218:221], 0
	v_mfma_f32_16x16x32_bf16 v[106:109], v[158:161], v[222:225], v[106:109]
	v_mfma_f32_16x16x32_bf16 v[94:97], v[138:141], v[226:229], 0
	v_mfma_f32_16x16x32_bf16 v[94:97], v[146:149], v[230:233], v[94:97]
	v_mfma_f32_16x16x32_bf16 v[90:93], v[150:153], v[226:229], 0
	v_mfma_f32_16x16x32_bf16 v[90:93], v[158:161], v[230:233], v[90:93]
	v_mfma_f32_16x16x32_bf16 v[78:81], v[138:141], v[234:237], 0
	v_mfma_f32_16x16x32_bf16 v[78:81], v[146:149], v[238:241], v[78:81]
	v_mfma_f32_16x16x32_bf16 v[74:77], v[150:153], v[234:237], 0
	v_mfma_f32_16x16x32_bf16 v[74:77], v[158:161], v[238:241], v[74:77]
	v_mfma_f32_16x16x32_bf16 v[118:121], v[182:185], v[198:201], 0
	v_mfma_f32_16x16x32_bf16 v[118:121], v[186:189], v[214:217], v[118:121]
	v_mfma_f32_16x16x32_bf16 v[114:117], v[190:193], v[198:201], 0
	v_mfma_f32_16x16x32_bf16 v[114:117], v[194:197], v[214:217], v[114:117]
	v_mfma_f32_16x16x32_bf16 v[102:105], v[182:185], v[218:221], 0
	v_mfma_f32_16x16x32_bf16 v[102:105], v[186:189], v[222:225], v[102:105]
	v_mfma_f32_16x16x32_bf16 v[98:101], v[190:193], v[218:221], 0
	v_mfma_f32_16x16x32_bf16 v[98:101], v[194:197], v[222:225], v[98:101]
	v_mfma_f32_16x16x32_bf16 v[86:89], v[182:185], v[226:229], 0
	v_mfma_f32_16x16x32_bf16 v[86:89], v[186:189], v[230:233], v[86:89]
	v_mfma_f32_16x16x32_bf16 v[82:85], v[190:193], v[226:229], 0
	v_mfma_f32_16x16x32_bf16 v[82:85], v[194:197], v[230:233], v[82:85]
	v_mfma_f32_16x16x32_bf16 v[70:73], v[182:185], v[234:237], 0
	v_mfma_f32_16x16x32_bf16 v[70:73], v[186:189], v[238:241], v[70:73]
	v_mfma_f32_16x16x32_bf16 v[66:69], v[190:193], v[234:237], 0
	v_mfma_f32_16x16x32_bf16 v[66:69], v[194:197], v[238:241], v[66:69]
	s_barrier
	ds_read_b128 v[198:201], v157 offset:16384
	ds_read_b128 v[214:217], v157 offset:17408
	ds_read_b128 v[218:221], v157 offset:18432
	ds_read_b128 v[222:225], v157 offset:19456
	ds_read_b128 v[226:229], v157 offset:20480
	ds_read_b128 v[230:233], v157 offset:21504
	ds_read_b128 v[234:237], v157 offset:22528
	ds_read_b128 v[238:241], v157 offset:23552
	v_lshl_add_u64 v[142:143], s[20:21], 0, v[130:131]
	s_add_i32 s20, vcc_lo, s14
	s_mov_b32 m0, s20
	s_nop 0
	s_nop 0
	global_load_lds_dwordx4 v[142:143], off
	v_lshl_add_u64 v[162:163], v[142:143], 0, s[72:73]
	s_add_i32 m0, s20, 0x2000
	s_add_i32 s20, vcc_hi, s14
	global_load_lds_dwordx4 v[162:163], off
	v_lshl_add_u64 v[162:163], v[142:143], 0, s[28:29]
	s_mov_b32 m0, s20
	s_nop 0
	global_load_lds_dwordx4 v[162:163], off
	v_lshl_add_u64 v[162:163], v[142:143], 0, s[82:83]
	s_add_i32 m0, s20, 0x2000
	s_nop 0
	global_load_lds_dwordx4 v[162:163], off
	v_lshl_add_u64 v[162:163], s[58:59], 0, v[132:133]
	s_mov_b32 m0, s15
	v_lshl_add_u64 v[202:203], v[162:163], 0, s[72:73]
	global_load_lds_dwordx4 v[162:163], off
	s_mov_b32 m0, s42
	s_nop 0
	global_load_lds_dwordx4 v[202:203], off
	s_waitcnt vmcnt(8) lgkmcnt(0)
	s_barrier
	v_mfma_f32_16x16x32_bf16 v[62:65], v[138:141], v[198:201], 0
	v_mfma_f32_16x16x32_bf16 v[62:65], v[146:149], v[214:217], v[62:65]
	v_mfma_f32_16x16x32_bf16 v[58:61], v[150:153], v[198:201], 0
	v_mfma_f32_16x16x32_bf16 v[58:61], v[158:161], v[214:217], v[58:61]
	v_mfma_f32_16x16x32_bf16 v[46:49], v[138:141], v[218:221], 0
	v_mfma_f32_16x16x32_bf16 v[46:49], v[146:149], v[222:225], v[46:49]
	v_mfma_f32_16x16x32_bf16 v[42:45], v[150:153], v[218:221], 0
	v_mfma_f32_16x16x32_bf16 v[42:45], v[158:161], v[222:225], v[42:45]
	v_mfma_f32_16x16x32_bf16 v[30:33], v[138:141], v[226:229], 0
	v_mfma_f32_16x16x32_bf16 v[30:33], v[146:149], v[230:233], v[30:33]
	v_mfma_f32_16x16x32_bf16 v[26:29], v[150:153], v[226:229], 0
	v_mfma_f32_16x16x32_bf16 v[26:29], v[158:161], v[230:233], v[26:29]
	v_mfma_f32_16x16x32_bf16 v[14:17], v[138:141], v[234:237], 0
	v_mfma_f32_16x16x32_bf16 v[14:17], v[146:149], v[238:241], v[14:17]
	v_mfma_f32_16x16x32_bf16 v[10:13], v[150:153], v[234:237], 0
	v_mfma_f32_16x16x32_bf16 v[10:13], v[158:161], v[238:241], v[10:13]
	v_mfma_f32_16x16x32_bf16 v[54:57], v[182:185], v[198:201], 0
	v_mfma_f32_16x16x32_bf16 v[54:57], v[186:189], v[214:217], v[54:57]
	v_mfma_f32_16x16x32_bf16 v[50:53], v[190:193], v[198:201], 0
	v_mfma_f32_16x16x32_bf16 v[50:53], v[194:197], v[214:217], v[50:53]
	v_mfma_f32_16x16x32_bf16 v[38:41], v[182:185], v[218:221], 0
	v_mfma_f32_16x16x32_bf16 v[38:41], v[186:189], v[222:225], v[38:41]
	v_mfma_f32_16x16x32_bf16 v[34:37], v[190:193], v[218:221], 0
	v_mfma_f32_16x16x32_bf16 v[34:37], v[194:197], v[222:225], v[34:37]
	v_mfma_f32_16x16x32_bf16 v[22:25], v[182:185], v[226:229], 0
	v_mfma_f32_16x16x32_bf16 v[22:25], v[186:189], v[230:233], v[22:25]
	v_mfma_f32_16x16x32_bf16 v[18:21], v[190:193], v[226:229], 0
	v_mfma_f32_16x16x32_bf16 v[18:21], v[194:197], v[230:233], v[18:21]
	v_mfma_f32_16x16x32_bf16 v[6:9], v[182:185], v[234:237], 0
	v_mfma_f32_16x16x32_bf16 v[6:9], v[186:189], v[238:241], v[6:9]
	v_mfma_f32_16x16x32_bf16 v[2:5], v[190:193], v[234:237], 0
	v_mfma_f32_16x16x32_bf16 v[2:5], v[194:197], v[238:241], v[2:5]
	s_barrier
	s_add_i32 s20, 0, 0x18000
	v_add_u32_e32 v0, s20, v145
	s_add_i32 s21, 0, 0x1c000
	ds_read_b128 v[138:141], v0
	ds_read_b128 v[146:149], v0 offset:1024
	ds_read_b128 v[150:153], v0 offset:2048
	ds_read_b128 v[158:161], v0 offset:3072
	v_add_u32_e32 v0, s21, v145
	ds_read_b128 v[182:185], v0
	ds_read_b128 v[186:189], v0 offset:1024
	ds_read_b128 v[190:193], v0 offset:2048
	ds_read_b128 v[194:197], v0 offset:3072
	ds_read_b128 v[198:201], v157 offset:32768
	ds_read_b128 v[214:217], v157 offset:33792
	ds_read_b128 v[218:221], v157 offset:34816
	ds_read_b128 v[222:225], v157 offset:35840
	ds_read_b128 v[226:229], v157 offset:36864
	ds_read_b128 v[230:233], v157 offset:37888
	ds_read_b128 v[234:237], v157 offset:38912
	ds_read_b128 v[238:241], v157 offset:39936
	s_mov_b32 m0, s43
	v_lshl_add_u64 v[202:203], v[162:163], 0, s[28:29]
	global_load_lds_dwordx4 v[202:203], off
	v_lshl_add_u64 v[202:203], v[162:163], 0, s[82:83]
	s_mov_b32 m0, s46
	s_nop 0
	global_load_lds_dwordx4 v[202:203], off
	s_waitcnt vmcnt(8) lgkmcnt(0)
	s_barrier
	v_mfma_f32_16x16x32_bf16 v[126:129], v[138:141], v[198:201], v[126:129]
	v_mfma_f32_16x16x32_bf16 v[126:129], v[146:149], v[214:217], v[126:129]
	v_mfma_f32_16x16x32_bf16 v[122:125], v[150:153], v[198:201], v[122:125]
	v_mfma_f32_16x16x32_bf16 v[122:125], v[158:161], v[214:217], v[122:125]
	v_mfma_f32_16x16x32_bf16 v[110:113], v[138:141], v[218:221], v[110:113]
	v_mfma_f32_16x16x32_bf16 v[110:113], v[146:149], v[222:225], v[110:113]
	v_mfma_f32_16x16x32_bf16 v[106:109], v[150:153], v[218:221], v[106:109]
	v_mfma_f32_16x16x32_bf16 v[106:109], v[158:161], v[222:225], v[106:109]
	v_mfma_f32_16x16x32_bf16 v[94:97], v[138:141], v[226:229], v[94:97]
	v_mfma_f32_16x16x32_bf16 v[94:97], v[146:149], v[230:233], v[94:97]
	v_mfma_f32_16x16x32_bf16 v[90:93], v[150:153], v[226:229], v[90:93]
	v_mfma_f32_16x16x32_bf16 v[90:93], v[158:161], v[230:233], v[90:93]
	v_mfma_f32_16x16x32_bf16 v[78:81], v[138:141], v[234:237], v[78:81]
	v_mfma_f32_16x16x32_bf16 v[78:81], v[146:149], v[238:241], v[78:81]
	v_mfma_f32_16x16x32_bf16 v[74:77], v[150:153], v[234:237], v[74:77]
	v_mfma_f32_16x16x32_bf16 v[74:77], v[158:161], v[238:241], v[74:77]
	v_mfma_f32_16x16x32_bf16 v[118:121], v[182:185], v[198:201], v[118:121]
	v_mfma_f32_16x16x32_bf16 v[118:121], v[186:189], v[214:217], v[118:121]
	v_mfma_f32_16x16x32_bf16 v[114:117], v[190:193], v[198:201], v[114:117]
	v_mfma_f32_16x16x32_bf16 v[114:117], v[194:197], v[214:217], v[114:117]
	v_mfma_f32_16x16x32_bf16 v[102:105], v[182:185], v[218:221], v[102:105]
	v_mfma_f32_16x16x32_bf16 v[102:105], v[186:189], v[222:225], v[102:105]
	v_mfma_f32_16x16x32_bf16 v[98:101], v[190:193], v[218:221], v[98:101]
	v_mfma_f32_16x16x32_bf16 v[98:101], v[194:197], v[222:225], v[98:101]
	v_mfma_f32_16x16x32_bf16 v[86:89], v[182:185], v[226:229], v[86:89]
	v_mfma_f32_16x16x32_bf16 v[86:89], v[186:189], v[230:233], v[86:89]
	v_mfma_f32_16x16x32_bf16 v[82:85], v[190:193], v[226:229], v[82:85]
	v_mfma_f32_16x16x32_bf16 v[82:85], v[194:197], v[230:233], v[82:85]
	v_mfma_f32_16x16x32_bf16 v[70:73], v[182:185], v[234:237], v[70:73]
	v_mfma_f32_16x16x32_bf16 v[70:73], v[186:189], v[238:241], v[70:73]
	v_mfma_f32_16x16x32_bf16 v[66:69], v[190:193], v[234:237], v[66:69]
	v_mfma_f32_16x16x32_bf16 v[66:69], v[194:197], v[238:241], v[66:69]
	s_barrier
	ds_read_b128 v[198:201], v157 offset:49152
	ds_read_b128 v[214:217], v157 offset:50176
	ds_read_b128 v[218:221], v157 offset:51200
	ds_read_b128 v[222:225], v157 offset:52224
	ds_read_b128 v[226:229], v157 offset:53248
	ds_read_b128 v[230:233], v157 offset:54272
	ds_read_b128 v[234:237], v157 offset:55296
	ds_read_b128 v[238:241], v157 offset:56320
	s_add_i32 s20, s20, s14
	s_mov_b32 m0, s20
	v_lshl_add_u64 v[202:203], v[142:143], 0, s[34:35]
	global_load_lds_dwordx4 v[202:203], off
	v_lshl_add_u64 v[202:203], v[142:143], 0, s[38:39]
	s_add_i32 m0, s20, 0x2000
	s_add_i32 s20, s21, s14
	global_load_lds_dwordx4 v[202:203], off
	v_lshl_add_u64 v[202:203], v[142:143], 0, s[44:45]
	s_mov_b32 m0, s20
	v_lshl_add_u64 v[142:143], v[142:143], 0, s[10:11]
	global_load_lds_dwordx4 v[202:203], off
	s_add_i32 m0, s20, 0x2000
	s_nop 0
	global_load_lds_dwordx4 v[142:143], off
	v_lshl_add_u64 v[142:143], v[162:163], 0, s[34:35]
	s_mov_b32 m0, s47
	s_nop 0
	global_load_lds_dwordx4 v[142:143], off
	v_lshl_add_u64 v[142:143], v[162:163], 0, s[38:39]
	s_mov_b32 m0, s96
	s_nop 0
	global_load_lds_dwordx4 v[142:143], off
	s_waitcnt vmcnt(8) lgkmcnt(0)
	s_barrier
	v_mfma_f32_16x16x32_bf16 v[62:65], v[138:141], v[198:201], v[62:65]
	v_mfma_f32_16x16x32_bf16 v[62:65], v[146:149], v[214:217], v[62:65]
	v_mfma_f32_16x16x32_bf16 v[58:61], v[150:153], v[198:201], v[58:61]
	v_mfma_f32_16x16x32_bf16 v[58:61], v[158:161], v[214:217], v[58:61]
	v_mfma_f32_16x16x32_bf16 v[46:49], v[138:141], v[218:221], v[46:49]
	v_mfma_f32_16x16x32_bf16 v[46:49], v[146:149], v[222:225], v[46:49]
	v_mfma_f32_16x16x32_bf16 v[42:45], v[150:153], v[218:221], v[42:45]
	v_mfma_f32_16x16x32_bf16 v[42:45], v[158:161], v[222:225], v[42:45]
	v_mfma_f32_16x16x32_bf16 v[30:33], v[138:141], v[226:229], v[30:33]
	v_mfma_f32_16x16x32_bf16 v[30:33], v[146:149], v[230:233], v[30:33]
	v_mfma_f32_16x16x32_bf16 v[26:29], v[150:153], v[226:229], v[26:29]
	v_mfma_f32_16x16x32_bf16 v[26:29], v[158:161], v[230:233], v[26:29]
	v_mfma_f32_16x16x32_bf16 v[14:17], v[138:141], v[234:237], v[14:17]
	v_mfma_f32_16x16x32_bf16 v[14:17], v[146:149], v[238:241], v[14:17]
	v_mfma_f32_16x16x32_bf16 v[10:13], v[150:153], v[234:237], v[10:13]
	v_mfma_f32_16x16x32_bf16 v[10:13], v[158:161], v[238:241], v[10:13]
	s_add_i32 s91, s91, 2
	s_add_u32 s56, s56, 0x100
	s_addc_u32 s57, s57, 0
	s_add_u32 s86, s86, 0x100
	s_addc_u32 s87, s87, 0
	v_mfma_f32_16x16x32_bf16 v[54:57], v[182:185], v[198:201], v[54:57]
	v_mfma_f32_16x16x32_bf16 v[54:57], v[186:189], v[214:217], v[54:57]
	v_mfma_f32_16x16x32_bf16 v[50:53], v[190:193], v[198:201], v[50:53]
	v_mfma_f32_16x16x32_bf16 v[50:53], v[194:197], v[214:217], v[50:53]
	v_mfma_f32_16x16x32_bf16 v[38:41], v[182:185], v[218:221], v[38:41]
	v_mfma_f32_16x16x32_bf16 v[38:41], v[186:189], v[222:225], v[38:41]
	v_mfma_f32_16x16x32_bf16 v[34:37], v[190:193], v[218:221], v[34:37]
	v_mfma_f32_16x16x32_bf16 v[34:37], v[194:197], v[222:225], v[34:37]
	v_mfma_f32_16x16x32_bf16 v[22:25], v[182:185], v[226:229], v[22:25]
	v_mfma_f32_16x16x32_bf16 v[22:25], v[186:189], v[230:233], v[22:25]
	v_mfma_f32_16x16x32_bf16 v[18:21], v[190:193], v[226:229], v[18:21]
	v_mfma_f32_16x16x32_bf16 v[18:21], v[194:197], v[230:233], v[18:21]
	v_mfma_f32_16x16x32_bf16 v[6:9], v[182:185], v[234:237], v[6:9]
	v_mfma_f32_16x16x32_bf16 v[6:9], v[186:189], v[238:241], v[6:9]
	v_mfma_f32_16x16x32_bf16 v[2:5], v[190:193], v[234:237], v[2:5]
	v_mfma_f32_16x16x32_bf16 v[2:5], v[194:197], v[238:241], v[2:5]
	s_barrier
	s_branch .LBB0_850
	.p2alignl 6, 3212836864
.LBB0_850:
	s_add_i32 vcc_lo, 0, 0x10000
	v_add_u32_e32 v0, vcc_lo, v145
	s_add_i32 vcc_hi, 0, 0x14000
	ds_read_b128 v[138:141], v0
	ds_read_b128 v[146:149], v0 offset:1024
	ds_read_b128 v[150:153], v0 offset:2048
	ds_read_b128 v[158:161], v0 offset:3072
	v_add_u32_e32 v0, vcc_hi, v145
	ds_read_b128 v[182:185], v0
	ds_read_b128 v[186:189], v0 offset:1024
	ds_read_b128 v[190:193], v0 offset:2048
	ds_read_b128 v[194:197], v0 offset:3072
	ds_read_b128 v[198:201], v157
	ds_read_b128 v[214:217], v157 offset:1024
	ds_read_b128 v[218:221], v157 offset:2048
	ds_read_b128 v[222:225], v157 offset:3072
	ds_read_b128 v[226:229], v157 offset:4096
	ds_read_b128 v[230:233], v157 offset:5120
	ds_read_b128 v[234:237], v157 offset:6144
	ds_read_b128 v[238:241], v157 offset:7168
	s_add_u32 s20, s56, 0xfffc0080
	s_addc_u32 s21, s57, -1
	s_cmp_eq_u32 s91, 12
	s_cselect_b32 s59, s76, s21
	s_cselect_b32 s58, s77, s20
	s_cselect_b32 s21, s69, s87
	s_cselect_b32 s20, s79, s86
	s_add_i32 m0, s15, 0xc000
	v_lshl_add_u64 v[142:143], s[56:57], 0, v[136:137]
	global_load_lds_dwordx4 v[142:143], off
	v_lshl_add_u64 v[142:143], v[142:143], 0, s[72:73]
	s_add_i32 m0, s15, 0xe000
	s_nop 0
	global_load_lds_dwordx4 v[142:143], off
	s_waitcnt vmcnt(8) lgkmcnt(0)
	s_barrier
	v_mfma_f32_16x16x32_bf16 v[126:129], v[138:141], v[198:201], v[126:129]
	v_mfma_f32_16x16x32_bf16 v[126:129], v[146:149], v[214:217], v[126:129]
	v_mfma_f32_16x16x32_bf16 v[122:125], v[150:153], v[198:201], v[122:125]
	v_mfma_f32_16x16x32_bf16 v[122:125], v[158:161], v[214:217], v[122:125]
	v_mfma_f32_16x16x32_bf16 v[110:113], v[138:141], v[218:221], v[110:113]
	v_mfma_f32_16x16x32_bf16 v[110:113], v[146:149], v[222:225], v[110:113]
	v_mfma_f32_16x16x32_bf16 v[106:109], v[150:153], v[218:221], v[106:109]
	v_mfma_f32_16x16x32_bf16 v[106:109], v[158:161], v[222:225], v[106:109]
	v_mfma_f32_16x16x32_bf16 v[94:97], v[138:141], v[226:229], v[94:97]
	v_mfma_f32_16x16x32_bf16 v[94:97], v[146:149], v[230:233], v[94:97]
	v_mfma_f32_16x16x32_bf16 v[90:93], v[150:153], v[226:229], v[90:93]
	v_mfma_f32_16x16x32_bf16 v[90:93], v[158:161], v[230:233], v[90:93]
	v_mfma_f32_16x16x32_bf16 v[78:81], v[138:141], v[234:237], v[78:81]
	v_mfma_f32_16x16x32_bf16 v[78:81], v[146:149], v[238:241], v[78:81]
	v_mfma_f32_16x16x32_bf16 v[74:77], v[150:153], v[234:237], v[74:77]
	v_mfma_f32_16x16x32_bf16 v[74:77], v[158:161], v[238:241], v[74:77]
	v_mfma_f32_16x16x32_bf16 v[118:121], v[182:185], v[198:201], v[118:121]
	v_mfma_f32_16x16x32_bf16 v[118:121], v[186:189], v[214:217], v[118:121]
	v_mfma_f32_16x16x32_bf16 v[114:117], v[190:193], v[198:201], v[114:117]
	v_mfma_f32_16x16x32_bf16 v[114:117], v[194:197], v[214:217], v[114:117]
	v_mfma_f32_16x16x32_bf16 v[102:105], v[182:185], v[218:221], v[102:105]
	v_mfma_f32_16x16x32_bf16 v[102:105], v[186:189], v[222:225], v[102:105]
	v_mfma_f32_16x16x32_bf16 v[98:101], v[190:193], v[218:221], v[98:101]
	v_mfma_f32_16x16x32_bf16 v[98:101], v[194:197], v[222:225], v[98:101]
	v_mfma_f32_16x16x32_bf16 v[86:89], v[182:185], v[226:229], v[86:89]
	v_mfma_f32_16x16x32_bf16 v[86:89], v[186:189], v[230:233], v[86:89]
	v_mfma_f32_16x16x32_bf16 v[82:85], v[190:193], v[226:229], v[82:85]
	v_mfma_f32_16x16x32_bf16 v[82:85], v[194:197], v[230:233], v[82:85]
	v_mfma_f32_16x16x32_bf16 v[70:73], v[182:185], v[234:237], v[70:73]
	v_mfma_f32_16x16x32_bf16 v[70:73], v[186:189], v[238:241], v[70:73]
	v_mfma_f32_16x16x32_bf16 v[66:69], v[190:193], v[234:237], v[66:69]
	v_mfma_f32_16x16x32_bf16 v[66:69], v[194:197], v[238:241], v[66:69]
	s_barrier
	ds_read_b128 v[198:201], v157 offset:16384
	ds_read_b128 v[214:217], v157 offset:17408
	ds_read_b128 v[218:221], v157 offset:18432
	ds_read_b128 v[222:225], v157 offset:19456
	ds_read_b128 v[226:229], v157 offset:20480
	ds_read_b128 v[230:233], v157 offset:21504
	ds_read_b128 v[234:237], v157 offset:22528
	ds_read_b128 v[238:241], v157 offset:23552
	v_lshl_add_u64 v[142:143], s[20:21], 0, v[130:131]
	s_add_i32 s20, vcc_lo, s14
	s_mov_b32 m0, s20
	s_nop 0
	s_nop 0
	global_load_lds_dwordx4 v[142:143], off
	v_lshl_add_u64 v[162:163], v[142:143], 0, s[72:73]
	s_add_i32 m0, s20, 0x2000
	s_add_i32 s20, vcc_hi, s14
	global_load_lds_dwordx4 v[162:163], off
	v_lshl_add_u64 v[162:163], v[142:143], 0, s[28:29]
	s_mov_b32 m0, s20
	s_nop 0
	global_load_lds_dwordx4 v[162:163], off
	v_lshl_add_u64 v[162:163], v[142:143], 0, s[82:83]
	s_add_i32 m0, s20, 0x2000
	s_nop 0
	global_load_lds_dwordx4 v[162:163], off
	v_lshl_add_u64 v[162:163], s[58:59], 0, v[132:133]
	s_mov_b32 m0, s15
	v_lshl_add_u64 v[202:203], v[162:163], 0, s[72:73]
	global_load_lds_dwordx4 v[162:163], off
	s_mov_b32 m0, s42
	s_nop 0
	global_load_lds_dwordx4 v[202:203], off
	s_waitcnt vmcnt(8) lgkmcnt(0)
	s_barrier
	v_mfma_f32_16x16x32_bf16 v[62:65], v[138:141], v[198:201], v[62:65]
	v_mfma_f32_16x16x32_bf16 v[62:65], v[146:149], v[214:217], v[62:65]
	v_mfma_f32_16x16x32_bf16 v[58:61], v[150:153], v[198:201], v[58:61]
	v_mfma_f32_16x16x32_bf16 v[58:61], v[158:161], v[214:217], v[58:61]
	v_mfma_f32_16x16x32_bf16 v[46:49], v[138:141], v[218:221], v[46:49]
	v_mfma_f32_16x16x32_bf16 v[46:49], v[146:149], v[222:225], v[46:49]
	v_mfma_f32_16x16x32_bf16 v[42:45], v[150:153], v[218:221], v[42:45]
	v_mfma_f32_16x16x32_bf16 v[42:45], v[158:161], v[222:225], v[42:45]
	v_mfma_f32_16x16x32_bf16 v[30:33], v[138:141], v[226:229], v[30:33]
	v_mfma_f32_16x16x32_bf16 v[30:33], v[146:149], v[230:233], v[30:33]
	v_mfma_f32_16x16x32_bf16 v[26:29], v[150:153], v[226:229], v[26:29]
	v_mfma_f32_16x16x32_bf16 v[26:29], v[158:161], v[230:233], v[26:29]
	v_mfma_f32_16x16x32_bf16 v[14:17], v[138:141], v[234:237], v[14:17]
	v_mfma_f32_16x16x32_bf16 v[14:17], v[146:149], v[238:241], v[14:17]
	v_mfma_f32_16x16x32_bf16 v[10:13], v[150:153], v[234:237], v[10:13]
	v_mfma_f32_16x16x32_bf16 v[10:13], v[158:161], v[238:241], v[10:13]
	v_mfma_f32_16x16x32_bf16 v[54:57], v[182:185], v[198:201], v[54:57]
	v_mfma_f32_16x16x32_bf16 v[54:57], v[186:189], v[214:217], v[54:57]
	v_mfma_f32_16x16x32_bf16 v[50:53], v[190:193], v[198:201], v[50:53]
	v_mfma_f32_16x16x32_bf16 v[50:53], v[194:197], v[214:217], v[50:53]
	v_mfma_f32_16x16x32_bf16 v[38:41], v[182:185], v[218:221], v[38:41]
	v_mfma_f32_16x16x32_bf16 v[38:41], v[186:189], v[222:225], v[38:41]
	v_mfma_f32_16x16x32_bf16 v[34:37], v[190:193], v[218:221], v[34:37]
	v_mfma_f32_16x16x32_bf16 v[34:37], v[194:197], v[222:225], v[34:37]
	v_mfma_f32_16x16x32_bf16 v[22:25], v[182:185], v[226:229], v[22:25]
	v_mfma_f32_16x16x32_bf16 v[22:25], v[186:189], v[230:233], v[22:25]
	v_mfma_f32_16x16x32_bf16 v[18:21], v[190:193], v[226:229], v[18:21]
	v_mfma_f32_16x16x32_bf16 v[18:21], v[194:197], v[230:233], v[18:21]
	v_mfma_f32_16x16x32_bf16 v[6:9], v[182:185], v[234:237], v[6:9]
	v_mfma_f32_16x16x32_bf16 v[6:9], v[186:189], v[238:241], v[6:9]
	v_mfma_f32_16x16x32_bf16 v[2:5], v[190:193], v[234:237], v[2:5]
	v_mfma_f32_16x16x32_bf16 v[2:5], v[194:197], v[238:241], v[2:5]
	s_barrier
	s_add_i32 s20, 0, 0x18000
	v_add_u32_e32 v0, s20, v145
	s_add_i32 s21, 0, 0x1c000
	ds_read_b128 v[138:141], v0
	ds_read_b128 v[146:149], v0 offset:1024
	ds_read_b128 v[150:153], v0 offset:2048
	ds_read_b128 v[158:161], v0 offset:3072
	v_add_u32_e32 v0, s21, v145
	ds_read_b128 v[182:185], v0
	ds_read_b128 v[186:189], v0 offset:1024
	ds_read_b128 v[190:193], v0 offset:2048
	ds_read_b128 v[194:197], v0 offset:3072
	ds_read_b128 v[198:201], v157 offset:32768
	ds_read_b128 v[214:217], v157 offset:33792
	ds_read_b128 v[218:221], v157 offset:34816
	ds_read_b128 v[222:225], v157 offset:35840
	ds_read_b128 v[226:229], v157 offset:36864
	ds_read_b128 v[230:233], v157 offset:37888
	ds_read_b128 v[234:237], v157 offset:38912
	ds_read_b128 v[238:241], v157 offset:39936
	s_mov_b32 m0, s43
	v_lshl_add_u64 v[202:203], v[162:163], 0, s[28:29]
	global_load_lds_dwordx4 v[202:203], off
	v_lshl_add_u64 v[202:203], v[162:163], 0, s[82:83]
	s_mov_b32 m0, s46
	s_nop 0
	global_load_lds_dwordx4 v[202:203], off
	s_waitcnt vmcnt(8) lgkmcnt(0)
	s_barrier
	v_mfma_f32_16x16x32_bf16 v[126:129], v[138:141], v[198:201], v[126:129]
	v_mfma_f32_16x16x32_bf16 v[126:129], v[146:149], v[214:217], v[126:129]
	v_mfma_f32_16x16x32_bf16 v[122:125], v[150:153], v[198:201], v[122:125]
	v_mfma_f32_16x16x32_bf16 v[122:125], v[158:161], v[214:217], v[122:125]
	v_mfma_f32_16x16x32_bf16 v[110:113], v[138:141], v[218:221], v[110:113]
	v_mfma_f32_16x16x32_bf16 v[110:113], v[146:149], v[222:225], v[110:113]
	v_mfma_f32_16x16x32_bf16 v[106:109], v[150:153], v[218:221], v[106:109]
	v_mfma_f32_16x16x32_bf16 v[106:109], v[158:161], v[222:225], v[106:109]
	v_mfma_f32_16x16x32_bf16 v[94:97], v[138:141], v[226:229], v[94:97]
	v_mfma_f32_16x16x32_bf16 v[94:97], v[146:149], v[230:233], v[94:97]
	v_mfma_f32_16x16x32_bf16 v[90:93], v[150:153], v[226:229], v[90:93]
	v_mfma_f32_16x16x32_bf16 v[90:93], v[158:161], v[230:233], v[90:93]
	v_mfma_f32_16x16x32_bf16 v[78:81], v[138:141], v[234:237], v[78:81]
	v_mfma_f32_16x16x32_bf16 v[78:81], v[146:149], v[238:241], v[78:81]
	v_mfma_f32_16x16x32_bf16 v[74:77], v[150:153], v[234:237], v[74:77]
	v_mfma_f32_16x16x32_bf16 v[74:77], v[158:161], v[238:241], v[74:77]
	v_mfma_f32_16x16x32_bf16 v[118:121], v[182:185], v[198:201], v[118:121]
	v_mfma_f32_16x16x32_bf16 v[118:121], v[186:189], v[214:217], v[118:121]
	v_mfma_f32_16x16x32_bf16 v[114:117], v[190:193], v[198:201], v[114:117]
	v_mfma_f32_16x16x32_bf16 v[114:117], v[194:197], v[214:217], v[114:117]
	v_mfma_f32_16x16x32_bf16 v[102:105], v[182:185], v[218:221], v[102:105]
	v_mfma_f32_16x16x32_bf16 v[102:105], v[186:189], v[222:225], v[102:105]
	v_mfma_f32_16x16x32_bf16 v[98:101], v[190:193], v[218:221], v[98:101]
	v_mfma_f32_16x16x32_bf16 v[98:101], v[194:197], v[222:225], v[98:101]
	v_mfma_f32_16x16x32_bf16 v[86:89], v[182:185], v[226:229], v[86:89]
	v_mfma_f32_16x16x32_bf16 v[86:89], v[186:189], v[230:233], v[86:89]
	v_mfma_f32_16x16x32_bf16 v[82:85], v[190:193], v[226:229], v[82:85]
	v_mfma_f32_16x16x32_bf16 v[82:85], v[194:197], v[230:233], v[82:85]
	v_mfma_f32_16x16x32_bf16 v[70:73], v[182:185], v[234:237], v[70:73]
	v_mfma_f32_16x16x32_bf16 v[70:73], v[186:189], v[238:241], v[70:73]
	v_mfma_f32_16x16x32_bf16 v[66:69], v[190:193], v[234:237], v[66:69]
	v_mfma_f32_16x16x32_bf16 v[66:69], v[194:197], v[238:241], v[66:69]
	s_barrier
	ds_read_b128 v[198:201], v157 offset:49152
	ds_read_b128 v[214:217], v157 offset:50176
	ds_read_b128 v[218:221], v157 offset:51200
	ds_read_b128 v[222:225], v157 offset:52224
	ds_read_b128 v[226:229], v157 offset:53248
	ds_read_b128 v[230:233], v157 offset:54272
	ds_read_b128 v[234:237], v157 offset:55296
	ds_read_b128 v[238:241], v157 offset:56320
	s_add_i32 s20, s20, s14
	s_mov_b32 m0, s20
	v_lshl_add_u64 v[202:203], v[142:143], 0, s[34:35]
	global_load_lds_dwordx4 v[202:203], off
	v_lshl_add_u64 v[202:203], v[142:143], 0, s[38:39]
	s_add_i32 m0, s20, 0x2000
	s_add_i32 s20, s21, s14
	global_load_lds_dwordx4 v[202:203], off
	v_lshl_add_u64 v[202:203], v[142:143], 0, s[44:45]
	s_mov_b32 m0, s20
	v_lshl_add_u64 v[142:143], v[142:143], 0, s[10:11]
	global_load_lds_dwordx4 v[202:203], off
	s_add_i32 m0, s20, 0x2000
	s_nop 0
	global_load_lds_dwordx4 v[142:143], off
	v_lshl_add_u64 v[142:143], v[162:163], 0, s[34:35]
	s_mov_b32 m0, s47
	s_nop 0
	global_load_lds_dwordx4 v[142:143], off
	v_lshl_add_u64 v[142:143], v[162:163], 0, s[38:39]
	s_mov_b32 m0, s96
	s_nop 0
	global_load_lds_dwordx4 v[142:143], off
	s_waitcnt vmcnt(8) lgkmcnt(0)
	s_barrier
	v_mfma_f32_16x16x32_bf16 v[62:65], v[138:141], v[198:201], v[62:65]
	v_mfma_f32_16x16x32_bf16 v[62:65], v[146:149], v[214:217], v[62:65]
	v_mfma_f32_16x16x32_bf16 v[58:61], v[150:153], v[198:201], v[58:61]
	v_mfma_f32_16x16x32_bf16 v[58:61], v[158:161], v[214:217], v[58:61]
	v_mfma_f32_16x16x32_bf16 v[46:49], v[138:141], v[218:221], v[46:49]
	v_mfma_f32_16x16x32_bf16 v[46:49], v[146:149], v[222:225], v[46:49]
	v_mfma_f32_16x16x32_bf16 v[42:45], v[150:153], v[218:221], v[42:45]
	v_mfma_f32_16x16x32_bf16 v[42:45], v[158:161], v[222:225], v[42:45]
	v_mfma_f32_16x16x32_bf16 v[30:33], v[138:141], v[226:229], v[30:33]
	v_mfma_f32_16x16x32_bf16 v[30:33], v[146:149], v[230:233], v[30:33]
	v_mfma_f32_16x16x32_bf16 v[26:29], v[150:153], v[226:229], v[26:29]
	v_mfma_f32_16x16x32_bf16 v[26:29], v[158:161], v[230:233], v[26:29]
	v_mfma_f32_16x16x32_bf16 v[14:17], v[138:141], v[234:237], v[14:17]
	v_mfma_f32_16x16x32_bf16 v[14:17], v[146:149], v[238:241], v[14:17]
	v_mfma_f32_16x16x32_bf16 v[10:13], v[150:153], v[234:237], v[10:13]
	v_mfma_f32_16x16x32_bf16 v[10:13], v[158:161], v[238:241], v[10:13]
	s_add_i32 s91, s91, 2
	s_add_u32 s56, s56, 0x100
	s_addc_u32 s57, s57, 0
	s_add_u32 s86, s86, 0x100
	s_addc_u32 s87, s87, 0
	v_mfma_f32_16x16x32_bf16 v[54:57], v[182:185], v[198:201], v[54:57]
	v_mfma_f32_16x16x32_bf16 v[54:57], v[186:189], v[214:217], v[54:57]
	v_mfma_f32_16x16x32_bf16 v[50:53], v[190:193], v[198:201], v[50:53]
	v_mfma_f32_16x16x32_bf16 v[50:53], v[194:197], v[214:217], v[50:53]
	v_mfma_f32_16x16x32_bf16 v[38:41], v[182:185], v[218:221], v[38:41]
	v_mfma_f32_16x16x32_bf16 v[38:41], v[186:189], v[222:225], v[38:41]
	v_mfma_f32_16x16x32_bf16 v[34:37], v[190:193], v[218:221], v[34:37]
	v_mfma_f32_16x16x32_bf16 v[34:37], v[194:197], v[222:225], v[34:37]
	v_mfma_f32_16x16x32_bf16 v[22:25], v[182:185], v[226:229], v[22:25]
	v_mfma_f32_16x16x32_bf16 v[22:25], v[186:189], v[230:233], v[22:25]
	v_mfma_f32_16x16x32_bf16 v[18:21], v[190:193], v[226:229], v[18:21]
	v_mfma_f32_16x16x32_bf16 v[18:21], v[194:197], v[230:233], v[18:21]
	v_mfma_f32_16x16x32_bf16 v[6:9], v[182:185], v[234:237], v[6:9]
	v_mfma_f32_16x16x32_bf16 v[6:9], v[186:189], v[238:241], v[6:9]
	v_mfma_f32_16x16x32_bf16 v[2:5], v[190:193], v[234:237], v[2:5]
	v_mfma_f32_16x16x32_bf16 v[2:5], v[194:197], v[238:241], v[2:5]
	s_barrier
	s_cmp_gt_u32 s91, 13
	s_cbranch_scc0 .LBB0_850
	s_setprio 0
	s_and_b64 vcc, exec, s[62:63]
	s_cbranch_vccz .LBB0_853
	s_barrier
